# hand-written phase-0 tail (rmsnorm->H, beta/g narrow f32 dots, KMEAN zero) on top of hand-written S2/MoBA
# speedup vs baseline: 1.0647x; 1.0149x over previous
.LBB0_123:
	s_waitcnt lgkmcnt(0)
	s_barrier
	s_waitcnt vmcnt(0)
	v_lshrrev_b32_e32 v196, 6, v198
	v_and_b32_e32 v197, 63, v198
	v_mbcnt_lo_u32_b32 v194, -1, 0
	v_lshlrev_b32_e32 v166, 4, v197
	v_lshlrev_b32_e32 v164, 3, v197
	v_writelane_b32 v236, s92, 38
	v_writelane_b32 v236, s93, 39
	v_writelane_b32 v236, s96, 40
	v_readlane_b32 s4, v236, 3
	v_readlane_b32 s5, v236, 4
	v_readlane_b32 s8, v236, 5
	v_readlane_b32 s9, v236, 6
	v_readlane_b32 s10, v236, 7
	v_readlane_b32 s11, v236, 8
	v_readlane_b32 s36, v236, 11
	v_readlane_b32 s37, v236, 12
	v_readlane_b32 s38, v236, 13
	v_readlane_b32 s39, v236, 14
	v_readlane_b32 s12, v236, 22
	v_readlane_b32 s13, v236, 23
	v_readlane_b32 s14, v236, 24
	v_readlane_b32 s15, v236, 25
	v_readlane_b32 s18, v236, 26
	v_readlane_b32 s19, v236, 27
	s_mov_b32 s6, s64
	s_mov_b32 s7, s65
	s_nop 3
	s_cmp_lt_u32 s96, 128
	s_cbranch_scc0 .Lp0_nokm
	s_lshl_b32 s20, s96, 11
	s_add_u32 s18, s18, s20
	s_addc_u32 s19, s19, 0
	v_lshlrev_b32_e32 v0, 2, v198
	v_mov_b32_e32 v1, 0
	global_store_dword v0, v1, s[18:19]
.Lp0_nokm:
	v_lshrrev_b32_e32 v0, 2, v198
	s_mov_b32 s20, 0xc040
	v_mul_lo_u32 v0, v0, s20
	v_and_b32_e32 v1, 3, v198
	v_lshl_add_u32 v0, v1, 4, v0
	s_add_u32 s18, s10, 0x4000
	s_addc_u32 s19, s11, 0
	global_load_dwordx4 v[4:7], v0, s[18:19]
	s_add_u32 s18, s18, 0x602000
	s_addc_u32 s19, s19, 0
	global_load_dwordx4 v[8:11], v0, s[18:19]
	s_add_u32 s18, s18, 0x602000
	s_addc_u32 s19, s19, 0
	global_load_dwordx4 v[12:15], v0, s[18:19]
	s_add_u32 s18, s18, 0x602000
	s_addc_u32 s19, s19, 0
	global_load_dwordx4 v[16:19], v0, s[18:19]
	s_add_u32 s18, s18, 0x602000
	s_addc_u32 s19, s19, 0
	global_load_dwordx4 v[20:23], v0, s[18:19]
	s_add_u32 s18, s18, 0x602000
	s_addc_u32 s19, s19, 0
	global_load_dwordx4 v[24:27], v0, s[18:19]
	s_add_u32 s18, s18, 0x602000
	s_addc_u32 s19, s19, 0
	global_load_dwordx4 v[28:31], v0, s[18:19]
	s_add_u32 s18, s18, 0x602000
	s_addc_u32 s19, s19, 0
	global_load_dwordx4 v[32:35], v0, s[18:19]
	s_add_u32 s18, s18, 0x602000
	s_addc_u32 s19, s19, 0
	global_load_dwordx4 v[36:39], v0, s[18:19]
	s_add_u32 s18, s18, 0x602000
	s_addc_u32 s19, s19, 0
	global_load_dwordx4 v[40:43], v0, s[18:19]
	s_add_u32 s18, s18, 0x602000
	s_addc_u32 s19, s19, 0
	global_load_dwordx4 v[44:47], v0, s[18:19]
	s_add_u32 s18, s18, 0x602000
	s_addc_u32 s19, s19, 0
	global_load_dwordx4 v[48:51], v0, s[18:19]
	s_add_u32 s18, s18, 0x602000
	s_addc_u32 s19, s19, 0
	global_load_dwordx4 v[52:55], v0, s[18:19]
	s_add_u32 s18, s18, 0x602000
	s_addc_u32 s19, s19, 0
	global_load_dwordx4 v[56:59], v0, s[18:19]
	s_add_u32 s18, s18, 0x602000
	s_addc_u32 s19, s19, 0
	global_load_dwordx4 v[60:63], v0, s[18:19]
	s_add_u32 s18, s18, 0x602000
	s_addc_u32 s19, s19, 0
	global_load_dwordx4 v[64:67], v0, s[18:19]
	s_add_u32 s32, s8, 0x1000
	s_addc_u32 s33, s9, 0
	global_load_dwordx4 v[200:203], v166, s[8:9] offset:0
	global_load_dwordx4 v[204:207], v166, s[8:9] offset:1024
	global_load_dwordx4 v[208:211], v166, s[8:9] offset:2048
	global_load_dwordx4 v[212:215], v166, s[8:9] offset:3072
	global_load_dwordx4 v[216:219], v166, s[32:33] offset:0
	global_load_dwordx4 v[220:223], v166, s[32:33] offset:1024
	global_load_dwordx4 v[224:227], v166, s[32:33] offset:2048
	global_load_dwordx4 v[228:231], v166, s[32:33] offset:3072
	v_bfe_u32 v2, v198, 2, 2
	v_lshrrev_b32_e32 v3, 4, v198
	v_lshl_add_u32 v2, v2, 6, v3
	v_lshlrev_b32_e32 v2, 6, v2
	v_add_u32_e32 v3, v1, v196
	v_and_b32_e32 v3, 3, v3
	v_lshl_add_u32 v2, v3, 4, v2
	s_waitcnt vmcnt(23)
	ds_write_b128 v2, v[4:7] offset:0
	s_waitcnt vmcnt(22)
	ds_write_b128 v2, v[8:11] offset:2048
	s_waitcnt vmcnt(21)
	ds_write_b128 v2, v[12:15] offset:16384
	s_waitcnt vmcnt(20)
	ds_write_b128 v2, v[16:19] offset:18432
	s_waitcnt vmcnt(19)
	ds_write_b128 v2, v[20:23] offset:32768
	s_waitcnt vmcnt(18)
	ds_write_b128 v2, v[24:27] offset:34816
	s_waitcnt vmcnt(17)
	ds_write_b128 v2, v[28:31] offset:49152
	s_waitcnt vmcnt(16)
	ds_write_b128 v2, v[32:35] offset:51200
	s_waitcnt vmcnt(15)
	v_add_u32_e32 v3, 0x10000, v2
	ds_write_b128 v3, v[36:39] offset:0
	s_waitcnt vmcnt(14)
	ds_write_b128 v3, v[40:43] offset:2048
	s_waitcnt vmcnt(13)
	ds_write_b128 v3, v[44:47] offset:16384
	s_waitcnt vmcnt(12)
	ds_write_b128 v3, v[48:51] offset:18432
	s_waitcnt vmcnt(11)
	ds_write_b128 v3, v[52:55] offset:32768
	s_waitcnt vmcnt(10)
	ds_write_b128 v3, v[56:59] offset:34816
	s_waitcnt vmcnt(9)
	ds_write_b128 v3, v[60:63] offset:49152
	s_waitcnt vmcnt(8)
	ds_write_b128 v3, v[64:67] offset:51200
	v_lshrrev_b32_e32 v0, 2, v197
	v_add_u32_e32 v1, 0, v0
	v_and_b32_e32 v1, 3, v1
	v_lshlrev_b32_e32 v1, 4, v1
	v_lshl_add_u32 v244, v197, 6, v1
	v_add_u32_e32 v248, 0x10000, v244
	v_add_u32_e32 v1, 1, v0
	v_and_b32_e32 v1, 3, v1
	v_lshlrev_b32_e32 v1, 4, v1
	v_lshl_add_u32 v245, v197, 6, v1
	v_add_u32_e32 v249, 0x10000, v245
	v_add_u32_e32 v1, 2, v0
	v_and_b32_e32 v1, 3, v1
	v_lshlrev_b32_e32 v1, 4, v1
	v_lshl_add_u32 v246, v197, 6, v1
	v_add_u32_e32 v250, 0x10000, v246
	v_add_u32_e32 v1, 3, v0
	v_and_b32_e32 v1, 3, v1
	v_lshlrev_b32_e32 v1, 4, v1
	v_lshl_add_u32 v247, v197, 6, v1
	v_add_u32_e32 v251, 0x10000, v247
	v_and_b32_e32 v0, 32, v197
	v_cmp_ne_u32_e64 s[24:25], 0, v0
	v_and_b32_e32 v0, 16, v197
	v_cmp_ne_u32_e64 s[26:27], 0, v0
	v_and_b32_e32 v0, 8, v197
	v_cmp_ne_u32_e64 s[28:29], 0, v0
	v_and_b32_e32 v0, 4, v197
	v_cmp_ne_u32_e64 s[30:31], 0, v0
	v_and_b32_e32 v0, 2, v197
	v_cmp_ne_u32_e64 s[34:35], 0, v0
	v_bfe_u32 v0, v197, 1, 3
	v_lshlrev_b32_e32 v0, 2, v0
	global_load_dword v237, v0, s[36:37]
	global_load_dword v195, v0, s[38:39]
	s_waitcnt vmcnt(0) lgkmcnt(0)
	v_mul_f32_e32 v237, 0x3fb8aa3b, v237
	v_exp_f32_e32 v237, v237
	s_mov_b32 s20, 0x3a000000
	s_barrier
	v_readfirstlane_b32 s18, v196
	s_lshl_b32 s16, s96, 6
	s_lshl_b32 s18, s18, 3
	s_add_u32 s16, s16, s18
	s_lshl_b32 s18, s16, 13
	s_add_u32 s22, s4, s18
	s_addc_u32 s23, s5, 0
	s_add_u32 s32, s22, 0x1000
	s_addc_u32 s33, s23, 0
	global_load_dwordx4 v[0:3], v166, s[22:23] offset:0
	global_load_dwordx4 v[4:7], v166, s[22:23] offset:1024
	global_load_dwordx4 v[8:11], v166, s[22:23] offset:2048
	global_load_dwordx4 v[12:15], v166, s[22:23] offset:3072
	global_load_dwordx4 v[16:19], v166, s[32:33] offset:0
	global_load_dwordx4 v[20:23], v166, s[32:33] offset:1024
	global_load_dwordx4 v[24:27], v166, s[32:33] offset:2048
	global_load_dwordx4 v[28:31], v166, s[32:33] offset:3072
	s_add_u32 s22, s22, 0x2000
	s_addc_u32 s23, s23, 0
	s_add_u32 s32, s22, 0x1000
	s_addc_u32 s33, s23, 0
	global_load_dwordx4 v[32:35], v166, s[22:23] offset:0
	global_load_dwordx4 v[36:39], v166, s[22:23] offset:1024
	global_load_dwordx4 v[40:43], v166, s[22:23] offset:2048
	global_load_dwordx4 v[44:47], v166, s[22:23] offset:3072
	global_load_dwordx4 v[48:51], v166, s[32:33] offset:0
	global_load_dwordx4 v[52:55], v166, s[32:33] offset:1024
	global_load_dwordx4 v[56:59], v166, s[32:33] offset:2048
	global_load_dwordx4 v[60:63], v166, s[32:33] offset:3072
	s_mov_b32 s17, 0
.Lp0_loop:
	s_add_u32 s16, s16, 2
	s_lshl_b32 s18, s16, 13
	s_add_u32 s22, s4, s18
	s_addc_u32 s23, s5, 0
	s_add_u32 s32, s22, 0x1000
	s_addc_u32 s33, s23, 0
	global_load_dwordx4 v[64:67], v166, s[22:23] offset:0
	global_load_dwordx4 v[68:71], v166, s[22:23] offset:1024
	global_load_dwordx4 v[72:75], v166, s[22:23] offset:2048
	global_load_dwordx4 v[76:79], v166, s[22:23] offset:3072
	global_load_dwordx4 v[80:83], v166, s[32:33] offset:0
	global_load_dwordx4 v[84:87], v166, s[32:33] offset:1024
	global_load_dwordx4 v[88:91], v166, s[32:33] offset:2048
	global_load_dwordx4 v[92:95], v166, s[32:33] offset:3072
	s_add_u32 s22, s22, 0x2000
	s_addc_u32 s23, s23, 0
	s_add_u32 s32, s22, 0x1000
	s_addc_u32 s33, s23, 0
	global_load_dwordx4 v[96:99], v166, s[22:23] offset:0
	global_load_dwordx4 v[100:103], v166, s[22:23] offset:1024
	global_load_dwordx4 v[104:107], v166, s[22:23] offset:2048
	global_load_dwordx4 v[108:111], v166, s[22:23] offset:3072
	global_load_dwordx4 v[112:115], v166, s[32:33] offset:0
	global_load_dwordx4 v[116:119], v166, s[32:33] offset:1024
	global_load_dwordx4 v[120:123], v166, s[32:33] offset:2048
	global_load_dwordx4 v[124:127], v166, s[32:33] offset:3072
	s_sub_u32 s16, s16, 2
	s_waitcnt vmcnt(16)
	v_mov_b32_e32 v128, 0
	v_mov_b32_e32 v129, 0
	v_mov_b32_e32 v130, 0
	v_mov_b32_e32 v131, 0
	v_mov_b32_e32 v132, 0
	v_mov_b32_e32 v133, 0
	v_mov_b32_e32 v134, 0
	v_mov_b32_e32 v135, 0
	v_mov_b32_e32 v136, 0
	v_mov_b32_e32 v137, 0
	v_mov_b32_e32 v138, 0
	v_mov_b32_e32 v139, 0
	v_mov_b32_e32 v140, 0
	v_mov_b32_e32 v141, 0
	v_mov_b32_e32 v142, 0
	v_mov_b32_e32 v143, 0
	v_mov_b32_e32 v254, 0
	v_mov_b32_e32 v144, 0
	v_mov_b32_e32 v145, 0
	v_mov_b32_e32 v146, 0
	v_mov_b32_e32 v147, 0
	v_mov_b32_e32 v148, 0
	v_mov_b32_e32 v149, 0
	v_mov_b32_e32 v150, 0
	v_mov_b32_e32 v151, 0
	v_mov_b32_e32 v152, 0
	v_mov_b32_e32 v153, 0
	v_mov_b32_e32 v154, 0
	v_mov_b32_e32 v155, 0
	v_mov_b32_e32 v156, 0
	v_mov_b32_e32 v157, 0
	v_mov_b32_e32 v158, 0
	v_mov_b32_e32 v159, 0
	v_mov_b32_e32 v255, 0
	ds_read_b128 v[168:171], v244 offset:0
	ds_read_b128 v[172:175], v245 offset:0
	ds_read_b128 v[176:179], v246 offset:0
	ds_read_b128 v[180:183], v247 offset:0
	ds_read_b128 v[184:187], v244 offset:4096
	ds_read_b128 v[188:191], v245 offset:4096
	ds_read_b128 v[232:235], v246 offset:4096
	ds_read_b128 v[240:243], v247 offset:4096
	v_mul_f32_e32 v252, v0, v200
	v_fmac_f32_e32 v254, v0, v0
	v_mul_f32_e32 v253, v32, v200
	v_fmac_f32_e32 v255, v32, v32
	s_waitcnt lgkmcnt(7)
	v_fmac_f32_e32 v128, v252, v168
	v_fmac_f32_e32 v144, v253, v168
	v_fmac_f32_e32 v129, v252, v169
	v_fmac_f32_e32 v145, v253, v169
	v_fmac_f32_e32 v130, v252, v170
	v_fmac_f32_e32 v146, v253, v170
	v_fmac_f32_e32 v131, v252, v171
	v_fmac_f32_e32 v147, v253, v171
	s_waitcnt lgkmcnt(6)
	v_fmac_f32_e32 v132, v252, v172
	v_fmac_f32_e32 v148, v253, v172
	v_fmac_f32_e32 v133, v252, v173
	v_fmac_f32_e32 v149, v253, v173
	v_fmac_f32_e32 v134, v252, v174
	v_fmac_f32_e32 v150, v253, v174
	v_fmac_f32_e32 v135, v252, v175
	v_fmac_f32_e32 v151, v253, v175
	s_waitcnt lgkmcnt(5)
	v_fmac_f32_e32 v136, v252, v176
	v_fmac_f32_e32 v152, v253, v176
	v_fmac_f32_e32 v137, v252, v177
	v_fmac_f32_e32 v153, v253, v177
	v_fmac_f32_e32 v138, v252, v178
	v_fmac_f32_e32 v154, v253, v178
	v_fmac_f32_e32 v139, v252, v179
	v_fmac_f32_e32 v155, v253, v179
	s_waitcnt lgkmcnt(4)
	v_fmac_f32_e32 v140, v252, v180
	v_fmac_f32_e32 v156, v253, v180
	v_fmac_f32_e32 v141, v252, v181
	v_fmac_f32_e32 v157, v253, v181
	v_fmac_f32_e32 v142, v252, v182
	v_fmac_f32_e32 v158, v253, v182
	v_fmac_f32_e32 v143, v252, v183
	v_fmac_f32_e32 v159, v253, v183
	ds_read_b128 v[168:171], v244 offset:8192
	ds_read_b128 v[172:175], v245 offset:8192
	ds_read_b128 v[176:179], v246 offset:8192
	ds_read_b128 v[180:183], v247 offset:8192
	v_mul_f32_e32 v252, v1, v201
	v_fmac_f32_e32 v254, v1, v1
	v_mul_f32_e32 v253, v33, v201
	v_fmac_f32_e32 v255, v33, v33
	s_waitcnt lgkmcnt(7)
	v_fmac_f32_e32 v128, v252, v184
	v_fmac_f32_e32 v144, v253, v184
	v_fmac_f32_e32 v129, v252, v185
	v_fmac_f32_e32 v145, v253, v185
	v_fmac_f32_e32 v130, v252, v186
	v_fmac_f32_e32 v146, v253, v186
	v_fmac_f32_e32 v131, v252, v187
	v_fmac_f32_e32 v147, v253, v187
	s_waitcnt lgkmcnt(6)
	v_fmac_f32_e32 v132, v252, v188
	v_fmac_f32_e32 v148, v253, v188
	v_fmac_f32_e32 v133, v252, v189
	v_fmac_f32_e32 v149, v253, v189
	v_fmac_f32_e32 v134, v252, v190
	v_fmac_f32_e32 v150, v253, v190
	v_fmac_f32_e32 v135, v252, v191
	v_fmac_f32_e32 v151, v253, v191
	s_waitcnt lgkmcnt(5)
	v_fmac_f32_e32 v136, v252, v232
	v_fmac_f32_e32 v152, v253, v232
	v_fmac_f32_e32 v137, v252, v233
	v_fmac_f32_e32 v153, v253, v233
	v_fmac_f32_e32 v138, v252, v234
	v_fmac_f32_e32 v154, v253, v234
	v_fmac_f32_e32 v139, v252, v235
	v_fmac_f32_e32 v155, v253, v235
	s_waitcnt lgkmcnt(4)
	v_fmac_f32_e32 v140, v252, v240
	v_fmac_f32_e32 v156, v253, v240
	v_fmac_f32_e32 v141, v252, v241
	v_fmac_f32_e32 v157, v253, v241
	v_fmac_f32_e32 v142, v252, v242
	v_fmac_f32_e32 v158, v253, v242
	v_fmac_f32_e32 v143, v252, v243
	v_fmac_f32_e32 v159, v253, v243
	ds_read_b128 v[184:187], v244 offset:12288
	ds_read_b128 v[188:191], v245 offset:12288
	ds_read_b128 v[232:235], v246 offset:12288
	ds_read_b128 v[240:243], v247 offset:12288
	v_mul_f32_e32 v252, v2, v202
	v_fmac_f32_e32 v254, v2, v2
	v_mul_f32_e32 v253, v34, v202
	v_fmac_f32_e32 v255, v34, v34
	s_waitcnt lgkmcnt(7)
	v_fmac_f32_e32 v128, v252, v168
	v_fmac_f32_e32 v144, v253, v168
	v_fmac_f32_e32 v129, v252, v169
	v_fmac_f32_e32 v145, v253, v169
	v_fmac_f32_e32 v130, v252, v170
	v_fmac_f32_e32 v146, v253, v170
	v_fmac_f32_e32 v131, v252, v171
	v_fmac_f32_e32 v147, v253, v171
	s_waitcnt lgkmcnt(6)
	v_fmac_f32_e32 v132, v252, v172
	v_fmac_f32_e32 v148, v253, v172
	v_fmac_f32_e32 v133, v252, v173
	v_fmac_f32_e32 v149, v253, v173
	v_fmac_f32_e32 v134, v252, v174
	v_fmac_f32_e32 v150, v253, v174
	v_fmac_f32_e32 v135, v252, v175
	v_fmac_f32_e32 v151, v253, v175
	s_waitcnt lgkmcnt(5)
	v_fmac_f32_e32 v136, v252, v176
	v_fmac_f32_e32 v152, v253, v176
	v_fmac_f32_e32 v137, v252, v177
	v_fmac_f32_e32 v153, v253, v177
	v_fmac_f32_e32 v138, v252, v178
	v_fmac_f32_e32 v154, v253, v178
	v_fmac_f32_e32 v139, v252, v179
	v_fmac_f32_e32 v155, v253, v179
	s_waitcnt lgkmcnt(4)
	v_fmac_f32_e32 v140, v252, v180
	v_fmac_f32_e32 v156, v253, v180
	v_fmac_f32_e32 v141, v252, v181
	v_fmac_f32_e32 v157, v253, v181
	v_fmac_f32_e32 v142, v252, v182
	v_fmac_f32_e32 v158, v253, v182
	v_fmac_f32_e32 v143, v252, v183
	v_fmac_f32_e32 v159, v253, v183
	ds_read_b128 v[168:171], v244 offset:16384
	ds_read_b128 v[172:175], v245 offset:16384
	ds_read_b128 v[176:179], v246 offset:16384
	ds_read_b128 v[180:183], v247 offset:16384
	v_mul_f32_e32 v252, v3, v203
	v_fmac_f32_e32 v254, v3, v3
	v_mul_f32_e32 v253, v35, v203
	v_fmac_f32_e32 v255, v35, v35
	s_waitcnt lgkmcnt(7)
	v_fmac_f32_e32 v128, v252, v184
	v_fmac_f32_e32 v144, v253, v184
	v_fmac_f32_e32 v129, v252, v185
	v_fmac_f32_e32 v145, v253, v185
	v_fmac_f32_e32 v130, v252, v186
	v_fmac_f32_e32 v146, v253, v186
	v_fmac_f32_e32 v131, v252, v187
	v_fmac_f32_e32 v147, v253, v187
	s_waitcnt lgkmcnt(6)
	v_fmac_f32_e32 v132, v252, v188
	v_fmac_f32_e32 v148, v253, v188
	v_fmac_f32_e32 v133, v252, v189
	v_fmac_f32_e32 v149, v253, v189
	v_fmac_f32_e32 v134, v252, v190
	v_fmac_f32_e32 v150, v253, v190
	v_fmac_f32_e32 v135, v252, v191
	v_fmac_f32_e32 v151, v253, v191
	s_waitcnt lgkmcnt(5)
	v_fmac_f32_e32 v136, v252, v232
	v_fmac_f32_e32 v152, v253, v232
	v_fmac_f32_e32 v137, v252, v233
	v_fmac_f32_e32 v153, v253, v233
	v_fmac_f32_e32 v138, v252, v234
	v_fmac_f32_e32 v154, v253, v234
	v_fmac_f32_e32 v139, v252, v235
	v_fmac_f32_e32 v155, v253, v235
	s_waitcnt lgkmcnt(4)
	v_fmac_f32_e32 v140, v252, v240
	v_fmac_f32_e32 v156, v253, v240
	v_fmac_f32_e32 v141, v252, v241
	v_fmac_f32_e32 v157, v253, v241
	v_fmac_f32_e32 v142, v252, v242
	v_fmac_f32_e32 v158, v253, v242
	v_fmac_f32_e32 v143, v252, v243
	v_fmac_f32_e32 v159, v253, v243
	ds_read_b128 v[184:187], v244 offset:20480
	ds_read_b128 v[188:191], v245 offset:20480
	ds_read_b128 v[232:235], v246 offset:20480
	ds_read_b128 v[240:243], v247 offset:20480
	v_mul_f32_e32 v252, v4, v204
	v_fmac_f32_e32 v254, v4, v4
	v_mul_f32_e32 v253, v36, v204
	v_fmac_f32_e32 v255, v36, v36
	s_waitcnt lgkmcnt(7)
	v_fmac_f32_e32 v128, v252, v168
	v_fmac_f32_e32 v144, v253, v168
	v_fmac_f32_e32 v129, v252, v169
	v_fmac_f32_e32 v145, v253, v169
	v_fmac_f32_e32 v130, v252, v170
	v_fmac_f32_e32 v146, v253, v170
	v_fmac_f32_e32 v131, v252, v171
	v_fmac_f32_e32 v147, v253, v171
	s_waitcnt lgkmcnt(6)
	v_fmac_f32_e32 v132, v252, v172
	v_fmac_f32_e32 v148, v253, v172
	v_fmac_f32_e32 v133, v252, v173
	v_fmac_f32_e32 v149, v253, v173
	v_fmac_f32_e32 v134, v252, v174
	v_fmac_f32_e32 v150, v253, v174
	v_fmac_f32_e32 v135, v252, v175
	v_fmac_f32_e32 v151, v253, v175
	s_waitcnt lgkmcnt(5)
	v_fmac_f32_e32 v136, v252, v176
	v_fmac_f32_e32 v152, v253, v176
	v_fmac_f32_e32 v137, v252, v177
	v_fmac_f32_e32 v153, v253, v177
	v_fmac_f32_e32 v138, v252, v178
	v_fmac_f32_e32 v154, v253, v178
	v_fmac_f32_e32 v139, v252, v179
	v_fmac_f32_e32 v155, v253, v179
	s_waitcnt lgkmcnt(4)
	v_fmac_f32_e32 v140, v252, v180
	v_fmac_f32_e32 v156, v253, v180
	v_fmac_f32_e32 v141, v252, v181
	v_fmac_f32_e32 v157, v253, v181
	v_fmac_f32_e32 v142, v252, v182
	v_fmac_f32_e32 v158, v253, v182
	v_fmac_f32_e32 v143, v252, v183
	v_fmac_f32_e32 v159, v253, v183
	ds_read_b128 v[168:171], v244 offset:24576
	ds_read_b128 v[172:175], v245 offset:24576
	ds_read_b128 v[176:179], v246 offset:24576
	ds_read_b128 v[180:183], v247 offset:24576
	v_mul_f32_e32 v252, v5, v205
	v_fmac_f32_e32 v254, v5, v5
	v_mul_f32_e32 v253, v37, v205
	v_fmac_f32_e32 v255, v37, v37
	s_waitcnt lgkmcnt(7)
	v_fmac_f32_e32 v128, v252, v184
	v_fmac_f32_e32 v144, v253, v184
	v_fmac_f32_e32 v129, v252, v185
	v_fmac_f32_e32 v145, v253, v185
	v_fmac_f32_e32 v130, v252, v186
	v_fmac_f32_e32 v146, v253, v186
	v_fmac_f32_e32 v131, v252, v187
	v_fmac_f32_e32 v147, v253, v187
	s_waitcnt lgkmcnt(6)
	v_fmac_f32_e32 v132, v252, v188
	v_fmac_f32_e32 v148, v253, v188
	v_fmac_f32_e32 v133, v252, v189
	v_fmac_f32_e32 v149, v253, v189
	v_fmac_f32_e32 v134, v252, v190
	v_fmac_f32_e32 v150, v253, v190
	v_fmac_f32_e32 v135, v252, v191
	v_fmac_f32_e32 v151, v253, v191
	s_waitcnt lgkmcnt(5)
	v_fmac_f32_e32 v136, v252, v232
	v_fmac_f32_e32 v152, v253, v232
	v_fmac_f32_e32 v137, v252, v233
	v_fmac_f32_e32 v153, v253, v233
	v_fmac_f32_e32 v138, v252, v234
	v_fmac_f32_e32 v154, v253, v234
	v_fmac_f32_e32 v139, v252, v235
	v_fmac_f32_e32 v155, v253, v235
	s_waitcnt lgkmcnt(4)
	v_fmac_f32_e32 v140, v252, v240
	v_fmac_f32_e32 v156, v253, v240
	v_fmac_f32_e32 v141, v252, v241
	v_fmac_f32_e32 v157, v253, v241
	v_fmac_f32_e32 v142, v252, v242
	v_fmac_f32_e32 v158, v253, v242
	v_fmac_f32_e32 v143, v252, v243
	v_fmac_f32_e32 v159, v253, v243
	ds_read_b128 v[184:187], v244 offset:28672
	ds_read_b128 v[188:191], v245 offset:28672
	ds_read_b128 v[232:235], v246 offset:28672
	ds_read_b128 v[240:243], v247 offset:28672
	v_mul_f32_e32 v252, v6, v206
	v_fmac_f32_e32 v254, v6, v6
	v_mul_f32_e32 v253, v38, v206
	v_fmac_f32_e32 v255, v38, v38
	s_waitcnt lgkmcnt(7)
	v_fmac_f32_e32 v128, v252, v168
	v_fmac_f32_e32 v144, v253, v168
	v_fmac_f32_e32 v129, v252, v169
	v_fmac_f32_e32 v145, v253, v169
	v_fmac_f32_e32 v130, v252, v170
	v_fmac_f32_e32 v146, v253, v170
	v_fmac_f32_e32 v131, v252, v171
	v_fmac_f32_e32 v147, v253, v171
	s_waitcnt lgkmcnt(6)
	v_fmac_f32_e32 v132, v252, v172
	v_fmac_f32_e32 v148, v253, v172
	v_fmac_f32_e32 v133, v252, v173
	v_fmac_f32_e32 v149, v253, v173
	v_fmac_f32_e32 v134, v252, v174
	v_fmac_f32_e32 v150, v253, v174
	v_fmac_f32_e32 v135, v252, v175
	v_fmac_f32_e32 v151, v253, v175
	s_waitcnt lgkmcnt(5)
	v_fmac_f32_e32 v136, v252, v176
	v_fmac_f32_e32 v152, v253, v176
	v_fmac_f32_e32 v137, v252, v177
	v_fmac_f32_e32 v153, v253, v177
	v_fmac_f32_e32 v138, v252, v178
	v_fmac_f32_e32 v154, v253, v178
	v_fmac_f32_e32 v139, v252, v179
	v_fmac_f32_e32 v155, v253, v179
	s_waitcnt lgkmcnt(4)
	v_fmac_f32_e32 v140, v252, v180
	v_fmac_f32_e32 v156, v253, v180
	v_fmac_f32_e32 v141, v252, v181
	v_fmac_f32_e32 v157, v253, v181
	v_fmac_f32_e32 v142, v252, v182
	v_fmac_f32_e32 v158, v253, v182
	v_fmac_f32_e32 v143, v252, v183
	v_fmac_f32_e32 v159, v253, v183
	ds_read_b128 v[168:171], v244 offset:32768
	ds_read_b128 v[172:175], v245 offset:32768
	ds_read_b128 v[176:179], v246 offset:32768
	ds_read_b128 v[180:183], v247 offset:32768
	v_mul_f32_e32 v252, v7, v207
	v_fmac_f32_e32 v254, v7, v7
	v_mul_f32_e32 v253, v39, v207
	v_fmac_f32_e32 v255, v39, v39
	s_waitcnt lgkmcnt(7)
	v_fmac_f32_e32 v128, v252, v184
	v_fmac_f32_e32 v144, v253, v184
	v_fmac_f32_e32 v129, v252, v185
	v_fmac_f32_e32 v145, v253, v185
	v_fmac_f32_e32 v130, v252, v186
	v_fmac_f32_e32 v146, v253, v186
	v_fmac_f32_e32 v131, v252, v187
	v_fmac_f32_e32 v147, v253, v187
	s_waitcnt lgkmcnt(6)
	v_fmac_f32_e32 v132, v252, v188
	v_fmac_f32_e32 v148, v253, v188
	v_fmac_f32_e32 v133, v252, v189
	v_fmac_f32_e32 v149, v253, v189
	v_fmac_f32_e32 v134, v252, v190
	v_fmac_f32_e32 v150, v253, v190
	v_fmac_f32_e32 v135, v252, v191
	v_fmac_f32_e32 v151, v253, v191
	s_waitcnt lgkmcnt(5)
	v_fmac_f32_e32 v136, v252, v232
	v_fmac_f32_e32 v152, v253, v232
	v_fmac_f32_e32 v137, v252, v233
	v_fmac_f32_e32 v153, v253, v233
	v_fmac_f32_e32 v138, v252, v234
	v_fmac_f32_e32 v154, v253, v234
	v_fmac_f32_e32 v139, v252, v235
	v_fmac_f32_e32 v155, v253, v235
	s_waitcnt lgkmcnt(4)
	v_fmac_f32_e32 v140, v252, v240
	v_fmac_f32_e32 v156, v253, v240
	v_fmac_f32_e32 v141, v252, v241
	v_fmac_f32_e32 v157, v253, v241
	v_fmac_f32_e32 v142, v252, v242
	v_fmac_f32_e32 v158, v253, v242
	v_fmac_f32_e32 v143, v252, v243
	v_fmac_f32_e32 v159, v253, v243
	ds_read_b128 v[184:187], v244 offset:36864
	ds_read_b128 v[188:191], v245 offset:36864
	ds_read_b128 v[232:235], v246 offset:36864
	ds_read_b128 v[240:243], v247 offset:36864
	v_mul_f32_e32 v252, v8, v208
	v_fmac_f32_e32 v254, v8, v8
	v_mul_f32_e32 v253, v40, v208
	v_fmac_f32_e32 v255, v40, v40
	s_waitcnt lgkmcnt(7)
	v_fmac_f32_e32 v128, v252, v168
	v_fmac_f32_e32 v144, v253, v168
	v_fmac_f32_e32 v129, v252, v169
	v_fmac_f32_e32 v145, v253, v169
	v_fmac_f32_e32 v130, v252, v170
	v_fmac_f32_e32 v146, v253, v170
	v_fmac_f32_e32 v131, v252, v171
	v_fmac_f32_e32 v147, v253, v171
	s_waitcnt lgkmcnt(6)
	v_fmac_f32_e32 v132, v252, v172
	v_fmac_f32_e32 v148, v253, v172
	v_fmac_f32_e32 v133, v252, v173
	v_fmac_f32_e32 v149, v253, v173
	v_fmac_f32_e32 v134, v252, v174
	v_fmac_f32_e32 v150, v253, v174
	v_fmac_f32_e32 v135, v252, v175
	v_fmac_f32_e32 v151, v253, v175
	s_waitcnt lgkmcnt(5)
	v_fmac_f32_e32 v136, v252, v176
	v_fmac_f32_e32 v152, v253, v176
	v_fmac_f32_e32 v137, v252, v177
	v_fmac_f32_e32 v153, v253, v177
	v_fmac_f32_e32 v138, v252, v178
	v_fmac_f32_e32 v154, v253, v178
	v_fmac_f32_e32 v139, v252, v179
	v_fmac_f32_e32 v155, v253, v179
	s_waitcnt lgkmcnt(4)
	v_fmac_f32_e32 v140, v252, v180
	v_fmac_f32_e32 v156, v253, v180
	v_fmac_f32_e32 v141, v252, v181
	v_fmac_f32_e32 v157, v253, v181
	v_fmac_f32_e32 v142, v252, v182
	v_fmac_f32_e32 v158, v253, v182
	v_fmac_f32_e32 v143, v252, v183
	v_fmac_f32_e32 v159, v253, v183
	ds_read_b128 v[168:171], v244 offset:40960
	ds_read_b128 v[172:175], v245 offset:40960
	ds_read_b128 v[176:179], v246 offset:40960
	ds_read_b128 v[180:183], v247 offset:40960
	v_mul_f32_e32 v252, v9, v209
	v_fmac_f32_e32 v254, v9, v9
	v_mul_f32_e32 v253, v41, v209
	v_fmac_f32_e32 v255, v41, v41
	s_waitcnt lgkmcnt(7)
	v_fmac_f32_e32 v128, v252, v184
	v_fmac_f32_e32 v144, v253, v184
	v_fmac_f32_e32 v129, v252, v185
	v_fmac_f32_e32 v145, v253, v185
	v_fmac_f32_e32 v130, v252, v186
	v_fmac_f32_e32 v146, v253, v186
	v_fmac_f32_e32 v131, v252, v187
	v_fmac_f32_e32 v147, v253, v187
	s_waitcnt lgkmcnt(6)
	v_fmac_f32_e32 v132, v252, v188
	v_fmac_f32_e32 v148, v253, v188
	v_fmac_f32_e32 v133, v252, v189
	v_fmac_f32_e32 v149, v253, v189
	v_fmac_f32_e32 v134, v252, v190
	v_fmac_f32_e32 v150, v253, v190
	v_fmac_f32_e32 v135, v252, v191
	v_fmac_f32_e32 v151, v253, v191
	s_waitcnt lgkmcnt(5)
	v_fmac_f32_e32 v136, v252, v232
	v_fmac_f32_e32 v152, v253, v232
	v_fmac_f32_e32 v137, v252, v233
	v_fmac_f32_e32 v153, v253, v233
	v_fmac_f32_e32 v138, v252, v234
	v_fmac_f32_e32 v154, v253, v234
	v_fmac_f32_e32 v139, v252, v235
	v_fmac_f32_e32 v155, v253, v235
	s_waitcnt lgkmcnt(4)
	v_fmac_f32_e32 v140, v252, v240
	v_fmac_f32_e32 v156, v253, v240
	v_fmac_f32_e32 v141, v252, v241
	v_fmac_f32_e32 v157, v253, v241
	v_fmac_f32_e32 v142, v252, v242
	v_fmac_f32_e32 v158, v253, v242
	v_fmac_f32_e32 v143, v252, v243
	v_fmac_f32_e32 v159, v253, v243
	ds_read_b128 v[184:187], v244 offset:45056
	ds_read_b128 v[188:191], v245 offset:45056
	ds_read_b128 v[232:235], v246 offset:45056
	ds_read_b128 v[240:243], v247 offset:45056
	v_mul_f32_e32 v252, v10, v210
	v_fmac_f32_e32 v254, v10, v10
	v_mul_f32_e32 v253, v42, v210
	v_fmac_f32_e32 v255, v42, v42
	s_waitcnt lgkmcnt(7)
	v_fmac_f32_e32 v128, v252, v168
	v_fmac_f32_e32 v144, v253, v168
	v_fmac_f32_e32 v129, v252, v169
	v_fmac_f32_e32 v145, v253, v169
	v_fmac_f32_e32 v130, v252, v170
	v_fmac_f32_e32 v146, v253, v170
	v_fmac_f32_e32 v131, v252, v171
	v_fmac_f32_e32 v147, v253, v171
	s_waitcnt lgkmcnt(6)
	v_fmac_f32_e32 v132, v252, v172
	v_fmac_f32_e32 v148, v253, v172
	v_fmac_f32_e32 v133, v252, v173
	v_fmac_f32_e32 v149, v253, v173
	v_fmac_f32_e32 v134, v252, v174
	v_fmac_f32_e32 v150, v253, v174
	v_fmac_f32_e32 v135, v252, v175
	v_fmac_f32_e32 v151, v253, v175
	s_waitcnt lgkmcnt(5)
	v_fmac_f32_e32 v136, v252, v176
	v_fmac_f32_e32 v152, v253, v176
	v_fmac_f32_e32 v137, v252, v177
	v_fmac_f32_e32 v153, v253, v177
	v_fmac_f32_e32 v138, v252, v178
	v_fmac_f32_e32 v154, v253, v178
	v_fmac_f32_e32 v139, v252, v179
	v_fmac_f32_e32 v155, v253, v179
	s_waitcnt lgkmcnt(4)
	v_fmac_f32_e32 v140, v252, v180
	v_fmac_f32_e32 v156, v253, v180
	v_fmac_f32_e32 v141, v252, v181
	v_fmac_f32_e32 v157, v253, v181
	v_fmac_f32_e32 v142, v252, v182
	v_fmac_f32_e32 v158, v253, v182
	v_fmac_f32_e32 v143, v252, v183
	v_fmac_f32_e32 v159, v253, v183
	ds_read_b128 v[168:171], v244 offset:49152
	ds_read_b128 v[172:175], v245 offset:49152
	ds_read_b128 v[176:179], v246 offset:49152
	ds_read_b128 v[180:183], v247 offset:49152
	v_mul_f32_e32 v252, v11, v211
	v_fmac_f32_e32 v254, v11, v11
	v_mul_f32_e32 v253, v43, v211
	v_fmac_f32_e32 v255, v43, v43
	s_waitcnt lgkmcnt(7)
	v_fmac_f32_e32 v128, v252, v184
	v_fmac_f32_e32 v144, v253, v184
	v_fmac_f32_e32 v129, v252, v185
	v_fmac_f32_e32 v145, v253, v185
	v_fmac_f32_e32 v130, v252, v186
	v_fmac_f32_e32 v146, v253, v186
	v_fmac_f32_e32 v131, v252, v187
	v_fmac_f32_e32 v147, v253, v187
	s_waitcnt lgkmcnt(6)
	v_fmac_f32_e32 v132, v252, v188
	v_fmac_f32_e32 v148, v253, v188
	v_fmac_f32_e32 v133, v252, v189
	v_fmac_f32_e32 v149, v253, v189
	v_fmac_f32_e32 v134, v252, v190
	v_fmac_f32_e32 v150, v253, v190
	v_fmac_f32_e32 v135, v252, v191
	v_fmac_f32_e32 v151, v253, v191
	s_waitcnt lgkmcnt(5)
	v_fmac_f32_e32 v136, v252, v232
	v_fmac_f32_e32 v152, v253, v232
	v_fmac_f32_e32 v137, v252, v233
	v_fmac_f32_e32 v153, v253, v233
	v_fmac_f32_e32 v138, v252, v234
	v_fmac_f32_e32 v154, v253, v234
	v_fmac_f32_e32 v139, v252, v235
	v_fmac_f32_e32 v155, v253, v235
	s_waitcnt lgkmcnt(4)
	v_fmac_f32_e32 v140, v252, v240
	v_fmac_f32_e32 v156, v253, v240
	v_fmac_f32_e32 v141, v252, v241
	v_fmac_f32_e32 v157, v253, v241
	v_fmac_f32_e32 v142, v252, v242
	v_fmac_f32_e32 v158, v253, v242
	v_fmac_f32_e32 v143, v252, v243
	v_fmac_f32_e32 v159, v253, v243
	ds_read_b128 v[184:187], v244 offset:53248
	ds_read_b128 v[188:191], v245 offset:53248
	ds_read_b128 v[232:235], v246 offset:53248
	ds_read_b128 v[240:243], v247 offset:53248
	v_mul_f32_e32 v252, v12, v212
	v_fmac_f32_e32 v254, v12, v12
	v_mul_f32_e32 v253, v44, v212
	v_fmac_f32_e32 v255, v44, v44
	s_waitcnt lgkmcnt(7)
	v_fmac_f32_e32 v128, v252, v168
	v_fmac_f32_e32 v144, v253, v168
	v_fmac_f32_e32 v129, v252, v169
	v_fmac_f32_e32 v145, v253, v169
	v_fmac_f32_e32 v130, v252, v170
	v_fmac_f32_e32 v146, v253, v170
	v_fmac_f32_e32 v131, v252, v171
	v_fmac_f32_e32 v147, v253, v171
	s_waitcnt lgkmcnt(6)
	v_fmac_f32_e32 v132, v252, v172
	v_fmac_f32_e32 v148, v253, v172
	v_fmac_f32_e32 v133, v252, v173
	v_fmac_f32_e32 v149, v253, v173
	v_fmac_f32_e32 v134, v252, v174
	v_fmac_f32_e32 v150, v253, v174
	v_fmac_f32_e32 v135, v252, v175
	v_fmac_f32_e32 v151, v253, v175
	s_waitcnt lgkmcnt(5)
	v_fmac_f32_e32 v136, v252, v176
	v_fmac_f32_e32 v152, v253, v176
	v_fmac_f32_e32 v137, v252, v177
	v_fmac_f32_e32 v153, v253, v177
	v_fmac_f32_e32 v138, v252, v178
	v_fmac_f32_e32 v154, v253, v178
	v_fmac_f32_e32 v139, v252, v179
	v_fmac_f32_e32 v155, v253, v179
	s_waitcnt lgkmcnt(4)
	v_fmac_f32_e32 v140, v252, v180
	v_fmac_f32_e32 v156, v253, v180
	v_fmac_f32_e32 v141, v252, v181
	v_fmac_f32_e32 v157, v253, v181
	v_fmac_f32_e32 v142, v252, v182
	v_fmac_f32_e32 v158, v253, v182
	v_fmac_f32_e32 v143, v252, v183
	v_fmac_f32_e32 v159, v253, v183
	ds_read_b128 v[168:171], v244 offset:57344
	ds_read_b128 v[172:175], v245 offset:57344
	ds_read_b128 v[176:179], v246 offset:57344
	ds_read_b128 v[180:183], v247 offset:57344
	v_mul_f32_e32 v252, v13, v213
	v_fmac_f32_e32 v254, v13, v13
	v_mul_f32_e32 v253, v45, v213
	v_fmac_f32_e32 v255, v45, v45
	s_waitcnt lgkmcnt(7)
	v_fmac_f32_e32 v128, v252, v184
	v_fmac_f32_e32 v144, v253, v184
	v_fmac_f32_e32 v129, v252, v185
	v_fmac_f32_e32 v145, v253, v185
	v_fmac_f32_e32 v130, v252, v186
	v_fmac_f32_e32 v146, v253, v186
	v_fmac_f32_e32 v131, v252, v187
	v_fmac_f32_e32 v147, v253, v187
	s_waitcnt lgkmcnt(6)
	v_fmac_f32_e32 v132, v252, v188
	v_fmac_f32_e32 v148, v253, v188
	v_fmac_f32_e32 v133, v252, v189
	v_fmac_f32_e32 v149, v253, v189
	v_fmac_f32_e32 v134, v252, v190
	v_fmac_f32_e32 v150, v253, v190
	v_fmac_f32_e32 v135, v252, v191
	v_fmac_f32_e32 v151, v253, v191
	s_waitcnt lgkmcnt(5)
	v_fmac_f32_e32 v136, v252, v232
	v_fmac_f32_e32 v152, v253, v232
	v_fmac_f32_e32 v137, v252, v233
	v_fmac_f32_e32 v153, v253, v233
	v_fmac_f32_e32 v138, v252, v234
	v_fmac_f32_e32 v154, v253, v234
	v_fmac_f32_e32 v139, v252, v235
	v_fmac_f32_e32 v155, v253, v235
	s_waitcnt lgkmcnt(4)
	v_fmac_f32_e32 v140, v252, v240
	v_fmac_f32_e32 v156, v253, v240
	v_fmac_f32_e32 v141, v252, v241
	v_fmac_f32_e32 v157, v253, v241
	v_fmac_f32_e32 v142, v252, v242
	v_fmac_f32_e32 v158, v253, v242
	v_fmac_f32_e32 v143, v252, v243
	v_fmac_f32_e32 v159, v253, v243
	ds_read_b128 v[184:187], v244 offset:61440
	ds_read_b128 v[188:191], v245 offset:61440
	ds_read_b128 v[232:235], v246 offset:61440
	ds_read_b128 v[240:243], v247 offset:61440
	v_mul_f32_e32 v252, v14, v214
	v_fmac_f32_e32 v254, v14, v14
	v_mul_f32_e32 v253, v46, v214
	v_fmac_f32_e32 v255, v46, v46
	s_waitcnt lgkmcnt(7)
	v_fmac_f32_e32 v128, v252, v168
	v_fmac_f32_e32 v144, v253, v168
	v_fmac_f32_e32 v129, v252, v169
	v_fmac_f32_e32 v145, v253, v169
	v_fmac_f32_e32 v130, v252, v170
	v_fmac_f32_e32 v146, v253, v170
	v_fmac_f32_e32 v131, v252, v171
	v_fmac_f32_e32 v147, v253, v171
	s_waitcnt lgkmcnt(6)
	v_fmac_f32_e32 v132, v252, v172
	v_fmac_f32_e32 v148, v253, v172
	v_fmac_f32_e32 v133, v252, v173
	v_fmac_f32_e32 v149, v253, v173
	v_fmac_f32_e32 v134, v252, v174
	v_fmac_f32_e32 v150, v253, v174
	v_fmac_f32_e32 v135, v252, v175
	v_fmac_f32_e32 v151, v253, v175
	s_waitcnt lgkmcnt(5)
	v_fmac_f32_e32 v136, v252, v176
	v_fmac_f32_e32 v152, v253, v176
	v_fmac_f32_e32 v137, v252, v177
	v_fmac_f32_e32 v153, v253, v177
	v_fmac_f32_e32 v138, v252, v178
	v_fmac_f32_e32 v154, v253, v178
	v_fmac_f32_e32 v139, v252, v179
	v_fmac_f32_e32 v155, v253, v179
	s_waitcnt lgkmcnt(4)
	v_fmac_f32_e32 v140, v252, v180
	v_fmac_f32_e32 v156, v253, v180
	v_fmac_f32_e32 v141, v252, v181
	v_fmac_f32_e32 v157, v253, v181
	v_fmac_f32_e32 v142, v252, v182
	v_fmac_f32_e32 v158, v253, v182
	v_fmac_f32_e32 v143, v252, v183
	v_fmac_f32_e32 v159, v253, v183
	ds_read_b128 v[168:171], v248 offset:0
	ds_read_b128 v[172:175], v249 offset:0
	ds_read_b128 v[176:179], v250 offset:0
	ds_read_b128 v[180:183], v251 offset:0
	v_mul_f32_e32 v252, v15, v215
	v_fmac_f32_e32 v254, v15, v15
	v_mul_f32_e32 v253, v47, v215
	v_fmac_f32_e32 v255, v47, v47
	s_waitcnt lgkmcnt(7)
	v_fmac_f32_e32 v128, v252, v184
	v_fmac_f32_e32 v144, v253, v184
	v_fmac_f32_e32 v129, v252, v185
	v_fmac_f32_e32 v145, v253, v185
	v_fmac_f32_e32 v130, v252, v186
	v_fmac_f32_e32 v146, v253, v186
	v_fmac_f32_e32 v131, v252, v187
	v_fmac_f32_e32 v147, v253, v187
	s_waitcnt lgkmcnt(6)
	v_fmac_f32_e32 v132, v252, v188
	v_fmac_f32_e32 v148, v253, v188
	v_fmac_f32_e32 v133, v252, v189
	v_fmac_f32_e32 v149, v253, v189
	v_fmac_f32_e32 v134, v252, v190
	v_fmac_f32_e32 v150, v253, v190
	v_fmac_f32_e32 v135, v252, v191
	v_fmac_f32_e32 v151, v253, v191
	s_waitcnt lgkmcnt(5)
	v_fmac_f32_e32 v136, v252, v232
	v_fmac_f32_e32 v152, v253, v232
	v_fmac_f32_e32 v137, v252, v233
	v_fmac_f32_e32 v153, v253, v233
	v_fmac_f32_e32 v138, v252, v234
	v_fmac_f32_e32 v154, v253, v234
	v_fmac_f32_e32 v139, v252, v235
	v_fmac_f32_e32 v155, v253, v235
	s_waitcnt lgkmcnt(4)
	v_fmac_f32_e32 v140, v252, v240
	v_fmac_f32_e32 v156, v253, v240
	v_fmac_f32_e32 v141, v252, v241
	v_fmac_f32_e32 v157, v253, v241
	v_fmac_f32_e32 v142, v252, v242
	v_fmac_f32_e32 v158, v253, v242
	v_fmac_f32_e32 v143, v252, v243
	v_fmac_f32_e32 v159, v253, v243
	ds_read_b128 v[184:187], v248 offset:4096
	ds_read_b128 v[188:191], v249 offset:4096
	ds_read_b128 v[232:235], v250 offset:4096
	ds_read_b128 v[240:243], v251 offset:4096
	v_mul_f32_e32 v252, v16, v216
	v_fmac_f32_e32 v254, v16, v16
	v_mul_f32_e32 v253, v48, v216
	v_fmac_f32_e32 v255, v48, v48
	s_waitcnt lgkmcnt(7)
	v_fmac_f32_e32 v128, v252, v168
	v_fmac_f32_e32 v144, v253, v168
	v_fmac_f32_e32 v129, v252, v169
	v_fmac_f32_e32 v145, v253, v169
	v_fmac_f32_e32 v130, v252, v170
	v_fmac_f32_e32 v146, v253, v170
	v_fmac_f32_e32 v131, v252, v171
	v_fmac_f32_e32 v147, v253, v171
	s_waitcnt lgkmcnt(6)
	v_fmac_f32_e32 v132, v252, v172
	v_fmac_f32_e32 v148, v253, v172
	v_fmac_f32_e32 v133, v252, v173
	v_fmac_f32_e32 v149, v253, v173
	v_fmac_f32_e32 v134, v252, v174
	v_fmac_f32_e32 v150, v253, v174
	v_fmac_f32_e32 v135, v252, v175
	v_fmac_f32_e32 v151, v253, v175
	s_waitcnt lgkmcnt(5)
	v_fmac_f32_e32 v136, v252, v176
	v_fmac_f32_e32 v152, v253, v176
	v_fmac_f32_e32 v137, v252, v177
	v_fmac_f32_e32 v153, v253, v177
	v_fmac_f32_e32 v138, v252, v178
	v_fmac_f32_e32 v154, v253, v178
	v_fmac_f32_e32 v139, v252, v179
	v_fmac_f32_e32 v155, v253, v179
	s_waitcnt lgkmcnt(4)
	v_fmac_f32_e32 v140, v252, v180
	v_fmac_f32_e32 v156, v253, v180
	v_fmac_f32_e32 v141, v252, v181
	v_fmac_f32_e32 v157, v253, v181
	v_fmac_f32_e32 v142, v252, v182
	v_fmac_f32_e32 v158, v253, v182
	v_fmac_f32_e32 v143, v252, v183
	v_fmac_f32_e32 v159, v253, v183
	ds_read_b128 v[168:171], v248 offset:8192
	ds_read_b128 v[172:175], v249 offset:8192
	ds_read_b128 v[176:179], v250 offset:8192
	ds_read_b128 v[180:183], v251 offset:8192
	v_mul_f32_e32 v252, v17, v217
	v_fmac_f32_e32 v254, v17, v17
	v_mul_f32_e32 v253, v49, v217
	v_fmac_f32_e32 v255, v49, v49
	s_waitcnt lgkmcnt(7)
	v_fmac_f32_e32 v128, v252, v184
	v_fmac_f32_e32 v144, v253, v184
	v_fmac_f32_e32 v129, v252, v185
	v_fmac_f32_e32 v145, v253, v185
	v_fmac_f32_e32 v130, v252, v186
	v_fmac_f32_e32 v146, v253, v186
	v_fmac_f32_e32 v131, v252, v187
	v_fmac_f32_e32 v147, v253, v187
	s_waitcnt lgkmcnt(6)
	v_fmac_f32_e32 v132, v252, v188
	v_fmac_f32_e32 v148, v253, v188
	v_fmac_f32_e32 v133, v252, v189
	v_fmac_f32_e32 v149, v253, v189
	v_fmac_f32_e32 v134, v252, v190
	v_fmac_f32_e32 v150, v253, v190
	v_fmac_f32_e32 v135, v252, v191
	v_fmac_f32_e32 v151, v253, v191
	s_waitcnt lgkmcnt(5)
	v_fmac_f32_e32 v136, v252, v232
	v_fmac_f32_e32 v152, v253, v232
	v_fmac_f32_e32 v137, v252, v233
	v_fmac_f32_e32 v153, v253, v233
	v_fmac_f32_e32 v138, v252, v234
	v_fmac_f32_e32 v154, v253, v234
	v_fmac_f32_e32 v139, v252, v235
	v_fmac_f32_e32 v155, v253, v235
	s_waitcnt lgkmcnt(4)
	v_fmac_f32_e32 v140, v252, v240
	v_fmac_f32_e32 v156, v253, v240
	v_fmac_f32_e32 v141, v252, v241
	v_fmac_f32_e32 v157, v253, v241
	v_fmac_f32_e32 v142, v252, v242
	v_fmac_f32_e32 v158, v253, v242
	v_fmac_f32_e32 v143, v252, v243
	v_fmac_f32_e32 v159, v253, v243
	ds_read_b128 v[184:187], v248 offset:12288
	ds_read_b128 v[188:191], v249 offset:12288
	ds_read_b128 v[232:235], v250 offset:12288
	ds_read_b128 v[240:243], v251 offset:12288
	v_mul_f32_e32 v252, v18, v218
	v_fmac_f32_e32 v254, v18, v18
	v_mul_f32_e32 v253, v50, v218
	v_fmac_f32_e32 v255, v50, v50
	s_waitcnt lgkmcnt(7)
	v_fmac_f32_e32 v128, v252, v168
	v_fmac_f32_e32 v144, v253, v168
	v_fmac_f32_e32 v129, v252, v169
	v_fmac_f32_e32 v145, v253, v169
	v_fmac_f32_e32 v130, v252, v170
	v_fmac_f32_e32 v146, v253, v170
	v_fmac_f32_e32 v131, v252, v171
	v_fmac_f32_e32 v147, v253, v171
	s_waitcnt lgkmcnt(6)
	v_fmac_f32_e32 v132, v252, v172
	v_fmac_f32_e32 v148, v253, v172
	v_fmac_f32_e32 v133, v252, v173
	v_fmac_f32_e32 v149, v253, v173
	v_fmac_f32_e32 v134, v252, v174
	v_fmac_f32_e32 v150, v253, v174
	v_fmac_f32_e32 v135, v252, v175
	v_fmac_f32_e32 v151, v253, v175
	s_waitcnt lgkmcnt(5)
	v_fmac_f32_e32 v136, v252, v176
	v_fmac_f32_e32 v152, v253, v176
	v_fmac_f32_e32 v137, v252, v177
	v_fmac_f32_e32 v153, v253, v177
	v_fmac_f32_e32 v138, v252, v178
	v_fmac_f32_e32 v154, v253, v178
	v_fmac_f32_e32 v139, v252, v179
	v_fmac_f32_e32 v155, v253, v179
	s_waitcnt lgkmcnt(4)
	v_fmac_f32_e32 v140, v252, v180
	v_fmac_f32_e32 v156, v253, v180
	v_fmac_f32_e32 v141, v252, v181
	v_fmac_f32_e32 v157, v253, v181
	v_fmac_f32_e32 v142, v252, v182
	v_fmac_f32_e32 v158, v253, v182
	v_fmac_f32_e32 v143, v252, v183
	v_fmac_f32_e32 v159, v253, v183
	ds_read_b128 v[168:171], v248 offset:16384
	ds_read_b128 v[172:175], v249 offset:16384
	ds_read_b128 v[176:179], v250 offset:16384
	ds_read_b128 v[180:183], v251 offset:16384
	v_mul_f32_e32 v252, v19, v219
	v_fmac_f32_e32 v254, v19, v19
	v_mul_f32_e32 v253, v51, v219
	v_fmac_f32_e32 v255, v51, v51
	s_waitcnt lgkmcnt(7)
	v_fmac_f32_e32 v128, v252, v184
	v_fmac_f32_e32 v144, v253, v184
	v_fmac_f32_e32 v129, v252, v185
	v_fmac_f32_e32 v145, v253, v185
	v_fmac_f32_e32 v130, v252, v186
	v_fmac_f32_e32 v146, v253, v186
	v_fmac_f32_e32 v131, v252, v187
	v_fmac_f32_e32 v147, v253, v187
	s_waitcnt lgkmcnt(6)
	v_fmac_f32_e32 v132, v252, v188
	v_fmac_f32_e32 v148, v253, v188
	v_fmac_f32_e32 v133, v252, v189
	v_fmac_f32_e32 v149, v253, v189
	v_fmac_f32_e32 v134, v252, v190
	v_fmac_f32_e32 v150, v253, v190
	v_fmac_f32_e32 v135, v252, v191
	v_fmac_f32_e32 v151, v253, v191
	s_waitcnt lgkmcnt(5)
	v_fmac_f32_e32 v136, v252, v232
	v_fmac_f32_e32 v152, v253, v232
	v_fmac_f32_e32 v137, v252, v233
	v_fmac_f32_e32 v153, v253, v233
	v_fmac_f32_e32 v138, v252, v234
	v_fmac_f32_e32 v154, v253, v234
	v_fmac_f32_e32 v139, v252, v235
	v_fmac_f32_e32 v155, v253, v235
	s_waitcnt lgkmcnt(4)
	v_fmac_f32_e32 v140, v252, v240
	v_fmac_f32_e32 v156, v253, v240
	v_fmac_f32_e32 v141, v252, v241
	v_fmac_f32_e32 v157, v253, v241
	v_fmac_f32_e32 v142, v252, v242
	v_fmac_f32_e32 v158, v253, v242
	v_fmac_f32_e32 v143, v252, v243
	v_fmac_f32_e32 v159, v253, v243
	ds_read_b128 v[184:187], v248 offset:20480
	ds_read_b128 v[188:191], v249 offset:20480
	ds_read_b128 v[232:235], v250 offset:20480
	ds_read_b128 v[240:243], v251 offset:20480
	v_mul_f32_e32 v252, v20, v220
	v_fmac_f32_e32 v254, v20, v20
	v_mul_f32_e32 v253, v52, v220
	v_fmac_f32_e32 v255, v52, v52
	s_waitcnt lgkmcnt(7)
	v_fmac_f32_e32 v128, v252, v168
	v_fmac_f32_e32 v144, v253, v168
	v_fmac_f32_e32 v129, v252, v169
	v_fmac_f32_e32 v145, v253, v169
	v_fmac_f32_e32 v130, v252, v170
	v_fmac_f32_e32 v146, v253, v170
	v_fmac_f32_e32 v131, v252, v171
	v_fmac_f32_e32 v147, v253, v171
	s_waitcnt lgkmcnt(6)
	v_fmac_f32_e32 v132, v252, v172
	v_fmac_f32_e32 v148, v253, v172
	v_fmac_f32_e32 v133, v252, v173
	v_fmac_f32_e32 v149, v253, v173
	v_fmac_f32_e32 v134, v252, v174
	v_fmac_f32_e32 v150, v253, v174
	v_fmac_f32_e32 v135, v252, v175
	v_fmac_f32_e32 v151, v253, v175
	s_waitcnt lgkmcnt(5)
	v_fmac_f32_e32 v136, v252, v176
	v_fmac_f32_e32 v152, v253, v176
	v_fmac_f32_e32 v137, v252, v177
	v_fmac_f32_e32 v153, v253, v177
	v_fmac_f32_e32 v138, v252, v178
	v_fmac_f32_e32 v154, v253, v178
	v_fmac_f32_e32 v139, v252, v179
	v_fmac_f32_e32 v155, v253, v179
	s_waitcnt lgkmcnt(4)
	v_fmac_f32_e32 v140, v252, v180
	v_fmac_f32_e32 v156, v253, v180
	v_fmac_f32_e32 v141, v252, v181
	v_fmac_f32_e32 v157, v253, v181
	v_fmac_f32_e32 v142, v252, v182
	v_fmac_f32_e32 v158, v253, v182
	v_fmac_f32_e32 v143, v252, v183
	v_fmac_f32_e32 v159, v253, v183
	ds_read_b128 v[168:171], v248 offset:24576
	ds_read_b128 v[172:175], v249 offset:24576
	ds_read_b128 v[176:179], v250 offset:24576
	ds_read_b128 v[180:183], v251 offset:24576
	v_mul_f32_e32 v252, v21, v221
	v_fmac_f32_e32 v254, v21, v21
	v_mul_f32_e32 v253, v53, v221
	v_fmac_f32_e32 v255, v53, v53
	s_waitcnt lgkmcnt(7)
	v_fmac_f32_e32 v128, v252, v184
	v_fmac_f32_e32 v144, v253, v184
	v_fmac_f32_e32 v129, v252, v185
	v_fmac_f32_e32 v145, v253, v185
	v_fmac_f32_e32 v130, v252, v186
	v_fmac_f32_e32 v146, v253, v186
	v_fmac_f32_e32 v131, v252, v187
	v_fmac_f32_e32 v147, v253, v187
	s_waitcnt lgkmcnt(6)
	v_fmac_f32_e32 v132, v252, v188
	v_fmac_f32_e32 v148, v253, v188
	v_fmac_f32_e32 v133, v252, v189
	v_fmac_f32_e32 v149, v253, v189
	v_fmac_f32_e32 v134, v252, v190
	v_fmac_f32_e32 v150, v253, v190
	v_fmac_f32_e32 v135, v252, v191
	v_fmac_f32_e32 v151, v253, v191
	s_waitcnt lgkmcnt(5)
	v_fmac_f32_e32 v136, v252, v232
	v_fmac_f32_e32 v152, v253, v232
	v_fmac_f32_e32 v137, v252, v233
	v_fmac_f32_e32 v153, v253, v233
	v_fmac_f32_e32 v138, v252, v234
	v_fmac_f32_e32 v154, v253, v234
	v_fmac_f32_e32 v139, v252, v235
	v_fmac_f32_e32 v155, v253, v235
	s_waitcnt lgkmcnt(4)
	v_fmac_f32_e32 v140, v252, v240
	v_fmac_f32_e32 v156, v253, v240
	v_fmac_f32_e32 v141, v252, v241
	v_fmac_f32_e32 v157, v253, v241
	v_fmac_f32_e32 v142, v252, v242
	v_fmac_f32_e32 v158, v253, v242
	v_fmac_f32_e32 v143, v252, v243
	v_fmac_f32_e32 v159, v253, v243
	ds_read_b128 v[184:187], v248 offset:28672
	ds_read_b128 v[188:191], v249 offset:28672
	ds_read_b128 v[232:235], v250 offset:28672
	ds_read_b128 v[240:243], v251 offset:28672
	v_mul_f32_e32 v252, v22, v222
	v_fmac_f32_e32 v254, v22, v22
	v_mul_f32_e32 v253, v54, v222
	v_fmac_f32_e32 v255, v54, v54
	s_waitcnt lgkmcnt(7)
	v_fmac_f32_e32 v128, v252, v168
	v_fmac_f32_e32 v144, v253, v168
	v_fmac_f32_e32 v129, v252, v169
	v_fmac_f32_e32 v145, v253, v169
	v_fmac_f32_e32 v130, v252, v170
	v_fmac_f32_e32 v146, v253, v170
	v_fmac_f32_e32 v131, v252, v171
	v_fmac_f32_e32 v147, v253, v171
	s_waitcnt lgkmcnt(6)
	v_fmac_f32_e32 v132, v252, v172
	v_fmac_f32_e32 v148, v253, v172
	v_fmac_f32_e32 v133, v252, v173
	v_fmac_f32_e32 v149, v253, v173
	v_fmac_f32_e32 v134, v252, v174
	v_fmac_f32_e32 v150, v253, v174
	v_fmac_f32_e32 v135, v252, v175
	v_fmac_f32_e32 v151, v253, v175
	s_waitcnt lgkmcnt(5)
	v_fmac_f32_e32 v136, v252, v176
	v_fmac_f32_e32 v152, v253, v176
	v_fmac_f32_e32 v137, v252, v177
	v_fmac_f32_e32 v153, v253, v177
	v_fmac_f32_e32 v138, v252, v178
	v_fmac_f32_e32 v154, v253, v178
	v_fmac_f32_e32 v139, v252, v179
	v_fmac_f32_e32 v155, v253, v179
	s_waitcnt lgkmcnt(4)
	v_fmac_f32_e32 v140, v252, v180
	v_fmac_f32_e32 v156, v253, v180
	v_fmac_f32_e32 v141, v252, v181
	v_fmac_f32_e32 v157, v253, v181
	v_fmac_f32_e32 v142, v252, v182
	v_fmac_f32_e32 v158, v253, v182
	v_fmac_f32_e32 v143, v252, v183
	v_fmac_f32_e32 v159, v253, v183
	ds_read_b128 v[168:171], v248 offset:32768
	ds_read_b128 v[172:175], v249 offset:32768
	ds_read_b128 v[176:179], v250 offset:32768
	ds_read_b128 v[180:183], v251 offset:32768
	v_mul_f32_e32 v252, v23, v223
	v_fmac_f32_e32 v254, v23, v23
	v_mul_f32_e32 v253, v55, v223
	v_fmac_f32_e32 v255, v55, v55
	s_waitcnt lgkmcnt(7)
	v_fmac_f32_e32 v128, v252, v184
	v_fmac_f32_e32 v144, v253, v184
	v_fmac_f32_e32 v129, v252, v185
	v_fmac_f32_e32 v145, v253, v185
	v_fmac_f32_e32 v130, v252, v186
	v_fmac_f32_e32 v146, v253, v186
	v_fmac_f32_e32 v131, v252, v187
	v_fmac_f32_e32 v147, v253, v187
	s_waitcnt lgkmcnt(6)
	v_fmac_f32_e32 v132, v252, v188
	v_fmac_f32_e32 v148, v253, v188
	v_fmac_f32_e32 v133, v252, v189
	v_fmac_f32_e32 v149, v253, v189
	v_fmac_f32_e32 v134, v252, v190
	v_fmac_f32_e32 v150, v253, v190
	v_fmac_f32_e32 v135, v252, v191
	v_fmac_f32_e32 v151, v253, v191
	s_waitcnt lgkmcnt(5)
	v_fmac_f32_e32 v136, v252, v232
	v_fmac_f32_e32 v152, v253, v232
	v_fmac_f32_e32 v137, v252, v233
	v_fmac_f32_e32 v153, v253, v233
	v_fmac_f32_e32 v138, v252, v234
	v_fmac_f32_e32 v154, v253, v234
	v_fmac_f32_e32 v139, v252, v235
	v_fmac_f32_e32 v155, v253, v235
	s_waitcnt lgkmcnt(4)
	v_fmac_f32_e32 v140, v252, v240
	v_fmac_f32_e32 v156, v253, v240
	v_fmac_f32_e32 v141, v252, v241
	v_fmac_f32_e32 v157, v253, v241
	v_fmac_f32_e32 v142, v252, v242
	v_fmac_f32_e32 v158, v253, v242
	v_fmac_f32_e32 v143, v252, v243
	v_fmac_f32_e32 v159, v253, v243
	ds_read_b128 v[184:187], v248 offset:36864
	ds_read_b128 v[188:191], v249 offset:36864
	ds_read_b128 v[232:235], v250 offset:36864
	ds_read_b128 v[240:243], v251 offset:36864
	v_mul_f32_e32 v252, v24, v224
	v_fmac_f32_e32 v254, v24, v24
	v_mul_f32_e32 v253, v56, v224
	v_fmac_f32_e32 v255, v56, v56
	s_waitcnt lgkmcnt(7)
	v_fmac_f32_e32 v128, v252, v168
	v_fmac_f32_e32 v144, v253, v168
	v_fmac_f32_e32 v129, v252, v169
	v_fmac_f32_e32 v145, v253, v169
	v_fmac_f32_e32 v130, v252, v170
	v_fmac_f32_e32 v146, v253, v170
	v_fmac_f32_e32 v131, v252, v171
	v_fmac_f32_e32 v147, v253, v171
	s_waitcnt lgkmcnt(6)
	v_fmac_f32_e32 v132, v252, v172
	v_fmac_f32_e32 v148, v253, v172
	v_fmac_f32_e32 v133, v252, v173
	v_fmac_f32_e32 v149, v253, v173
	v_fmac_f32_e32 v134, v252, v174
	v_fmac_f32_e32 v150, v253, v174
	v_fmac_f32_e32 v135, v252, v175
	v_fmac_f32_e32 v151, v253, v175
	s_waitcnt lgkmcnt(5)
	v_fmac_f32_e32 v136, v252, v176
	v_fmac_f32_e32 v152, v253, v176
	v_fmac_f32_e32 v137, v252, v177
	v_fmac_f32_e32 v153, v253, v177
	v_fmac_f32_e32 v138, v252, v178
	v_fmac_f32_e32 v154, v253, v178
	v_fmac_f32_e32 v139, v252, v179
	v_fmac_f32_e32 v155, v253, v179
	s_waitcnt lgkmcnt(4)
	v_fmac_f32_e32 v140, v252, v180
	v_fmac_f32_e32 v156, v253, v180
	v_fmac_f32_e32 v141, v252, v181
	v_fmac_f32_e32 v157, v253, v181
	v_fmac_f32_e32 v142, v252, v182
	v_fmac_f32_e32 v158, v253, v182
	v_fmac_f32_e32 v143, v252, v183
	v_fmac_f32_e32 v159, v253, v183
	ds_read_b128 v[168:171], v248 offset:40960
	ds_read_b128 v[172:175], v249 offset:40960
	ds_read_b128 v[176:179], v250 offset:40960
	ds_read_b128 v[180:183], v251 offset:40960
	v_mul_f32_e32 v252, v25, v225
	v_fmac_f32_e32 v254, v25, v25
	v_mul_f32_e32 v253, v57, v225
	v_fmac_f32_e32 v255, v57, v57
	s_waitcnt lgkmcnt(7)
	v_fmac_f32_e32 v128, v252, v184
	v_fmac_f32_e32 v144, v253, v184
	v_fmac_f32_e32 v129, v252, v185
	v_fmac_f32_e32 v145, v253, v185
	v_fmac_f32_e32 v130, v252, v186
	v_fmac_f32_e32 v146, v253, v186
	v_fmac_f32_e32 v131, v252, v187
	v_fmac_f32_e32 v147, v253, v187
	s_waitcnt lgkmcnt(6)
	v_fmac_f32_e32 v132, v252, v188
	v_fmac_f32_e32 v148, v253, v188
	v_fmac_f32_e32 v133, v252, v189
	v_fmac_f32_e32 v149, v253, v189
	v_fmac_f32_e32 v134, v252, v190
	v_fmac_f32_e32 v150, v253, v190
	v_fmac_f32_e32 v135, v252, v191
	v_fmac_f32_e32 v151, v253, v191
	s_waitcnt lgkmcnt(5)
	v_fmac_f32_e32 v136, v252, v232
	v_fmac_f32_e32 v152, v253, v232
	v_fmac_f32_e32 v137, v252, v233
	v_fmac_f32_e32 v153, v253, v233
	v_fmac_f32_e32 v138, v252, v234
	v_fmac_f32_e32 v154, v253, v234
	v_fmac_f32_e32 v139, v252, v235
	v_fmac_f32_e32 v155, v253, v235
	s_waitcnt lgkmcnt(4)
	v_fmac_f32_e32 v140, v252, v240
	v_fmac_f32_e32 v156, v253, v240
	v_fmac_f32_e32 v141, v252, v241
	v_fmac_f32_e32 v157, v253, v241
	v_fmac_f32_e32 v142, v252, v242
	v_fmac_f32_e32 v158, v253, v242
	v_fmac_f32_e32 v143, v252, v243
	v_fmac_f32_e32 v159, v253, v243
	ds_read_b128 v[184:187], v248 offset:45056
	ds_read_b128 v[188:191], v249 offset:45056
	ds_read_b128 v[232:235], v250 offset:45056
	ds_read_b128 v[240:243], v251 offset:45056
	v_mul_f32_e32 v252, v26, v226
	v_fmac_f32_e32 v254, v26, v26
	v_mul_f32_e32 v253, v58, v226
	v_fmac_f32_e32 v255, v58, v58
	s_waitcnt lgkmcnt(7)
	v_fmac_f32_e32 v128, v252, v168
	v_fmac_f32_e32 v144, v253, v168
	v_fmac_f32_e32 v129, v252, v169
	v_fmac_f32_e32 v145, v253, v169
	v_fmac_f32_e32 v130, v252, v170
	v_fmac_f32_e32 v146, v253, v170
	v_fmac_f32_e32 v131, v252, v171
	v_fmac_f32_e32 v147, v253, v171
	s_waitcnt lgkmcnt(6)
	v_fmac_f32_e32 v132, v252, v172
	v_fmac_f32_e32 v148, v253, v172
	v_fmac_f32_e32 v133, v252, v173
	v_fmac_f32_e32 v149, v253, v173
	v_fmac_f32_e32 v134, v252, v174
	v_fmac_f32_e32 v150, v253, v174
	v_fmac_f32_e32 v135, v252, v175
	v_fmac_f32_e32 v151, v253, v175
	s_waitcnt lgkmcnt(5)
	v_fmac_f32_e32 v136, v252, v176
	v_fmac_f32_e32 v152, v253, v176
	v_fmac_f32_e32 v137, v252, v177
	v_fmac_f32_e32 v153, v253, v177
	v_fmac_f32_e32 v138, v252, v178
	v_fmac_f32_e32 v154, v253, v178
	v_fmac_f32_e32 v139, v252, v179
	v_fmac_f32_e32 v155, v253, v179
	s_waitcnt lgkmcnt(4)
	v_fmac_f32_e32 v140, v252, v180
	v_fmac_f32_e32 v156, v253, v180
	v_fmac_f32_e32 v141, v252, v181
	v_fmac_f32_e32 v157, v253, v181
	v_fmac_f32_e32 v142, v252, v182
	v_fmac_f32_e32 v158, v253, v182
	v_fmac_f32_e32 v143, v252, v183
	v_fmac_f32_e32 v159, v253, v183
	ds_read_b128 v[168:171], v248 offset:49152
	ds_read_b128 v[172:175], v249 offset:49152
	ds_read_b128 v[176:179], v250 offset:49152
	ds_read_b128 v[180:183], v251 offset:49152
	v_mul_f32_e32 v252, v27, v227
	v_fmac_f32_e32 v254, v27, v27
	v_mul_f32_e32 v253, v59, v227
	v_fmac_f32_e32 v255, v59, v59
	s_waitcnt lgkmcnt(7)
	v_fmac_f32_e32 v128, v252, v184
	v_fmac_f32_e32 v144, v253, v184
	v_fmac_f32_e32 v129, v252, v185
	v_fmac_f32_e32 v145, v253, v185
	v_fmac_f32_e32 v130, v252, v186
	v_fmac_f32_e32 v146, v253, v186
	v_fmac_f32_e32 v131, v252, v187
	v_fmac_f32_e32 v147, v253, v187
	s_waitcnt lgkmcnt(6)
	v_fmac_f32_e32 v132, v252, v188
	v_fmac_f32_e32 v148, v253, v188
	v_fmac_f32_e32 v133, v252, v189
	v_fmac_f32_e32 v149, v253, v189
	v_fmac_f32_e32 v134, v252, v190
	v_fmac_f32_e32 v150, v253, v190
	v_fmac_f32_e32 v135, v252, v191
	v_fmac_f32_e32 v151, v253, v191
	s_waitcnt lgkmcnt(5)
	v_fmac_f32_e32 v136, v252, v232
	v_fmac_f32_e32 v152, v253, v232
	v_fmac_f32_e32 v137, v252, v233
	v_fmac_f32_e32 v153, v253, v233
	v_fmac_f32_e32 v138, v252, v234
	v_fmac_f32_e32 v154, v253, v234
	v_fmac_f32_e32 v139, v252, v235
	v_fmac_f32_e32 v155, v253, v235
	s_waitcnt lgkmcnt(4)
	v_fmac_f32_e32 v140, v252, v240
	v_fmac_f32_e32 v156, v253, v240
	v_fmac_f32_e32 v141, v252, v241
	v_fmac_f32_e32 v157, v253, v241
	v_fmac_f32_e32 v142, v252, v242
	v_fmac_f32_e32 v158, v253, v242
	v_fmac_f32_e32 v143, v252, v243
	v_fmac_f32_e32 v159, v253, v243
	ds_read_b128 v[184:187], v248 offset:53248
	ds_read_b128 v[188:191], v249 offset:53248
	ds_read_b128 v[232:235], v250 offset:53248
	ds_read_b128 v[240:243], v251 offset:53248
	v_mul_f32_e32 v252, v28, v228
	v_fmac_f32_e32 v254, v28, v28
	v_mul_f32_e32 v253, v60, v228
	v_fmac_f32_e32 v255, v60, v60
	s_waitcnt lgkmcnt(7)
	v_fmac_f32_e32 v128, v252, v168
	v_fmac_f32_e32 v144, v253, v168
	v_fmac_f32_e32 v129, v252, v169
	v_fmac_f32_e32 v145, v253, v169
	v_fmac_f32_e32 v130, v252, v170
	v_fmac_f32_e32 v146, v253, v170
	v_fmac_f32_e32 v131, v252, v171
	v_fmac_f32_e32 v147, v253, v171
	s_waitcnt lgkmcnt(6)
	v_fmac_f32_e32 v132, v252, v172
	v_fmac_f32_e32 v148, v253, v172
	v_fmac_f32_e32 v133, v252, v173
	v_fmac_f32_e32 v149, v253, v173
	v_fmac_f32_e32 v134, v252, v174
	v_fmac_f32_e32 v150, v253, v174
	v_fmac_f32_e32 v135, v252, v175
	v_fmac_f32_e32 v151, v253, v175
	s_waitcnt lgkmcnt(5)
	v_fmac_f32_e32 v136, v252, v176
	v_fmac_f32_e32 v152, v253, v176
	v_fmac_f32_e32 v137, v252, v177
	v_fmac_f32_e32 v153, v253, v177
	v_fmac_f32_e32 v138, v252, v178
	v_fmac_f32_e32 v154, v253, v178
	v_fmac_f32_e32 v139, v252, v179
	v_fmac_f32_e32 v155, v253, v179
	s_waitcnt lgkmcnt(4)
	v_fmac_f32_e32 v140, v252, v180
	v_fmac_f32_e32 v156, v253, v180
	v_fmac_f32_e32 v141, v252, v181
	v_fmac_f32_e32 v157, v253, v181
	v_fmac_f32_e32 v142, v252, v182
	v_fmac_f32_e32 v158, v253, v182
	v_fmac_f32_e32 v143, v252, v183
	v_fmac_f32_e32 v159, v253, v183
	ds_read_b128 v[168:171], v248 offset:57344
	ds_read_b128 v[172:175], v249 offset:57344
	ds_read_b128 v[176:179], v250 offset:57344
	ds_read_b128 v[180:183], v251 offset:57344
	v_mul_f32_e32 v252, v29, v229
	v_fmac_f32_e32 v254, v29, v29
	v_mul_f32_e32 v253, v61, v229
	v_fmac_f32_e32 v255, v61, v61
	s_waitcnt lgkmcnt(7)
	v_fmac_f32_e32 v128, v252, v184
	v_fmac_f32_e32 v144, v253, v184
	v_fmac_f32_e32 v129, v252, v185
	v_fmac_f32_e32 v145, v253, v185
	v_fmac_f32_e32 v130, v252, v186
	v_fmac_f32_e32 v146, v253, v186
	v_fmac_f32_e32 v131, v252, v187
	v_fmac_f32_e32 v147, v253, v187
	s_waitcnt lgkmcnt(6)
	v_fmac_f32_e32 v132, v252, v188
	v_fmac_f32_e32 v148, v253, v188
	v_fmac_f32_e32 v133, v252, v189
	v_fmac_f32_e32 v149, v253, v189
	v_fmac_f32_e32 v134, v252, v190
	v_fmac_f32_e32 v150, v253, v190
	v_fmac_f32_e32 v135, v252, v191
	v_fmac_f32_e32 v151, v253, v191
	s_waitcnt lgkmcnt(5)
	v_fmac_f32_e32 v136, v252, v232
	v_fmac_f32_e32 v152, v253, v232
	v_fmac_f32_e32 v137, v252, v233
	v_fmac_f32_e32 v153, v253, v233
	v_fmac_f32_e32 v138, v252, v234
	v_fmac_f32_e32 v154, v253, v234
	v_fmac_f32_e32 v139, v252, v235
	v_fmac_f32_e32 v155, v253, v235
	s_waitcnt lgkmcnt(4)
	v_fmac_f32_e32 v140, v252, v240
	v_fmac_f32_e32 v156, v253, v240
	v_fmac_f32_e32 v141, v252, v241
	v_fmac_f32_e32 v157, v253, v241
	v_fmac_f32_e32 v142, v252, v242
	v_fmac_f32_e32 v158, v253, v242
	v_fmac_f32_e32 v143, v252, v243
	v_fmac_f32_e32 v159, v253, v243
	ds_read_b128 v[184:187], v248 offset:61440
	ds_read_b128 v[188:191], v249 offset:61440
	ds_read_b128 v[232:235], v250 offset:61440
	ds_read_b128 v[240:243], v251 offset:61440
	v_mul_f32_e32 v252, v30, v230
	v_fmac_f32_e32 v254, v30, v30
	v_mul_f32_e32 v253, v62, v230
	v_fmac_f32_e32 v255, v62, v62
	s_waitcnt lgkmcnt(7)
	v_fmac_f32_e32 v128, v252, v168
	v_fmac_f32_e32 v144, v253, v168
	v_fmac_f32_e32 v129, v252, v169
	v_fmac_f32_e32 v145, v253, v169
	v_fmac_f32_e32 v130, v252, v170
	v_fmac_f32_e32 v146, v253, v170
	v_fmac_f32_e32 v131, v252, v171
	v_fmac_f32_e32 v147, v253, v171
	s_waitcnt lgkmcnt(6)
	v_fmac_f32_e32 v132, v252, v172
	v_fmac_f32_e32 v148, v253, v172
	v_fmac_f32_e32 v133, v252, v173
	v_fmac_f32_e32 v149, v253, v173
	v_fmac_f32_e32 v134, v252, v174
	v_fmac_f32_e32 v150, v253, v174
	v_fmac_f32_e32 v135, v252, v175
	v_fmac_f32_e32 v151, v253, v175
	s_waitcnt lgkmcnt(5)
	v_fmac_f32_e32 v136, v252, v176
	v_fmac_f32_e32 v152, v253, v176
	v_fmac_f32_e32 v137, v252, v177
	v_fmac_f32_e32 v153, v253, v177
	v_fmac_f32_e32 v138, v252, v178
	v_fmac_f32_e32 v154, v253, v178
	v_fmac_f32_e32 v139, v252, v179
	v_fmac_f32_e32 v155, v253, v179
	s_waitcnt lgkmcnt(4)
	v_fmac_f32_e32 v140, v252, v180
	v_fmac_f32_e32 v156, v253, v180
	v_fmac_f32_e32 v141, v252, v181
	v_fmac_f32_e32 v157, v253, v181
	v_fmac_f32_e32 v142, v252, v182
	v_fmac_f32_e32 v158, v253, v182
	v_fmac_f32_e32 v143, v252, v183
	v_fmac_f32_e32 v159, v253, v183
	v_mul_f32_e32 v252, v31, v231
	v_fmac_f32_e32 v254, v31, v31
	v_mul_f32_e32 v253, v63, v231
	v_fmac_f32_e32 v255, v63, v63
	s_waitcnt lgkmcnt(3)
	v_fmac_f32_e32 v128, v252, v184
	v_fmac_f32_e32 v144, v253, v184
	v_fmac_f32_e32 v129, v252, v185
	v_fmac_f32_e32 v145, v253, v185
	v_fmac_f32_e32 v130, v252, v186
	v_fmac_f32_e32 v146, v253, v186
	v_fmac_f32_e32 v131, v252, v187
	v_fmac_f32_e32 v147, v253, v187
	s_waitcnt lgkmcnt(2)
	v_fmac_f32_e32 v132, v252, v188
	v_fmac_f32_e32 v148, v253, v188
	v_fmac_f32_e32 v133, v252, v189
	v_fmac_f32_e32 v149, v253, v189
	v_fmac_f32_e32 v134, v252, v190
	v_fmac_f32_e32 v150, v253, v190
	v_fmac_f32_e32 v135, v252, v191
	v_fmac_f32_e32 v151, v253, v191
	s_waitcnt lgkmcnt(1)
	v_fmac_f32_e32 v136, v252, v232
	v_fmac_f32_e32 v152, v253, v232
	v_fmac_f32_e32 v137, v252, v233
	v_fmac_f32_e32 v153, v253, v233
	v_fmac_f32_e32 v138, v252, v234
	v_fmac_f32_e32 v154, v253, v234
	v_fmac_f32_e32 v139, v252, v235
	v_fmac_f32_e32 v155, v253, v235
	s_waitcnt lgkmcnt(0)
	v_fmac_f32_e32 v140, v252, v240
	v_fmac_f32_e32 v156, v253, v240
	v_fmac_f32_e32 v141, v252, v241
	v_fmac_f32_e32 v157, v253, v241
	v_fmac_f32_e32 v142, v252, v242
	v_fmac_f32_e32 v158, v253, v242
	v_fmac_f32_e32 v143, v252, v243
	v_fmac_f32_e32 v159, v253, v243
	v_xor_b32_e32 v162, 32, v197
	v_lshlrev_b32_e32 v162, 2, v162
	ds_bpermute_b32 v160, v162, v254
	ds_bpermute_b32 v161, v162, v255
	s_waitcnt lgkmcnt(0)
	v_add_f32_e32 v254, v254, v160
	v_add_f32_e32 v255, v255, v161
	v_xor_b32_e32 v162, 16, v197
	v_lshlrev_b32_e32 v162, 2, v162
	ds_bpermute_b32 v160, v162, v254
	ds_bpermute_b32 v161, v162, v255
	s_waitcnt lgkmcnt(0)
	v_add_f32_e32 v254, v254, v160
	v_add_f32_e32 v255, v255, v161
	v_xor_b32_e32 v162, 8, v197
	v_lshlrev_b32_e32 v162, 2, v162
	ds_bpermute_b32 v160, v162, v254
	ds_bpermute_b32 v161, v162, v255
	s_waitcnt lgkmcnt(0)
	v_add_f32_e32 v254, v254, v160
	v_add_f32_e32 v255, v255, v161
	v_xor_b32_e32 v162, 4, v197
	v_lshlrev_b32_e32 v162, 2, v162
	ds_bpermute_b32 v160, v162, v254
	ds_bpermute_b32 v161, v162, v255
	s_waitcnt lgkmcnt(0)
	v_add_f32_e32 v254, v254, v160
	v_add_f32_e32 v255, v255, v161
	v_xor_b32_e32 v162, 2, v197
	v_lshlrev_b32_e32 v162, 2, v162
	ds_bpermute_b32 v160, v162, v254
	ds_bpermute_b32 v161, v162, v255
	s_waitcnt lgkmcnt(0)
	v_add_f32_e32 v254, v254, v160
	v_add_f32_e32 v255, v255, v161
	v_xor_b32_e32 v162, 1, v197
	v_lshlrev_b32_e32 v162, 2, v162
	ds_bpermute_b32 v160, v162, v254
	ds_bpermute_b32 v161, v162, v255
	s_waitcnt lgkmcnt(0)
	v_add_f32_e32 v254, v254, v160
	v_add_f32_e32 v255, v255, v161
	v_mov_b32_e32 v160, 0x358637bd
	v_fma_f32 v254, v254, s20, v160
	v_fma_f32 v255, v255, s20, v160
	v_rsq_f32_e32 v254, v254
	v_rsq_f32_e32 v255, v255
	s_nop 0
	s_lshl_b32 s18, s16, 12
	s_add_u32 s22, s6, s18
	s_addc_u32 s23, s7, 0
	v_mul_f32_e32 v163, v0, v254
	v_mul_f32_e32 v165, v1, v254
	v_mul_f32_e32 v167, v2, v254
	v_mul_f32_e32 v199, v3, v254
	v_mul_f32_e32 v163, v163, v200
	v_mul_f32_e32 v165, v165, v201
	v_mul_f32_e32 v167, v167, v202
	v_mul_f32_e32 v199, v199, v203
	v_cvt_pk_bf16_f32 v192, v163, v165
	v_cvt_pk_bf16_f32 v193, v167, v199
	global_store_dwordx2 v164, v[192:193], s[22:23] offset:0
	v_mul_f32_e32 v163, v4, v254
	v_mul_f32_e32 v165, v5, v254
	v_mul_f32_e32 v167, v6, v254
	v_mul_f32_e32 v199, v7, v254
	v_mul_f32_e32 v163, v163, v204
	v_mul_f32_e32 v165, v165, v205
	v_mul_f32_e32 v167, v167, v206
	v_mul_f32_e32 v199, v199, v207
	v_cvt_pk_bf16_f32 v238, v163, v165
	v_cvt_pk_bf16_f32 v239, v167, v199
	global_store_dwordx2 v164, v[238:239], s[22:23] offset:512
	v_mul_f32_e32 v163, v8, v254
	v_mul_f32_e32 v165, v9, v254
	v_mul_f32_e32 v167, v10, v254
	v_mul_f32_e32 v199, v11, v254
	v_mul_f32_e32 v163, v163, v208
	v_mul_f32_e32 v165, v165, v209
	v_mul_f32_e32 v167, v167, v210
	v_mul_f32_e32 v199, v199, v211
	v_cvt_pk_bf16_f32 v192, v163, v165
	v_cvt_pk_bf16_f32 v193, v167, v199
	global_store_dwordx2 v164, v[192:193], s[22:23] offset:1024
	v_mul_f32_e32 v163, v12, v254
	v_mul_f32_e32 v165, v13, v254
	v_mul_f32_e32 v167, v14, v254
	v_mul_f32_e32 v199, v15, v254
	v_mul_f32_e32 v163, v163, v212
	v_mul_f32_e32 v165, v165, v213
	v_mul_f32_e32 v167, v167, v214
	v_mul_f32_e32 v199, v199, v215
	v_cvt_pk_bf16_f32 v238, v163, v165
	v_cvt_pk_bf16_f32 v239, v167, v199
	global_store_dwordx2 v164, v[238:239], s[22:23] offset:1536
	v_mul_f32_e32 v163, v16, v254
	v_mul_f32_e32 v165, v17, v254
	v_mul_f32_e32 v167, v18, v254
	v_mul_f32_e32 v199, v19, v254
	v_mul_f32_e32 v163, v163, v216
	v_mul_f32_e32 v165, v165, v217
	v_mul_f32_e32 v167, v167, v218
	v_mul_f32_e32 v199, v199, v219
	v_cvt_pk_bf16_f32 v192, v163, v165
	v_cvt_pk_bf16_f32 v193, v167, v199
	global_store_dwordx2 v164, v[192:193], s[22:23] offset:2048
	v_mul_f32_e32 v163, v20, v254
	v_mul_f32_e32 v165, v21, v254
	v_mul_f32_e32 v167, v22, v254
	v_mul_f32_e32 v199, v23, v254
	v_mul_f32_e32 v163, v163, v220
	v_mul_f32_e32 v165, v165, v221
	v_mul_f32_e32 v167, v167, v222
	v_mul_f32_e32 v199, v199, v223
	v_cvt_pk_bf16_f32 v238, v163, v165
	v_cvt_pk_bf16_f32 v239, v167, v199
	global_store_dwordx2 v164, v[238:239], s[22:23] offset:2560
	v_mul_f32_e32 v163, v24, v254
	v_mul_f32_e32 v165, v25, v254
	v_mul_f32_e32 v167, v26, v254
	v_mul_f32_e32 v199, v27, v254
	v_mul_f32_e32 v163, v163, v224
	v_mul_f32_e32 v165, v165, v225
	v_mul_f32_e32 v167, v167, v226
	v_mul_f32_e32 v199, v199, v227
	v_cvt_pk_bf16_f32 v192, v163, v165
	v_cvt_pk_bf16_f32 v193, v167, v199
	global_store_dwordx2 v164, v[192:193], s[22:23] offset:3072
	v_mul_f32_e32 v163, v28, v254
	v_mul_f32_e32 v165, v29, v254
	v_mul_f32_e32 v167, v30, v254
	v_mul_f32_e32 v199, v31, v254
	v_mul_f32_e32 v163, v163, v228
	v_mul_f32_e32 v165, v165, v229
	v_mul_f32_e32 v167, v167, v230
	v_mul_f32_e32 v199, v199, v231
	v_cvt_pk_bf16_f32 v238, v163, v165
	v_cvt_pk_bf16_f32 v239, v167, v199
	global_store_dwordx2 v164, v[238:239], s[22:23] offset:3584
	s_add_u32 s22, s22, 0x1000
	s_addc_u32 s23, s23, 0
	v_mul_f32_e32 v163, v32, v255
	v_mul_f32_e32 v165, v33, v255
	v_mul_f32_e32 v167, v34, v255
	v_mul_f32_e32 v199, v35, v255
	v_mul_f32_e32 v163, v163, v200
	v_mul_f32_e32 v165, v165, v201
	v_mul_f32_e32 v167, v167, v202
	v_mul_f32_e32 v199, v199, v203
	v_cvt_pk_bf16_f32 v192, v163, v165
	v_cvt_pk_bf16_f32 v193, v167, v199
	global_store_dwordx2 v164, v[192:193], s[22:23] offset:0
	v_mul_f32_e32 v163, v36, v255
	v_mul_f32_e32 v165, v37, v255
	v_mul_f32_e32 v167, v38, v255
	v_mul_f32_e32 v199, v39, v255
	v_mul_f32_e32 v163, v163, v204
	v_mul_f32_e32 v165, v165, v205
	v_mul_f32_e32 v167, v167, v206
	v_mul_f32_e32 v199, v199, v207
	v_cvt_pk_bf16_f32 v238, v163, v165
	v_cvt_pk_bf16_f32 v239, v167, v199
	global_store_dwordx2 v164, v[238:239], s[22:23] offset:512
	v_mul_f32_e32 v163, v40, v255
	v_mul_f32_e32 v165, v41, v255
	v_mul_f32_e32 v167, v42, v255
	v_mul_f32_e32 v199, v43, v255
	v_mul_f32_e32 v163, v163, v208
	v_mul_f32_e32 v165, v165, v209
	v_mul_f32_e32 v167, v167, v210
	v_mul_f32_e32 v199, v199, v211
	v_cvt_pk_bf16_f32 v192, v163, v165
	v_cvt_pk_bf16_f32 v193, v167, v199
	global_store_dwordx2 v164, v[192:193], s[22:23] offset:1024
	v_mul_f32_e32 v163, v44, v255
	v_mul_f32_e32 v165, v45, v255
	v_mul_f32_e32 v167, v46, v255
	v_mul_f32_e32 v199, v47, v255
	v_mul_f32_e32 v163, v163, v212
	v_mul_f32_e32 v165, v165, v213
	v_mul_f32_e32 v167, v167, v214
	v_mul_f32_e32 v199, v199, v215
	v_cvt_pk_bf16_f32 v238, v163, v165
	v_cvt_pk_bf16_f32 v239, v167, v199
	global_store_dwordx2 v164, v[238:239], s[22:23] offset:1536
	v_mul_f32_e32 v163, v48, v255
	v_mul_f32_e32 v165, v49, v255
	v_mul_f32_e32 v167, v50, v255
	v_mul_f32_e32 v199, v51, v255
	v_mul_f32_e32 v163, v163, v216
	v_mul_f32_e32 v165, v165, v217
	v_mul_f32_e32 v167, v167, v218
	v_mul_f32_e32 v199, v199, v219
	v_cvt_pk_bf16_f32 v192, v163, v165
	v_cvt_pk_bf16_f32 v193, v167, v199
	global_store_dwordx2 v164, v[192:193], s[22:23] offset:2048
	v_mul_f32_e32 v163, v52, v255
	v_mul_f32_e32 v165, v53, v255
	v_mul_f32_e32 v167, v54, v255
	v_mul_f32_e32 v199, v55, v255
	v_mul_f32_e32 v163, v163, v220
	v_mul_f32_e32 v165, v165, v221
	v_mul_f32_e32 v167, v167, v222
	v_mul_f32_e32 v199, v199, v223
	v_cvt_pk_bf16_f32 v238, v163, v165
	v_cvt_pk_bf16_f32 v239, v167, v199
	global_store_dwordx2 v164, v[238:239], s[22:23] offset:2560
	v_mul_f32_e32 v163, v56, v255
	v_mul_f32_e32 v165, v57, v255
	v_mul_f32_e32 v167, v58, v255
	v_mul_f32_e32 v199, v59, v255
	v_mul_f32_e32 v163, v163, v224
	v_mul_f32_e32 v165, v165, v225
	v_mul_f32_e32 v167, v167, v226
	v_mul_f32_e32 v199, v199, v227
	v_cvt_pk_bf16_f32 v192, v163, v165
	v_cvt_pk_bf16_f32 v193, v167, v199
	global_store_dwordx2 v164, v[192:193], s[22:23] offset:3072
	v_mul_f32_e32 v163, v60, v255
	v_mul_f32_e32 v165, v61, v255
	v_mul_f32_e32 v167, v62, v255
	v_mul_f32_e32 v199, v63, v255
	v_mul_f32_e32 v163, v163, v228
	v_mul_f32_e32 v165, v165, v229
	v_mul_f32_e32 v167, v167, v230
	v_mul_f32_e32 v199, v199, v231
	v_cvt_pk_bf16_f32 v238, v163, v165
	v_cvt_pk_bf16_f32 v239, v167, v199
	global_store_dwordx2 v164, v[238:239], s[22:23] offset:3584
	v_xor_b32_e32 v162, 32, v197
	v_lshlrev_b32_e32 v162, 2, v162
	v_cndmask_b32_e64 v163, v144, v128, s[24:25]
	v_cndmask_b32_e64 v128, v128, v144, s[24:25]
	ds_bpermute_b32 v144, v162, v163
	v_cndmask_b32_e64 v165, v145, v129, s[24:25]
	v_cndmask_b32_e64 v129, v129, v145, s[24:25]
	ds_bpermute_b32 v145, v162, v165
	v_cndmask_b32_e64 v167, v146, v130, s[24:25]
	v_cndmask_b32_e64 v130, v130, v146, s[24:25]
	ds_bpermute_b32 v146, v162, v167
	v_cndmask_b32_e64 v199, v147, v131, s[24:25]
	v_cndmask_b32_e64 v131, v131, v147, s[24:25]
	ds_bpermute_b32 v147, v162, v199
	v_cndmask_b32_e64 v163, v148, v132, s[24:25]
	v_cndmask_b32_e64 v132, v132, v148, s[24:25]
	ds_bpermute_b32 v148, v162, v163
	v_cndmask_b32_e64 v165, v149, v133, s[24:25]
	v_cndmask_b32_e64 v133, v133, v149, s[24:25]
	ds_bpermute_b32 v149, v162, v165
	v_cndmask_b32_e64 v167, v150, v134, s[24:25]
	v_cndmask_b32_e64 v134, v134, v150, s[24:25]
	ds_bpermute_b32 v150, v162, v167
	v_cndmask_b32_e64 v199, v151, v135, s[24:25]
	v_cndmask_b32_e64 v135, v135, v151, s[24:25]
	ds_bpermute_b32 v151, v162, v199
	s_waitcnt lgkmcnt(0)
	v_add_f32_e32 v128, v128, v144
	v_add_f32_e32 v129, v129, v145
	v_add_f32_e32 v130, v130, v146
	v_add_f32_e32 v131, v131, v147
	v_add_f32_e32 v132, v132, v148
	v_add_f32_e32 v133, v133, v149
	v_add_f32_e32 v134, v134, v150
	v_add_f32_e32 v135, v135, v151
	v_cndmask_b32_e64 v163, v152, v136, s[24:25]
	v_cndmask_b32_e64 v136, v136, v152, s[24:25]
	ds_bpermute_b32 v152, v162, v163
	v_cndmask_b32_e64 v165, v153, v137, s[24:25]
	v_cndmask_b32_e64 v137, v137, v153, s[24:25]
	ds_bpermute_b32 v153, v162, v165
	v_cndmask_b32_e64 v167, v154, v138, s[24:25]
	v_cndmask_b32_e64 v138, v138, v154, s[24:25]
	ds_bpermute_b32 v154, v162, v167
	v_cndmask_b32_e64 v199, v155, v139, s[24:25]
	v_cndmask_b32_e64 v139, v139, v155, s[24:25]
	ds_bpermute_b32 v155, v162, v199
	v_cndmask_b32_e64 v163, v156, v140, s[24:25]
	v_cndmask_b32_e64 v140, v140, v156, s[24:25]
	ds_bpermute_b32 v156, v162, v163
	v_cndmask_b32_e64 v165, v157, v141, s[24:25]
	v_cndmask_b32_e64 v141, v141, v157, s[24:25]
	ds_bpermute_b32 v157, v162, v165
	v_cndmask_b32_e64 v167, v158, v142, s[24:25]
	v_cndmask_b32_e64 v142, v142, v158, s[24:25]
	ds_bpermute_b32 v158, v162, v167
	v_cndmask_b32_e64 v199, v159, v143, s[24:25]
	v_cndmask_b32_e64 v143, v143, v159, s[24:25]
	ds_bpermute_b32 v159, v162, v199
	s_waitcnt lgkmcnt(0)
	v_add_f32_e32 v136, v136, v152
	v_add_f32_e32 v137, v137, v153
	v_add_f32_e32 v138, v138, v154
	v_add_f32_e32 v139, v139, v155
	v_add_f32_e32 v140, v140, v156
	v_add_f32_e32 v141, v141, v157
	v_add_f32_e32 v142, v142, v158
	v_add_f32_e32 v143, v143, v159
	v_xor_b32_e32 v162, 16, v197
	v_lshlrev_b32_e32 v162, 2, v162
	v_cndmask_b32_e64 v163, v136, v128, s[26:27]
	v_cndmask_b32_e64 v128, v128, v136, s[26:27]
	ds_bpermute_b32 v136, v162, v163
	v_cndmask_b32_e64 v165, v137, v129, s[26:27]
	v_cndmask_b32_e64 v129, v129, v137, s[26:27]
	ds_bpermute_b32 v137, v162, v165
	v_cndmask_b32_e64 v167, v138, v130, s[26:27]
	v_cndmask_b32_e64 v130, v130, v138, s[26:27]
	ds_bpermute_b32 v138, v162, v167
	v_cndmask_b32_e64 v199, v139, v131, s[26:27]
	v_cndmask_b32_e64 v131, v131, v139, s[26:27]
	ds_bpermute_b32 v139, v162, v199
	v_cndmask_b32_e64 v163, v140, v132, s[26:27]
	v_cndmask_b32_e64 v132, v132, v140, s[26:27]
	ds_bpermute_b32 v140, v162, v163
	v_cndmask_b32_e64 v165, v141, v133, s[26:27]
	v_cndmask_b32_e64 v133, v133, v141, s[26:27]
	ds_bpermute_b32 v141, v162, v165
	v_cndmask_b32_e64 v167, v142, v134, s[26:27]
	v_cndmask_b32_e64 v134, v134, v142, s[26:27]
	ds_bpermute_b32 v142, v162, v167
	v_cndmask_b32_e64 v199, v143, v135, s[26:27]
	v_cndmask_b32_e64 v135, v135, v143, s[26:27]
	ds_bpermute_b32 v143, v162, v199
	s_waitcnt lgkmcnt(0)
	v_add_f32_e32 v128, v128, v136
	v_add_f32_e32 v129, v129, v137
	v_add_f32_e32 v130, v130, v138
	v_add_f32_e32 v131, v131, v139
	v_add_f32_e32 v132, v132, v140
	v_add_f32_e32 v133, v133, v141
	v_add_f32_e32 v134, v134, v142
	v_add_f32_e32 v135, v135, v143
	v_xor_b32_e32 v162, 8, v197
	v_lshlrev_b32_e32 v162, 2, v162
	v_cndmask_b32_e64 v163, v132, v128, s[28:29]
	v_cndmask_b32_e64 v128, v128, v132, s[28:29]
	ds_bpermute_b32 v132, v162, v163
	v_cndmask_b32_e64 v165, v133, v129, s[28:29]
	v_cndmask_b32_e64 v129, v129, v133, s[28:29]
	ds_bpermute_b32 v133, v162, v165
	v_cndmask_b32_e64 v167, v134, v130, s[28:29]
	v_cndmask_b32_e64 v130, v130, v134, s[28:29]
	ds_bpermute_b32 v134, v162, v167
	v_cndmask_b32_e64 v199, v135, v131, s[28:29]
	v_cndmask_b32_e64 v131, v131, v135, s[28:29]
	ds_bpermute_b32 v135, v162, v199
	s_waitcnt lgkmcnt(0)
	v_add_f32_e32 v128, v128, v132
	v_add_f32_e32 v129, v129, v133
	v_add_f32_e32 v130, v130, v134
	v_add_f32_e32 v131, v131, v135
	v_xor_b32_e32 v162, 4, v197
	v_lshlrev_b32_e32 v162, 2, v162
	v_cndmask_b32_e64 v163, v130, v128, s[30:31]
	v_cndmask_b32_e64 v128, v128, v130, s[30:31]
	ds_bpermute_b32 v130, v162, v163
	v_cndmask_b32_e64 v165, v131, v129, s[30:31]
	v_cndmask_b32_e64 v129, v129, v131, s[30:31]
	ds_bpermute_b32 v131, v162, v165
	s_waitcnt lgkmcnt(0)
	v_add_f32_e32 v128, v128, v130
	v_add_f32_e32 v129, v129, v131
	v_xor_b32_e32 v162, 2, v197
	v_lshlrev_b32_e32 v162, 2, v162
	v_cndmask_b32_e64 v163, v129, v128, s[34:35]
	v_cndmask_b32_e64 v128, v128, v129, s[34:35]
	ds_bpermute_b32 v129, v162, v163
	s_waitcnt lgkmcnt(0)
	v_add_f32_e32 v128, v128, v129
	v_xor_b32_e32 v162, 1, v197
	v_lshlrev_b32_e32 v162, 2, v162
	ds_bpermute_b32 v160, v162, v128
	s_waitcnt lgkmcnt(0)
	v_add_f32_e32 v128, v128, v160
	v_cndmask_b32_e64 v160, v254, v255, s[24:25]
	v_mul_f32_e32 v128, v128, v160
	v_mul_f32_e32 v163, 0xbfb8aa3b, v128
	v_exp_f32_e32 v163, v163
	v_add_f32_e32 v167, v128, v195
	v_add_f32_e32 v163, 1.0, v163
	v_and_b32_e32 v199, 0x7fffffff, v167
	v_mul_f32_e32 v199, 0xbfb8aa3b, v199
	v_exp_f32_e32 v199, v199
	v_rcp_f32_e32 v163, v163
	v_add_f32_e32 v160, 1.0, v199
	v_log_f32_e32 v160, v160
	v_mul_f32_e32 v161, v199, v199
	v_mul_f32_e32 v160, 0x3f317218, v160
	v_mul_f32_e32 v162, v161, v199
	v_fma_f32 v161, v161, -0.5, v199
	v_mov_b32_e32 v165, 0x3eaaaaab
	v_fmac_f32_e32 v161, v162, v165
	v_cmp_gt_f32_e32 vcc, 0x3c800000, v199
	v_max_f32_e32 v167, 0, v167
	s_nop 0
	v_cndmask_b32_e32 v160, v160, v161, vcc
	v_add_f32_e32 v167, v167, v160
	v_mul_f32_e64 v165, -v237, v167
	v_bfe_u32 v162, v197, 1, 4
	v_cmp_gt_u32_e32 vcc, 8, v162
	v_and_b32_e32 v162, 7, v162
	s_lshr_b32 s18, s16, 11
	s_lshl_b32 s18, s18, 3
	v_add_u32_e32 v162, s18, v162
	v_lshlrev_b32_e32 v162, 13, v162
	s_and_b32 s18, s16, 2047
	v_lshrrev_b32_e32 v161, 5, v197
	v_add_u32_e32 v161, s18, v161
	v_lshl_add_u32 v162, v161, 2, v162
	v_cndmask_b32_e32 v160, v165, v163, vcc
	v_and_b32_e32 v161, 1, v197
	v_cmp_eq_u32_e64 s[22:23], 0, v161
	s_nop 1
	s_and_b64 s[0:1], s[22:23], vcc
	s_andn2_b64 s[2:3], s[22:23], vcc
	s_mov_b64 s[22:23], exec
	s_mov_b64 exec, s[0:1]
	global_store_dword v162, v160, s[12:13]
	s_mov_b64 exec, s[2:3]
	global_store_dword v162, v160, s[14:15]
	s_mov_b64 exec, s[22:23]
	s_add_u32 s16, s16, 2
	s_cmp_ge_u32 s17, 1
	s_cbranch_scc1 .Lp0_nopf1
	s_add_u32 s16, s16, 2
	s_lshl_b32 s18, s16, 13
	s_add_u32 s22, s4, s18
	s_addc_u32 s23, s5, 0
	s_add_u32 s32, s22, 0x1000
	s_addc_u32 s33, s23, 0
	global_load_dwordx4 v[0:3], v166, s[22:23] offset:0
	global_load_dwordx4 v[4:7], v166, s[22:23] offset:1024
	global_load_dwordx4 v[8:11], v166, s[22:23] offset:2048
	global_load_dwordx4 v[12:15], v166, s[22:23] offset:3072
	global_load_dwordx4 v[16:19], v166, s[32:33] offset:0
	global_load_dwordx4 v[20:23], v166, s[32:33] offset:1024
	global_load_dwordx4 v[24:27], v166, s[32:33] offset:2048
	global_load_dwordx4 v[28:31], v166, s[32:33] offset:3072
	s_add_u32 s22, s22, 0x2000
	s_addc_u32 s23, s23, 0
	s_add_u32 s32, s22, 0x1000
	s_addc_u32 s33, s23, 0
	global_load_dwordx4 v[32:35], v166, s[22:23] offset:0
	global_load_dwordx4 v[36:39], v166, s[22:23] offset:1024
	global_load_dwordx4 v[40:43], v166, s[22:23] offset:2048
	global_load_dwordx4 v[44:47], v166, s[22:23] offset:3072
	global_load_dwordx4 v[48:51], v166, s[32:33] offset:0
	global_load_dwordx4 v[52:55], v166, s[32:33] offset:1024
	global_load_dwordx4 v[56:59], v166, s[32:33] offset:2048
	global_load_dwordx4 v[60:63], v166, s[32:33] offset:3072
	s_sub_u32 s16, s16, 2
	s_waitcnt vmcnt(16)
	s_branch .Lp0_nopf1_j

.Lp0_nopf1_j:
	v_mov_b32_e32 v128, 0
	v_mov_b32_e32 v129, 0
	v_mov_b32_e32 v130, 0
	v_mov_b32_e32 v131, 0
	v_mov_b32_e32 v132, 0
	v_mov_b32_e32 v133, 0
	v_mov_b32_e32 v134, 0
	v_mov_b32_e32 v135, 0
	v_mov_b32_e32 v136, 0
	v_mov_b32_e32 v137, 0
	v_mov_b32_e32 v138, 0
	v_mov_b32_e32 v139, 0
	v_mov_b32_e32 v140, 0
	v_mov_b32_e32 v141, 0
	v_mov_b32_e32 v142, 0
	v_mov_b32_e32 v143, 0
	v_mov_b32_e32 v254, 0
	v_mov_b32_e32 v144, 0
	v_mov_b32_e32 v145, 0
	v_mov_b32_e32 v146, 0
	v_mov_b32_e32 v147, 0
	v_mov_b32_e32 v148, 0
	v_mov_b32_e32 v149, 0
	v_mov_b32_e32 v150, 0
	v_mov_b32_e32 v151, 0
	v_mov_b32_e32 v152, 0
	v_mov_b32_e32 v153, 0
	v_mov_b32_e32 v154, 0
	v_mov_b32_e32 v155, 0
	v_mov_b32_e32 v156, 0
	v_mov_b32_e32 v157, 0
	v_mov_b32_e32 v158, 0
	v_mov_b32_e32 v159, 0
	v_mov_b32_e32 v255, 0
	ds_read_b128 v[168:171], v244 offset:0
	ds_read_b128 v[172:175], v245 offset:0
	ds_read_b128 v[176:179], v246 offset:0
	ds_read_b128 v[180:183], v247 offset:0
	ds_read_b128 v[184:187], v244 offset:4096
	ds_read_b128 v[188:191], v245 offset:4096
	ds_read_b128 v[232:235], v246 offset:4096
	ds_read_b128 v[240:243], v247 offset:4096
	v_mul_f32_e32 v252, v64, v200
	v_fmac_f32_e32 v254, v64, v64
	v_mul_f32_e32 v253, v96, v200
	v_fmac_f32_e32 v255, v96, v96
	s_waitcnt lgkmcnt(7)
	v_fmac_f32_e32 v128, v252, v168
	v_fmac_f32_e32 v144, v253, v168
	v_fmac_f32_e32 v129, v252, v169
	v_fmac_f32_e32 v145, v253, v169
	v_fmac_f32_e32 v130, v252, v170
	v_fmac_f32_e32 v146, v253, v170
	v_fmac_f32_e32 v131, v252, v171
	v_fmac_f32_e32 v147, v253, v171
	s_waitcnt lgkmcnt(6)
	v_fmac_f32_e32 v132, v252, v172
	v_fmac_f32_e32 v148, v253, v172
	v_fmac_f32_e32 v133, v252, v173
	v_fmac_f32_e32 v149, v253, v173
	v_fmac_f32_e32 v134, v252, v174
	v_fmac_f32_e32 v150, v253, v174
	v_fmac_f32_e32 v135, v252, v175
	v_fmac_f32_e32 v151, v253, v175
	s_waitcnt lgkmcnt(5)
	v_fmac_f32_e32 v136, v252, v176
	v_fmac_f32_e32 v152, v253, v176
	v_fmac_f32_e32 v137, v252, v177
	v_fmac_f32_e32 v153, v253, v177
	v_fmac_f32_e32 v138, v252, v178
	v_fmac_f32_e32 v154, v253, v178
	v_fmac_f32_e32 v139, v252, v179
	v_fmac_f32_e32 v155, v253, v179
	s_waitcnt lgkmcnt(4)
	v_fmac_f32_e32 v140, v252, v180
	v_fmac_f32_e32 v156, v253, v180
	v_fmac_f32_e32 v141, v252, v181
	v_fmac_f32_e32 v157, v253, v181
	v_fmac_f32_e32 v142, v252, v182
	v_fmac_f32_e32 v158, v253, v182
	v_fmac_f32_e32 v143, v252, v183
	v_fmac_f32_e32 v159, v253, v183
	ds_read_b128 v[168:171], v244 offset:8192
	ds_read_b128 v[172:175], v245 offset:8192
	ds_read_b128 v[176:179], v246 offset:8192
	ds_read_b128 v[180:183], v247 offset:8192
	v_mul_f32_e32 v252, v65, v201
	v_fmac_f32_e32 v254, v65, v65
	v_mul_f32_e32 v253, v97, v201
	v_fmac_f32_e32 v255, v97, v97
	s_waitcnt lgkmcnt(7)
	v_fmac_f32_e32 v128, v252, v184
	v_fmac_f32_e32 v144, v253, v184
	v_fmac_f32_e32 v129, v252, v185
	v_fmac_f32_e32 v145, v253, v185
	v_fmac_f32_e32 v130, v252, v186
	v_fmac_f32_e32 v146, v253, v186
	v_fmac_f32_e32 v131, v252, v187
	v_fmac_f32_e32 v147, v253, v187
	s_waitcnt lgkmcnt(6)
	v_fmac_f32_e32 v132, v252, v188
	v_fmac_f32_e32 v148, v253, v188
	v_fmac_f32_e32 v133, v252, v189
	v_fmac_f32_e32 v149, v253, v189
	v_fmac_f32_e32 v134, v252, v190
	v_fmac_f32_e32 v150, v253, v190
	v_fmac_f32_e32 v135, v252, v191
	v_fmac_f32_e32 v151, v253, v191
	s_waitcnt lgkmcnt(5)
	v_fmac_f32_e32 v136, v252, v232
	v_fmac_f32_e32 v152, v253, v232
	v_fmac_f32_e32 v137, v252, v233
	v_fmac_f32_e32 v153, v253, v233
	v_fmac_f32_e32 v138, v252, v234
	v_fmac_f32_e32 v154, v253, v234
	v_fmac_f32_e32 v139, v252, v235
	v_fmac_f32_e32 v155, v253, v235
	s_waitcnt lgkmcnt(4)
	v_fmac_f32_e32 v140, v252, v240
	v_fmac_f32_e32 v156, v253, v240
	v_fmac_f32_e32 v141, v252, v241
	v_fmac_f32_e32 v157, v253, v241
	v_fmac_f32_e32 v142, v252, v242
	v_fmac_f32_e32 v158, v253, v242
	v_fmac_f32_e32 v143, v252, v243
	v_fmac_f32_e32 v159, v253, v243
	ds_read_b128 v[184:187], v244 offset:12288
	ds_read_b128 v[188:191], v245 offset:12288
	ds_read_b128 v[232:235], v246 offset:12288
	ds_read_b128 v[240:243], v247 offset:12288
	v_mul_f32_e32 v252, v66, v202
	v_fmac_f32_e32 v254, v66, v66
	v_mul_f32_e32 v253, v98, v202
	v_fmac_f32_e32 v255, v98, v98
	s_waitcnt lgkmcnt(7)
	v_fmac_f32_e32 v128, v252, v168
	v_fmac_f32_e32 v144, v253, v168
	v_fmac_f32_e32 v129, v252, v169
	v_fmac_f32_e32 v145, v253, v169
	v_fmac_f32_e32 v130, v252, v170
	v_fmac_f32_e32 v146, v253, v170
	v_fmac_f32_e32 v131, v252, v171
	v_fmac_f32_e32 v147, v253, v171
	s_waitcnt lgkmcnt(6)
	v_fmac_f32_e32 v132, v252, v172
	v_fmac_f32_e32 v148, v253, v172
	v_fmac_f32_e32 v133, v252, v173
	v_fmac_f32_e32 v149, v253, v173
	v_fmac_f32_e32 v134, v252, v174
	v_fmac_f32_e32 v150, v253, v174
	v_fmac_f32_e32 v135, v252, v175
	v_fmac_f32_e32 v151, v253, v175
	s_waitcnt lgkmcnt(5)
	v_fmac_f32_e32 v136, v252, v176
	v_fmac_f32_e32 v152, v253, v176
	v_fmac_f32_e32 v137, v252, v177
	v_fmac_f32_e32 v153, v253, v177
	v_fmac_f32_e32 v138, v252, v178
	v_fmac_f32_e32 v154, v253, v178
	v_fmac_f32_e32 v139, v252, v179
	v_fmac_f32_e32 v155, v253, v179
	s_waitcnt lgkmcnt(4)
	v_fmac_f32_e32 v140, v252, v180
	v_fmac_f32_e32 v156, v253, v180
	v_fmac_f32_e32 v141, v252, v181
	v_fmac_f32_e32 v157, v253, v181
	v_fmac_f32_e32 v142, v252, v182
	v_fmac_f32_e32 v158, v253, v182
	v_fmac_f32_e32 v143, v252, v183
	v_fmac_f32_e32 v159, v253, v183
	ds_read_b128 v[168:171], v244 offset:16384
	ds_read_b128 v[172:175], v245 offset:16384
	ds_read_b128 v[176:179], v246 offset:16384
	ds_read_b128 v[180:183], v247 offset:16384
	v_mul_f32_e32 v252, v67, v203
	v_fmac_f32_e32 v254, v67, v67
	v_mul_f32_e32 v253, v99, v203
	v_fmac_f32_e32 v255, v99, v99
	s_waitcnt lgkmcnt(7)
	v_fmac_f32_e32 v128, v252, v184
	v_fmac_f32_e32 v144, v253, v184
	v_fmac_f32_e32 v129, v252, v185
	v_fmac_f32_e32 v145, v253, v185
	v_fmac_f32_e32 v130, v252, v186
	v_fmac_f32_e32 v146, v253, v186
	v_fmac_f32_e32 v131, v252, v187
	v_fmac_f32_e32 v147, v253, v187
	s_waitcnt lgkmcnt(6)
	v_fmac_f32_e32 v132, v252, v188
	v_fmac_f32_e32 v148, v253, v188
	v_fmac_f32_e32 v133, v252, v189
	v_fmac_f32_e32 v149, v253, v189
	v_fmac_f32_e32 v134, v252, v190
	v_fmac_f32_e32 v150, v253, v190
	v_fmac_f32_e32 v135, v252, v191
	v_fmac_f32_e32 v151, v253, v191
	s_waitcnt lgkmcnt(5)
	v_fmac_f32_e32 v136, v252, v232
	v_fmac_f32_e32 v152, v253, v232
	v_fmac_f32_e32 v137, v252, v233
	v_fmac_f32_e32 v153, v253, v233
	v_fmac_f32_e32 v138, v252, v234
	v_fmac_f32_e32 v154, v253, v234
	v_fmac_f32_e32 v139, v252, v235
	v_fmac_f32_e32 v155, v253, v235
	s_waitcnt lgkmcnt(4)
	v_fmac_f32_e32 v140, v252, v240
	v_fmac_f32_e32 v156, v253, v240
	v_fmac_f32_e32 v141, v252, v241
	v_fmac_f32_e32 v157, v253, v241
	v_fmac_f32_e32 v142, v252, v242
	v_fmac_f32_e32 v158, v253, v242
	v_fmac_f32_e32 v143, v252, v243
	v_fmac_f32_e32 v159, v253, v243
	ds_read_b128 v[184:187], v244 offset:20480
	ds_read_b128 v[188:191], v245 offset:20480
	ds_read_b128 v[232:235], v246 offset:20480
	ds_read_b128 v[240:243], v247 offset:20480
	v_mul_f32_e32 v252, v68, v204
	v_fmac_f32_e32 v254, v68, v68
	v_mul_f32_e32 v253, v100, v204
	v_fmac_f32_e32 v255, v100, v100
	s_waitcnt lgkmcnt(7)
	v_fmac_f32_e32 v128, v252, v168
	v_fmac_f32_e32 v144, v253, v168
	v_fmac_f32_e32 v129, v252, v169
	v_fmac_f32_e32 v145, v253, v169
	v_fmac_f32_e32 v130, v252, v170
	v_fmac_f32_e32 v146, v253, v170
	v_fmac_f32_e32 v131, v252, v171
	v_fmac_f32_e32 v147, v253, v171
	s_waitcnt lgkmcnt(6)
	v_fmac_f32_e32 v132, v252, v172
	v_fmac_f32_e32 v148, v253, v172
	v_fmac_f32_e32 v133, v252, v173
	v_fmac_f32_e32 v149, v253, v173
	v_fmac_f32_e32 v134, v252, v174
	v_fmac_f32_e32 v150, v253, v174
	v_fmac_f32_e32 v135, v252, v175
	v_fmac_f32_e32 v151, v253, v175
	s_waitcnt lgkmcnt(5)
	v_fmac_f32_e32 v136, v252, v176
	v_fmac_f32_e32 v152, v253, v176
	v_fmac_f32_e32 v137, v252, v177
	v_fmac_f32_e32 v153, v253, v177
	v_fmac_f32_e32 v138, v252, v178
	v_fmac_f32_e32 v154, v253, v178
	v_fmac_f32_e32 v139, v252, v179
	v_fmac_f32_e32 v155, v253, v179
	s_waitcnt lgkmcnt(4)
	v_fmac_f32_e32 v140, v252, v180
	v_fmac_f32_e32 v156, v253, v180
	v_fmac_f32_e32 v141, v252, v181
	v_fmac_f32_e32 v157, v253, v181
	v_fmac_f32_e32 v142, v252, v182
	v_fmac_f32_e32 v158, v253, v182
	v_fmac_f32_e32 v143, v252, v183
	v_fmac_f32_e32 v159, v253, v183
	ds_read_b128 v[168:171], v244 offset:24576
	ds_read_b128 v[172:175], v245 offset:24576
	ds_read_b128 v[176:179], v246 offset:24576
	ds_read_b128 v[180:183], v247 offset:24576
	v_mul_f32_e32 v252, v69, v205
	v_fmac_f32_e32 v254, v69, v69
	v_mul_f32_e32 v253, v101, v205
	v_fmac_f32_e32 v255, v101, v101
	s_waitcnt lgkmcnt(7)
	v_fmac_f32_e32 v128, v252, v184
	v_fmac_f32_e32 v144, v253, v184
	v_fmac_f32_e32 v129, v252, v185
	v_fmac_f32_e32 v145, v253, v185
	v_fmac_f32_e32 v130, v252, v186
	v_fmac_f32_e32 v146, v253, v186
	v_fmac_f32_e32 v131, v252, v187
	v_fmac_f32_e32 v147, v253, v187
	s_waitcnt lgkmcnt(6)
	v_fmac_f32_e32 v132, v252, v188
	v_fmac_f32_e32 v148, v253, v188
	v_fmac_f32_e32 v133, v252, v189
	v_fmac_f32_e32 v149, v253, v189
	v_fmac_f32_e32 v134, v252, v190
	v_fmac_f32_e32 v150, v253, v190
	v_fmac_f32_e32 v135, v252, v191
	v_fmac_f32_e32 v151, v253, v191
	s_waitcnt lgkmcnt(5)
	v_fmac_f32_e32 v136, v252, v232
	v_fmac_f32_e32 v152, v253, v232
	v_fmac_f32_e32 v137, v252, v233
	v_fmac_f32_e32 v153, v253, v233
	v_fmac_f32_e32 v138, v252, v234
	v_fmac_f32_e32 v154, v253, v234
	v_fmac_f32_e32 v139, v252, v235
	v_fmac_f32_e32 v155, v253, v235
	s_waitcnt lgkmcnt(4)
	v_fmac_f32_e32 v140, v252, v240
	v_fmac_f32_e32 v156, v253, v240
	v_fmac_f32_e32 v141, v252, v241
	v_fmac_f32_e32 v157, v253, v241
	v_fmac_f32_e32 v142, v252, v242
	v_fmac_f32_e32 v158, v253, v242
	v_fmac_f32_e32 v143, v252, v243
	v_fmac_f32_e32 v159, v253, v243
	ds_read_b128 v[184:187], v244 offset:28672
	ds_read_b128 v[188:191], v245 offset:28672
	ds_read_b128 v[232:235], v246 offset:28672
	ds_read_b128 v[240:243], v247 offset:28672
	v_mul_f32_e32 v252, v70, v206
	v_fmac_f32_e32 v254, v70, v70
	v_mul_f32_e32 v253, v102, v206
	v_fmac_f32_e32 v255, v102, v102
	s_waitcnt lgkmcnt(7)
	v_fmac_f32_e32 v128, v252, v168
	v_fmac_f32_e32 v144, v253, v168
	v_fmac_f32_e32 v129, v252, v169
	v_fmac_f32_e32 v145, v253, v169
	v_fmac_f32_e32 v130, v252, v170
	v_fmac_f32_e32 v146, v253, v170
	v_fmac_f32_e32 v131, v252, v171
	v_fmac_f32_e32 v147, v253, v171
	s_waitcnt lgkmcnt(6)
	v_fmac_f32_e32 v132, v252, v172
	v_fmac_f32_e32 v148, v253, v172
	v_fmac_f32_e32 v133, v252, v173
	v_fmac_f32_e32 v149, v253, v173
	v_fmac_f32_e32 v134, v252, v174
	v_fmac_f32_e32 v150, v253, v174
	v_fmac_f32_e32 v135, v252, v175
	v_fmac_f32_e32 v151, v253, v175
	s_waitcnt lgkmcnt(5)
	v_fmac_f32_e32 v136, v252, v176
	v_fmac_f32_e32 v152, v253, v176
	v_fmac_f32_e32 v137, v252, v177
	v_fmac_f32_e32 v153, v253, v177
	v_fmac_f32_e32 v138, v252, v178
	v_fmac_f32_e32 v154, v253, v178
	v_fmac_f32_e32 v139, v252, v179
	v_fmac_f32_e32 v155, v253, v179
	s_waitcnt lgkmcnt(4)
	v_fmac_f32_e32 v140, v252, v180
	v_fmac_f32_e32 v156, v253, v180
	v_fmac_f32_e32 v141, v252, v181
	v_fmac_f32_e32 v157, v253, v181
	v_fmac_f32_e32 v142, v252, v182
	v_fmac_f32_e32 v158, v253, v182
	v_fmac_f32_e32 v143, v252, v183
	v_fmac_f32_e32 v159, v253, v183
	ds_read_b128 v[168:171], v244 offset:32768
	ds_read_b128 v[172:175], v245 offset:32768
	ds_read_b128 v[176:179], v246 offset:32768
	ds_read_b128 v[180:183], v247 offset:32768
	v_mul_f32_e32 v252, v71, v207
	v_fmac_f32_e32 v254, v71, v71
	v_mul_f32_e32 v253, v103, v207
	v_fmac_f32_e32 v255, v103, v103
	s_waitcnt lgkmcnt(7)
	v_fmac_f32_e32 v128, v252, v184
	v_fmac_f32_e32 v144, v253, v184
	v_fmac_f32_e32 v129, v252, v185
	v_fmac_f32_e32 v145, v253, v185
	v_fmac_f32_e32 v130, v252, v186
	v_fmac_f32_e32 v146, v253, v186
	v_fmac_f32_e32 v131, v252, v187
	v_fmac_f32_e32 v147, v253, v187
	s_waitcnt lgkmcnt(6)
	v_fmac_f32_e32 v132, v252, v188
	v_fmac_f32_e32 v148, v253, v188
	v_fmac_f32_e32 v133, v252, v189
	v_fmac_f32_e32 v149, v253, v189
	v_fmac_f32_e32 v134, v252, v190
	v_fmac_f32_e32 v150, v253, v190
	v_fmac_f32_e32 v135, v252, v191
	v_fmac_f32_e32 v151, v253, v191
	s_waitcnt lgkmcnt(5)
	v_fmac_f32_e32 v136, v252, v232
	v_fmac_f32_e32 v152, v253, v232
	v_fmac_f32_e32 v137, v252, v233
	v_fmac_f32_e32 v153, v253, v233
	v_fmac_f32_e32 v138, v252, v234
	v_fmac_f32_e32 v154, v253, v234
	v_fmac_f32_e32 v139, v252, v235
	v_fmac_f32_e32 v155, v253, v235
	s_waitcnt lgkmcnt(4)
	v_fmac_f32_e32 v140, v252, v240
	v_fmac_f32_e32 v156, v253, v240
	v_fmac_f32_e32 v141, v252, v241
	v_fmac_f32_e32 v157, v253, v241
	v_fmac_f32_e32 v142, v252, v242
	v_fmac_f32_e32 v158, v253, v242
	v_fmac_f32_e32 v143, v252, v243
	v_fmac_f32_e32 v159, v253, v243
	ds_read_b128 v[184:187], v244 offset:36864
	ds_read_b128 v[188:191], v245 offset:36864
	ds_read_b128 v[232:235], v246 offset:36864
	ds_read_b128 v[240:243], v247 offset:36864
	v_mul_f32_e32 v252, v72, v208
	v_fmac_f32_e32 v254, v72, v72
	v_mul_f32_e32 v253, v104, v208
	v_fmac_f32_e32 v255, v104, v104
	s_waitcnt lgkmcnt(7)
	v_fmac_f32_e32 v128, v252, v168
	v_fmac_f32_e32 v144, v253, v168
	v_fmac_f32_e32 v129, v252, v169
	v_fmac_f32_e32 v145, v253, v169
	v_fmac_f32_e32 v130, v252, v170
	v_fmac_f32_e32 v146, v253, v170
	v_fmac_f32_e32 v131, v252, v171
	v_fmac_f32_e32 v147, v253, v171
	s_waitcnt lgkmcnt(6)
	v_fmac_f32_e32 v132, v252, v172
	v_fmac_f32_e32 v148, v253, v172
	v_fmac_f32_e32 v133, v252, v173
	v_fmac_f32_e32 v149, v253, v173
	v_fmac_f32_e32 v134, v252, v174
	v_fmac_f32_e32 v150, v253, v174
	v_fmac_f32_e32 v135, v252, v175
	v_fmac_f32_e32 v151, v253, v175
	s_waitcnt lgkmcnt(5)
	v_fmac_f32_e32 v136, v252, v176
	v_fmac_f32_e32 v152, v253, v176
	v_fmac_f32_e32 v137, v252, v177
	v_fmac_f32_e32 v153, v253, v177
	v_fmac_f32_e32 v138, v252, v178
	v_fmac_f32_e32 v154, v253, v178
	v_fmac_f32_e32 v139, v252, v179
	v_fmac_f32_e32 v155, v253, v179
	s_waitcnt lgkmcnt(4)
	v_fmac_f32_e32 v140, v252, v180
	v_fmac_f32_e32 v156, v253, v180
	v_fmac_f32_e32 v141, v252, v181
	v_fmac_f32_e32 v157, v253, v181
	v_fmac_f32_e32 v142, v252, v182
	v_fmac_f32_e32 v158, v253, v182
	v_fmac_f32_e32 v143, v252, v183
	v_fmac_f32_e32 v159, v253, v183
	ds_read_b128 v[168:171], v244 offset:40960
	ds_read_b128 v[172:175], v245 offset:40960
	ds_read_b128 v[176:179], v246 offset:40960
	ds_read_b128 v[180:183], v247 offset:40960
	v_mul_f32_e32 v252, v73, v209
	v_fmac_f32_e32 v254, v73, v73
	v_mul_f32_e32 v253, v105, v209
	v_fmac_f32_e32 v255, v105, v105
	s_waitcnt lgkmcnt(7)
	v_fmac_f32_e32 v128, v252, v184
	v_fmac_f32_e32 v144, v253, v184
	v_fmac_f32_e32 v129, v252, v185
	v_fmac_f32_e32 v145, v253, v185
	v_fmac_f32_e32 v130, v252, v186
	v_fmac_f32_e32 v146, v253, v186
	v_fmac_f32_e32 v131, v252, v187
	v_fmac_f32_e32 v147, v253, v187
	s_waitcnt lgkmcnt(6)
	v_fmac_f32_e32 v132, v252, v188
	v_fmac_f32_e32 v148, v253, v188
	v_fmac_f32_e32 v133, v252, v189
	v_fmac_f32_e32 v149, v253, v189
	v_fmac_f32_e32 v134, v252, v190
	v_fmac_f32_e32 v150, v253, v190
	v_fmac_f32_e32 v135, v252, v191
	v_fmac_f32_e32 v151, v253, v191
	s_waitcnt lgkmcnt(5)
	v_fmac_f32_e32 v136, v252, v232
	v_fmac_f32_e32 v152, v253, v232
	v_fmac_f32_e32 v137, v252, v233
	v_fmac_f32_e32 v153, v253, v233
	v_fmac_f32_e32 v138, v252, v234
	v_fmac_f32_e32 v154, v253, v234
	v_fmac_f32_e32 v139, v252, v235
	v_fmac_f32_e32 v155, v253, v235
	s_waitcnt lgkmcnt(4)
	v_fmac_f32_e32 v140, v252, v240
	v_fmac_f32_e32 v156, v253, v240
	v_fmac_f32_e32 v141, v252, v241
	v_fmac_f32_e32 v157, v253, v241
	v_fmac_f32_e32 v142, v252, v242
	v_fmac_f32_e32 v158, v253, v242
	v_fmac_f32_e32 v143, v252, v243
	v_fmac_f32_e32 v159, v253, v243
	ds_read_b128 v[184:187], v244 offset:45056
	ds_read_b128 v[188:191], v245 offset:45056
	ds_read_b128 v[232:235], v246 offset:45056
	ds_read_b128 v[240:243], v247 offset:45056
	v_mul_f32_e32 v252, v74, v210
	v_fmac_f32_e32 v254, v74, v74
	v_mul_f32_e32 v253, v106, v210
	v_fmac_f32_e32 v255, v106, v106
	s_waitcnt lgkmcnt(7)
	v_fmac_f32_e32 v128, v252, v168
	v_fmac_f32_e32 v144, v253, v168
	v_fmac_f32_e32 v129, v252, v169
	v_fmac_f32_e32 v145, v253, v169
	v_fmac_f32_e32 v130, v252, v170
	v_fmac_f32_e32 v146, v253, v170
	v_fmac_f32_e32 v131, v252, v171
	v_fmac_f32_e32 v147, v253, v171
	s_waitcnt lgkmcnt(6)
	v_fmac_f32_e32 v132, v252, v172
	v_fmac_f32_e32 v148, v253, v172
	v_fmac_f32_e32 v133, v252, v173
	v_fmac_f32_e32 v149, v253, v173
	v_fmac_f32_e32 v134, v252, v174
	v_fmac_f32_e32 v150, v253, v174
	v_fmac_f32_e32 v135, v252, v175
	v_fmac_f32_e32 v151, v253, v175
	s_waitcnt lgkmcnt(5)
	v_fmac_f32_e32 v136, v252, v176
	v_fmac_f32_e32 v152, v253, v176
	v_fmac_f32_e32 v137, v252, v177
	v_fmac_f32_e32 v153, v253, v177
	v_fmac_f32_e32 v138, v252, v178
	v_fmac_f32_e32 v154, v253, v178
	v_fmac_f32_e32 v139, v252, v179
	v_fmac_f32_e32 v155, v253, v179
	s_waitcnt lgkmcnt(4)
	v_fmac_f32_e32 v140, v252, v180
	v_fmac_f32_e32 v156, v253, v180
	v_fmac_f32_e32 v141, v252, v181
	v_fmac_f32_e32 v157, v253, v181
	v_fmac_f32_e32 v142, v252, v182
	v_fmac_f32_e32 v158, v253, v182
	v_fmac_f32_e32 v143, v252, v183
	v_fmac_f32_e32 v159, v253, v183
	ds_read_b128 v[168:171], v244 offset:49152
	ds_read_b128 v[172:175], v245 offset:49152
	ds_read_b128 v[176:179], v246 offset:49152
	ds_read_b128 v[180:183], v247 offset:49152
	v_mul_f32_e32 v252, v75, v211
	v_fmac_f32_e32 v254, v75, v75
	v_mul_f32_e32 v253, v107, v211
	v_fmac_f32_e32 v255, v107, v107
	s_waitcnt lgkmcnt(7)
	v_fmac_f32_e32 v128, v252, v184
	v_fmac_f32_e32 v144, v253, v184
	v_fmac_f32_e32 v129, v252, v185
	v_fmac_f32_e32 v145, v253, v185
	v_fmac_f32_e32 v130, v252, v186
	v_fmac_f32_e32 v146, v253, v186
	v_fmac_f32_e32 v131, v252, v187
	v_fmac_f32_e32 v147, v253, v187
	s_waitcnt lgkmcnt(6)
	v_fmac_f32_e32 v132, v252, v188
	v_fmac_f32_e32 v148, v253, v188
	v_fmac_f32_e32 v133, v252, v189
	v_fmac_f32_e32 v149, v253, v189
	v_fmac_f32_e32 v134, v252, v190
	v_fmac_f32_e32 v150, v253, v190
	v_fmac_f32_e32 v135, v252, v191
	v_fmac_f32_e32 v151, v253, v191
	s_waitcnt lgkmcnt(5)
	v_fmac_f32_e32 v136, v252, v232
	v_fmac_f32_e32 v152, v253, v232
	v_fmac_f32_e32 v137, v252, v233
	v_fmac_f32_e32 v153, v253, v233
	v_fmac_f32_e32 v138, v252, v234
	v_fmac_f32_e32 v154, v253, v234
	v_fmac_f32_e32 v139, v252, v235
	v_fmac_f32_e32 v155, v253, v235
	s_waitcnt lgkmcnt(4)
	v_fmac_f32_e32 v140, v252, v240
	v_fmac_f32_e32 v156, v253, v240
	v_fmac_f32_e32 v141, v252, v241
	v_fmac_f32_e32 v157, v253, v241
	v_fmac_f32_e32 v142, v252, v242
	v_fmac_f32_e32 v158, v253, v242
	v_fmac_f32_e32 v143, v252, v243
	v_fmac_f32_e32 v159, v253, v243
	ds_read_b128 v[184:187], v244 offset:53248
	ds_read_b128 v[188:191], v245 offset:53248
	ds_read_b128 v[232:235], v246 offset:53248
	ds_read_b128 v[240:243], v247 offset:53248
	v_mul_f32_e32 v252, v76, v212
	v_fmac_f32_e32 v254, v76, v76
	v_mul_f32_e32 v253, v108, v212
	v_fmac_f32_e32 v255, v108, v108
	s_waitcnt lgkmcnt(7)
	v_fmac_f32_e32 v128, v252, v168
	v_fmac_f32_e32 v144, v253, v168
	v_fmac_f32_e32 v129, v252, v169
	v_fmac_f32_e32 v145, v253, v169
	v_fmac_f32_e32 v130, v252, v170
	v_fmac_f32_e32 v146, v253, v170
	v_fmac_f32_e32 v131, v252, v171
	v_fmac_f32_e32 v147, v253, v171
	s_waitcnt lgkmcnt(6)
	v_fmac_f32_e32 v132, v252, v172
	v_fmac_f32_e32 v148, v253, v172
	v_fmac_f32_e32 v133, v252, v173
	v_fmac_f32_e32 v149, v253, v173
	v_fmac_f32_e32 v134, v252, v174
	v_fmac_f32_e32 v150, v253, v174
	v_fmac_f32_e32 v135, v252, v175
	v_fmac_f32_e32 v151, v253, v175
	s_waitcnt lgkmcnt(5)
	v_fmac_f32_e32 v136, v252, v176
	v_fmac_f32_e32 v152, v253, v176
	v_fmac_f32_e32 v137, v252, v177
	v_fmac_f32_e32 v153, v253, v177
	v_fmac_f32_e32 v138, v252, v178
	v_fmac_f32_e32 v154, v253, v178
	v_fmac_f32_e32 v139, v252, v179
	v_fmac_f32_e32 v155, v253, v179
	s_waitcnt lgkmcnt(4)
	v_fmac_f32_e32 v140, v252, v180
	v_fmac_f32_e32 v156, v253, v180
	v_fmac_f32_e32 v141, v252, v181
	v_fmac_f32_e32 v157, v253, v181
	v_fmac_f32_e32 v142, v252, v182
	v_fmac_f32_e32 v158, v253, v182
	v_fmac_f32_e32 v143, v252, v183
	v_fmac_f32_e32 v159, v253, v183
	ds_read_b128 v[168:171], v244 offset:57344
	ds_read_b128 v[172:175], v245 offset:57344
	ds_read_b128 v[176:179], v246 offset:57344
	ds_read_b128 v[180:183], v247 offset:57344
	v_mul_f32_e32 v252, v77, v213
	v_fmac_f32_e32 v254, v77, v77
	v_mul_f32_e32 v253, v109, v213
	v_fmac_f32_e32 v255, v109, v109
	s_waitcnt lgkmcnt(7)
	v_fmac_f32_e32 v128, v252, v184
	v_fmac_f32_e32 v144, v253, v184
	v_fmac_f32_e32 v129, v252, v185
	v_fmac_f32_e32 v145, v253, v185
	v_fmac_f32_e32 v130, v252, v186
	v_fmac_f32_e32 v146, v253, v186
	v_fmac_f32_e32 v131, v252, v187
	v_fmac_f32_e32 v147, v253, v187
	s_waitcnt lgkmcnt(6)
	v_fmac_f32_e32 v132, v252, v188
	v_fmac_f32_e32 v148, v253, v188
	v_fmac_f32_e32 v133, v252, v189
	v_fmac_f32_e32 v149, v253, v189
	v_fmac_f32_e32 v134, v252, v190
	v_fmac_f32_e32 v150, v253, v190
	v_fmac_f32_e32 v135, v252, v191
	v_fmac_f32_e32 v151, v253, v191
	s_waitcnt lgkmcnt(5)
	v_fmac_f32_e32 v136, v252, v232
	v_fmac_f32_e32 v152, v253, v232
	v_fmac_f32_e32 v137, v252, v233
	v_fmac_f32_e32 v153, v253, v233
	v_fmac_f32_e32 v138, v252, v234
	v_fmac_f32_e32 v154, v253, v234
	v_fmac_f32_e32 v139, v252, v235
	v_fmac_f32_e32 v155, v253, v235
	s_waitcnt lgkmcnt(4)
	v_fmac_f32_e32 v140, v252, v240
	v_fmac_f32_e32 v156, v253, v240
	v_fmac_f32_e32 v141, v252, v241
	v_fmac_f32_e32 v157, v253, v241
	v_fmac_f32_e32 v142, v252, v242
	v_fmac_f32_e32 v158, v253, v242
	v_fmac_f32_e32 v143, v252, v243
	v_fmac_f32_e32 v159, v253, v243
	ds_read_b128 v[184:187], v244 offset:61440
	ds_read_b128 v[188:191], v245 offset:61440
	ds_read_b128 v[232:235], v246 offset:61440
	ds_read_b128 v[240:243], v247 offset:61440
	v_mul_f32_e32 v252, v78, v214
	v_fmac_f32_e32 v254, v78, v78
	v_mul_f32_e32 v253, v110, v214
	v_fmac_f32_e32 v255, v110, v110
	s_waitcnt lgkmcnt(7)
	v_fmac_f32_e32 v128, v252, v168
	v_fmac_f32_e32 v144, v253, v168
	v_fmac_f32_e32 v129, v252, v169
	v_fmac_f32_e32 v145, v253, v169
	v_fmac_f32_e32 v130, v252, v170
	v_fmac_f32_e32 v146, v253, v170
	v_fmac_f32_e32 v131, v252, v171
	v_fmac_f32_e32 v147, v253, v171
	s_waitcnt lgkmcnt(6)
	v_fmac_f32_e32 v132, v252, v172
	v_fmac_f32_e32 v148, v253, v172
	v_fmac_f32_e32 v133, v252, v173
	v_fmac_f32_e32 v149, v253, v173
	v_fmac_f32_e32 v134, v252, v174
	v_fmac_f32_e32 v150, v253, v174
	v_fmac_f32_e32 v135, v252, v175
	v_fmac_f32_e32 v151, v253, v175
	s_waitcnt lgkmcnt(5)
	v_fmac_f32_e32 v136, v252, v176
	v_fmac_f32_e32 v152, v253, v176
	v_fmac_f32_e32 v137, v252, v177
	v_fmac_f32_e32 v153, v253, v177
	v_fmac_f32_e32 v138, v252, v178
	v_fmac_f32_e32 v154, v253, v178
	v_fmac_f32_e32 v139, v252, v179
	v_fmac_f32_e32 v155, v253, v179
	s_waitcnt lgkmcnt(4)
	v_fmac_f32_e32 v140, v252, v180
	v_fmac_f32_e32 v156, v253, v180
	v_fmac_f32_e32 v141, v252, v181
	v_fmac_f32_e32 v157, v253, v181
	v_fmac_f32_e32 v142, v252, v182
	v_fmac_f32_e32 v158, v253, v182
	v_fmac_f32_e32 v143, v252, v183
	v_fmac_f32_e32 v159, v253, v183
	ds_read_b128 v[168:171], v248 offset:0
	ds_read_b128 v[172:175], v249 offset:0
	ds_read_b128 v[176:179], v250 offset:0
	ds_read_b128 v[180:183], v251 offset:0
	v_mul_f32_e32 v252, v79, v215
	v_fmac_f32_e32 v254, v79, v79
	v_mul_f32_e32 v253, v111, v215
	v_fmac_f32_e32 v255, v111, v111
	s_waitcnt lgkmcnt(7)
	v_fmac_f32_e32 v128, v252, v184
	v_fmac_f32_e32 v144, v253, v184
	v_fmac_f32_e32 v129, v252, v185
	v_fmac_f32_e32 v145, v253, v185
	v_fmac_f32_e32 v130, v252, v186
	v_fmac_f32_e32 v146, v253, v186
	v_fmac_f32_e32 v131, v252, v187
	v_fmac_f32_e32 v147, v253, v187
	s_waitcnt lgkmcnt(6)
	v_fmac_f32_e32 v132, v252, v188
	v_fmac_f32_e32 v148, v253, v188
	v_fmac_f32_e32 v133, v252, v189
	v_fmac_f32_e32 v149, v253, v189
	v_fmac_f32_e32 v134, v252, v190
	v_fmac_f32_e32 v150, v253, v190
	v_fmac_f32_e32 v135, v252, v191
	v_fmac_f32_e32 v151, v253, v191
	s_waitcnt lgkmcnt(5)
	v_fmac_f32_e32 v136, v252, v232
	v_fmac_f32_e32 v152, v253, v232
	v_fmac_f32_e32 v137, v252, v233
	v_fmac_f32_e32 v153, v253, v233
	v_fmac_f32_e32 v138, v252, v234
	v_fmac_f32_e32 v154, v253, v234
	v_fmac_f32_e32 v139, v252, v235
	v_fmac_f32_e32 v155, v253, v235
	s_waitcnt lgkmcnt(4)
	v_fmac_f32_e32 v140, v252, v240
	v_fmac_f32_e32 v156, v253, v240
	v_fmac_f32_e32 v141, v252, v241
	v_fmac_f32_e32 v157, v253, v241
	v_fmac_f32_e32 v142, v252, v242
	v_fmac_f32_e32 v158, v253, v242
	v_fmac_f32_e32 v143, v252, v243
	v_fmac_f32_e32 v159, v253, v243
	ds_read_b128 v[184:187], v248 offset:4096
	ds_read_b128 v[188:191], v249 offset:4096
	ds_read_b128 v[232:235], v250 offset:4096
	ds_read_b128 v[240:243], v251 offset:4096
	v_mul_f32_e32 v252, v80, v216
	v_fmac_f32_e32 v254, v80, v80
	v_mul_f32_e32 v253, v112, v216
	v_fmac_f32_e32 v255, v112, v112
	s_waitcnt lgkmcnt(7)
	v_fmac_f32_e32 v128, v252, v168
	v_fmac_f32_e32 v144, v253, v168
	v_fmac_f32_e32 v129, v252, v169
	v_fmac_f32_e32 v145, v253, v169
	v_fmac_f32_e32 v130, v252, v170
	v_fmac_f32_e32 v146, v253, v170
	v_fmac_f32_e32 v131, v252, v171
	v_fmac_f32_e32 v147, v253, v171
	s_waitcnt lgkmcnt(6)
	v_fmac_f32_e32 v132, v252, v172
	v_fmac_f32_e32 v148, v253, v172
	v_fmac_f32_e32 v133, v252, v173
	v_fmac_f32_e32 v149, v253, v173
	v_fmac_f32_e32 v134, v252, v174
	v_fmac_f32_e32 v150, v253, v174
	v_fmac_f32_e32 v135, v252, v175
	v_fmac_f32_e32 v151, v253, v175
	s_waitcnt lgkmcnt(5)
	v_fmac_f32_e32 v136, v252, v176
	v_fmac_f32_e32 v152, v253, v176
	v_fmac_f32_e32 v137, v252, v177
	v_fmac_f32_e32 v153, v253, v177
	v_fmac_f32_e32 v138, v252, v178
	v_fmac_f32_e32 v154, v253, v178
	v_fmac_f32_e32 v139, v252, v179
	v_fmac_f32_e32 v155, v253, v179
	s_waitcnt lgkmcnt(4)
	v_fmac_f32_e32 v140, v252, v180
	v_fmac_f32_e32 v156, v253, v180
	v_fmac_f32_e32 v141, v252, v181
	v_fmac_f32_e32 v157, v253, v181
	v_fmac_f32_e32 v142, v252, v182
	v_fmac_f32_e32 v158, v253, v182
	v_fmac_f32_e32 v143, v252, v183
	v_fmac_f32_e32 v159, v253, v183
	ds_read_b128 v[168:171], v248 offset:8192
	ds_read_b128 v[172:175], v249 offset:8192
	ds_read_b128 v[176:179], v250 offset:8192
	ds_read_b128 v[180:183], v251 offset:8192
	v_mul_f32_e32 v252, v81, v217
	v_fmac_f32_e32 v254, v81, v81
	v_mul_f32_e32 v253, v113, v217
	v_fmac_f32_e32 v255, v113, v113
	s_waitcnt lgkmcnt(7)
	v_fmac_f32_e32 v128, v252, v184
	v_fmac_f32_e32 v144, v253, v184
	v_fmac_f32_e32 v129, v252, v185
	v_fmac_f32_e32 v145, v253, v185
	v_fmac_f32_e32 v130, v252, v186
	v_fmac_f32_e32 v146, v253, v186
	v_fmac_f32_e32 v131, v252, v187
	v_fmac_f32_e32 v147, v253, v187
	s_waitcnt lgkmcnt(6)
	v_fmac_f32_e32 v132, v252, v188
	v_fmac_f32_e32 v148, v253, v188
	v_fmac_f32_e32 v133, v252, v189
	v_fmac_f32_e32 v149, v253, v189
	v_fmac_f32_e32 v134, v252, v190
	v_fmac_f32_e32 v150, v253, v190
	v_fmac_f32_e32 v135, v252, v191
	v_fmac_f32_e32 v151, v253, v191
	s_waitcnt lgkmcnt(5)
	v_fmac_f32_e32 v136, v252, v232
	v_fmac_f32_e32 v152, v253, v232
	v_fmac_f32_e32 v137, v252, v233
	v_fmac_f32_e32 v153, v253, v233
	v_fmac_f32_e32 v138, v252, v234
	v_fmac_f32_e32 v154, v253, v234
	v_fmac_f32_e32 v139, v252, v235
	v_fmac_f32_e32 v155, v253, v235
	s_waitcnt lgkmcnt(4)
	v_fmac_f32_e32 v140, v252, v240
	v_fmac_f32_e32 v156, v253, v240
	v_fmac_f32_e32 v141, v252, v241
	v_fmac_f32_e32 v157, v253, v241
	v_fmac_f32_e32 v142, v252, v242
	v_fmac_f32_e32 v158, v253, v242
	v_fmac_f32_e32 v143, v252, v243
	v_fmac_f32_e32 v159, v253, v243
	ds_read_b128 v[184:187], v248 offset:12288
	ds_read_b128 v[188:191], v249 offset:12288
	ds_read_b128 v[232:235], v250 offset:12288
	ds_read_b128 v[240:243], v251 offset:12288
	v_mul_f32_e32 v252, v82, v218
	v_fmac_f32_e32 v254, v82, v82
	v_mul_f32_e32 v253, v114, v218
	v_fmac_f32_e32 v255, v114, v114
	s_waitcnt lgkmcnt(7)
	v_fmac_f32_e32 v128, v252, v168
	v_fmac_f32_e32 v144, v253, v168
	v_fmac_f32_e32 v129, v252, v169
	v_fmac_f32_e32 v145, v253, v169
	v_fmac_f32_e32 v130, v252, v170
	v_fmac_f32_e32 v146, v253, v170
	v_fmac_f32_e32 v131, v252, v171
	v_fmac_f32_e32 v147, v253, v171
	s_waitcnt lgkmcnt(6)
	v_fmac_f32_e32 v132, v252, v172
	v_fmac_f32_e32 v148, v253, v172
	v_fmac_f32_e32 v133, v252, v173
	v_fmac_f32_e32 v149, v253, v173
	v_fmac_f32_e32 v134, v252, v174
	v_fmac_f32_e32 v150, v253, v174
	v_fmac_f32_e32 v135, v252, v175
	v_fmac_f32_e32 v151, v253, v175
	s_waitcnt lgkmcnt(5)
	v_fmac_f32_e32 v136, v252, v176
	v_fmac_f32_e32 v152, v253, v176
	v_fmac_f32_e32 v137, v252, v177
	v_fmac_f32_e32 v153, v253, v177
	v_fmac_f32_e32 v138, v252, v178
	v_fmac_f32_e32 v154, v253, v178
	v_fmac_f32_e32 v139, v252, v179
	v_fmac_f32_e32 v155, v253, v179
	s_waitcnt lgkmcnt(4)
	v_fmac_f32_e32 v140, v252, v180
	v_fmac_f32_e32 v156, v253, v180
	v_fmac_f32_e32 v141, v252, v181
	v_fmac_f32_e32 v157, v253, v181
	v_fmac_f32_e32 v142, v252, v182
	v_fmac_f32_e32 v158, v253, v182
	v_fmac_f32_e32 v143, v252, v183
	v_fmac_f32_e32 v159, v253, v183
	ds_read_b128 v[168:171], v248 offset:16384
	ds_read_b128 v[172:175], v249 offset:16384
	ds_read_b128 v[176:179], v250 offset:16384
	ds_read_b128 v[180:183], v251 offset:16384
	v_mul_f32_e32 v252, v83, v219
	v_fmac_f32_e32 v254, v83, v83
	v_mul_f32_e32 v253, v115, v219
	v_fmac_f32_e32 v255, v115, v115
	s_waitcnt lgkmcnt(7)
	v_fmac_f32_e32 v128, v252, v184
	v_fmac_f32_e32 v144, v253, v184
	v_fmac_f32_e32 v129, v252, v185
	v_fmac_f32_e32 v145, v253, v185
	v_fmac_f32_e32 v130, v252, v186
	v_fmac_f32_e32 v146, v253, v186
	v_fmac_f32_e32 v131, v252, v187
	v_fmac_f32_e32 v147, v253, v187
	s_waitcnt lgkmcnt(6)
	v_fmac_f32_e32 v132, v252, v188
	v_fmac_f32_e32 v148, v253, v188
	v_fmac_f32_e32 v133, v252, v189
	v_fmac_f32_e32 v149, v253, v189
	v_fmac_f32_e32 v134, v252, v190
	v_fmac_f32_e32 v150, v253, v190
	v_fmac_f32_e32 v135, v252, v191
	v_fmac_f32_e32 v151, v253, v191
	s_waitcnt lgkmcnt(5)
	v_fmac_f32_e32 v136, v252, v232
	v_fmac_f32_e32 v152, v253, v232
	v_fmac_f32_e32 v137, v252, v233
	v_fmac_f32_e32 v153, v253, v233
	v_fmac_f32_e32 v138, v252, v234
	v_fmac_f32_e32 v154, v253, v234
	v_fmac_f32_e32 v139, v252, v235
	v_fmac_f32_e32 v155, v253, v235
	s_waitcnt lgkmcnt(4)
	v_fmac_f32_e32 v140, v252, v240
	v_fmac_f32_e32 v156, v253, v240
	v_fmac_f32_e32 v141, v252, v241
	v_fmac_f32_e32 v157, v253, v241
	v_fmac_f32_e32 v142, v252, v242
	v_fmac_f32_e32 v158, v253, v242
	v_fmac_f32_e32 v143, v252, v243
	v_fmac_f32_e32 v159, v253, v243
	ds_read_b128 v[184:187], v248 offset:20480
	ds_read_b128 v[188:191], v249 offset:20480
	ds_read_b128 v[232:235], v250 offset:20480
	ds_read_b128 v[240:243], v251 offset:20480
	v_mul_f32_e32 v252, v84, v220
	v_fmac_f32_e32 v254, v84, v84
	v_mul_f32_e32 v253, v116, v220
	v_fmac_f32_e32 v255, v116, v116
	s_waitcnt lgkmcnt(7)
	v_fmac_f32_e32 v128, v252, v168
	v_fmac_f32_e32 v144, v253, v168
	v_fmac_f32_e32 v129, v252, v169
	v_fmac_f32_e32 v145, v253, v169
	v_fmac_f32_e32 v130, v252, v170
	v_fmac_f32_e32 v146, v253, v170
	v_fmac_f32_e32 v131, v252, v171
	v_fmac_f32_e32 v147, v253, v171
	s_waitcnt lgkmcnt(6)
	v_fmac_f32_e32 v132, v252, v172
	v_fmac_f32_e32 v148, v253, v172
	v_fmac_f32_e32 v133, v252, v173
	v_fmac_f32_e32 v149, v253, v173
	v_fmac_f32_e32 v134, v252, v174
	v_fmac_f32_e32 v150, v253, v174
	v_fmac_f32_e32 v135, v252, v175
	v_fmac_f32_e32 v151, v253, v175
	s_waitcnt lgkmcnt(5)
	v_fmac_f32_e32 v136, v252, v176
	v_fmac_f32_e32 v152, v253, v176
	v_fmac_f32_e32 v137, v252, v177
	v_fmac_f32_e32 v153, v253, v177
	v_fmac_f32_e32 v138, v252, v178
	v_fmac_f32_e32 v154, v253, v178
	v_fmac_f32_e32 v139, v252, v179
	v_fmac_f32_e32 v155, v253, v179
	s_waitcnt lgkmcnt(4)
	v_fmac_f32_e32 v140, v252, v180
	v_fmac_f32_e32 v156, v253, v180
	v_fmac_f32_e32 v141, v252, v181
	v_fmac_f32_e32 v157, v253, v181
	v_fmac_f32_e32 v142, v252, v182
	v_fmac_f32_e32 v158, v253, v182
	v_fmac_f32_e32 v143, v252, v183
	v_fmac_f32_e32 v159, v253, v183
	ds_read_b128 v[168:171], v248 offset:24576
	ds_read_b128 v[172:175], v249 offset:24576
	ds_read_b128 v[176:179], v250 offset:24576
	ds_read_b128 v[180:183], v251 offset:24576
	v_mul_f32_e32 v252, v85, v221
	v_fmac_f32_e32 v254, v85, v85
	v_mul_f32_e32 v253, v117, v221
	v_fmac_f32_e32 v255, v117, v117
	s_waitcnt lgkmcnt(7)
	v_fmac_f32_e32 v128, v252, v184
	v_fmac_f32_e32 v144, v253, v184
	v_fmac_f32_e32 v129, v252, v185
	v_fmac_f32_e32 v145, v253, v185
	v_fmac_f32_e32 v130, v252, v186
	v_fmac_f32_e32 v146, v253, v186
	v_fmac_f32_e32 v131, v252, v187
	v_fmac_f32_e32 v147, v253, v187
	s_waitcnt lgkmcnt(6)
	v_fmac_f32_e32 v132, v252, v188
	v_fmac_f32_e32 v148, v253, v188
	v_fmac_f32_e32 v133, v252, v189
	v_fmac_f32_e32 v149, v253, v189
	v_fmac_f32_e32 v134, v252, v190
	v_fmac_f32_e32 v150, v253, v190
	v_fmac_f32_e32 v135, v252, v191
	v_fmac_f32_e32 v151, v253, v191
	s_waitcnt lgkmcnt(5)
	v_fmac_f32_e32 v136, v252, v232
	v_fmac_f32_e32 v152, v253, v232
	v_fmac_f32_e32 v137, v252, v233
	v_fmac_f32_e32 v153, v253, v233
	v_fmac_f32_e32 v138, v252, v234
	v_fmac_f32_e32 v154, v253, v234
	v_fmac_f32_e32 v139, v252, v235
	v_fmac_f32_e32 v155, v253, v235
	s_waitcnt lgkmcnt(4)
	v_fmac_f32_e32 v140, v252, v240
	v_fmac_f32_e32 v156, v253, v240
	v_fmac_f32_e32 v141, v252, v241
	v_fmac_f32_e32 v157, v253, v241
	v_fmac_f32_e32 v142, v252, v242
	v_fmac_f32_e32 v158, v253, v242
	v_fmac_f32_e32 v143, v252, v243
	v_fmac_f32_e32 v159, v253, v243
	ds_read_b128 v[184:187], v248 offset:28672
	ds_read_b128 v[188:191], v249 offset:28672
	ds_read_b128 v[232:235], v250 offset:28672
	ds_read_b128 v[240:243], v251 offset:28672
	v_mul_f32_e32 v252, v86, v222
	v_fmac_f32_e32 v254, v86, v86
	v_mul_f32_e32 v253, v118, v222
	v_fmac_f32_e32 v255, v118, v118
	s_waitcnt lgkmcnt(7)
	v_fmac_f32_e32 v128, v252, v168
	v_fmac_f32_e32 v144, v253, v168
	v_fmac_f32_e32 v129, v252, v169
	v_fmac_f32_e32 v145, v253, v169
	v_fmac_f32_e32 v130, v252, v170
	v_fmac_f32_e32 v146, v253, v170
	v_fmac_f32_e32 v131, v252, v171
	v_fmac_f32_e32 v147, v253, v171
	s_waitcnt lgkmcnt(6)
	v_fmac_f32_e32 v132, v252, v172
	v_fmac_f32_e32 v148, v253, v172
	v_fmac_f32_e32 v133, v252, v173
	v_fmac_f32_e32 v149, v253, v173
	v_fmac_f32_e32 v134, v252, v174
	v_fmac_f32_e32 v150, v253, v174
	v_fmac_f32_e32 v135, v252, v175
	v_fmac_f32_e32 v151, v253, v175
	s_waitcnt lgkmcnt(5)
	v_fmac_f32_e32 v136, v252, v176
	v_fmac_f32_e32 v152, v253, v176
	v_fmac_f32_e32 v137, v252, v177
	v_fmac_f32_e32 v153, v253, v177
	v_fmac_f32_e32 v138, v252, v178
	v_fmac_f32_e32 v154, v253, v178
	v_fmac_f32_e32 v139, v252, v179
	v_fmac_f32_e32 v155, v253, v179
	s_waitcnt lgkmcnt(4)
	v_fmac_f32_e32 v140, v252, v180
	v_fmac_f32_e32 v156, v253, v180
	v_fmac_f32_e32 v141, v252, v181
	v_fmac_f32_e32 v157, v253, v181
	v_fmac_f32_e32 v142, v252, v182
	v_fmac_f32_e32 v158, v253, v182
	v_fmac_f32_e32 v143, v252, v183
	v_fmac_f32_e32 v159, v253, v183
	ds_read_b128 v[168:171], v248 offset:32768
	ds_read_b128 v[172:175], v249 offset:32768
	ds_read_b128 v[176:179], v250 offset:32768
	ds_read_b128 v[180:183], v251 offset:32768
	v_mul_f32_e32 v252, v87, v223
	v_fmac_f32_e32 v254, v87, v87
	v_mul_f32_e32 v253, v119, v223
	v_fmac_f32_e32 v255, v119, v119
	s_waitcnt lgkmcnt(7)
	v_fmac_f32_e32 v128, v252, v184
	v_fmac_f32_e32 v144, v253, v184
	v_fmac_f32_e32 v129, v252, v185
	v_fmac_f32_e32 v145, v253, v185
	v_fmac_f32_e32 v130, v252, v186
	v_fmac_f32_e32 v146, v253, v186
	v_fmac_f32_e32 v131, v252, v187
	v_fmac_f32_e32 v147, v253, v187
	s_waitcnt lgkmcnt(6)
	v_fmac_f32_e32 v132, v252, v188
	v_fmac_f32_e32 v148, v253, v188
	v_fmac_f32_e32 v133, v252, v189
	v_fmac_f32_e32 v149, v253, v189
	v_fmac_f32_e32 v134, v252, v190
	v_fmac_f32_e32 v150, v253, v190
	v_fmac_f32_e32 v135, v252, v191
	v_fmac_f32_e32 v151, v253, v191
	s_waitcnt lgkmcnt(5)
	v_fmac_f32_e32 v136, v252, v232
	v_fmac_f32_e32 v152, v253, v232
	v_fmac_f32_e32 v137, v252, v233
	v_fmac_f32_e32 v153, v253, v233
	v_fmac_f32_e32 v138, v252, v234
	v_fmac_f32_e32 v154, v253, v234
	v_fmac_f32_e32 v139, v252, v235
	v_fmac_f32_e32 v155, v253, v235
	s_waitcnt lgkmcnt(4)
	v_fmac_f32_e32 v140, v252, v240
	v_fmac_f32_e32 v156, v253, v240
	v_fmac_f32_e32 v141, v252, v241
	v_fmac_f32_e32 v157, v253, v241
	v_fmac_f32_e32 v142, v252, v242
	v_fmac_f32_e32 v158, v253, v242
	v_fmac_f32_e32 v143, v252, v243
	v_fmac_f32_e32 v159, v253, v243
	ds_read_b128 v[184:187], v248 offset:36864
	ds_read_b128 v[188:191], v249 offset:36864
	ds_read_b128 v[232:235], v250 offset:36864
	ds_read_b128 v[240:243], v251 offset:36864
	v_mul_f32_e32 v252, v88, v224
	v_fmac_f32_e32 v254, v88, v88
	v_mul_f32_e32 v253, v120, v224
	v_fmac_f32_e32 v255, v120, v120
	s_waitcnt lgkmcnt(7)
	v_fmac_f32_e32 v128, v252, v168
	v_fmac_f32_e32 v144, v253, v168
	v_fmac_f32_e32 v129, v252, v169
	v_fmac_f32_e32 v145, v253, v169
	v_fmac_f32_e32 v130, v252, v170
	v_fmac_f32_e32 v146, v253, v170
	v_fmac_f32_e32 v131, v252, v171
	v_fmac_f32_e32 v147, v253, v171
	s_waitcnt lgkmcnt(6)
	v_fmac_f32_e32 v132, v252, v172
	v_fmac_f32_e32 v148, v253, v172
	v_fmac_f32_e32 v133, v252, v173
	v_fmac_f32_e32 v149, v253, v173
	v_fmac_f32_e32 v134, v252, v174
	v_fmac_f32_e32 v150, v253, v174
	v_fmac_f32_e32 v135, v252, v175
	v_fmac_f32_e32 v151, v253, v175
	s_waitcnt lgkmcnt(5)
	v_fmac_f32_e32 v136, v252, v176
	v_fmac_f32_e32 v152, v253, v176
	v_fmac_f32_e32 v137, v252, v177
	v_fmac_f32_e32 v153, v253, v177
	v_fmac_f32_e32 v138, v252, v178
	v_fmac_f32_e32 v154, v253, v178
	v_fmac_f32_e32 v139, v252, v179
	v_fmac_f32_e32 v155, v253, v179
	s_waitcnt lgkmcnt(4)
	v_fmac_f32_e32 v140, v252, v180
	v_fmac_f32_e32 v156, v253, v180
	v_fmac_f32_e32 v141, v252, v181
	v_fmac_f32_e32 v157, v253, v181
	v_fmac_f32_e32 v142, v252, v182
	v_fmac_f32_e32 v158, v253, v182
	v_fmac_f32_e32 v143, v252, v183
	v_fmac_f32_e32 v159, v253, v183
	ds_read_b128 v[168:171], v248 offset:40960
	ds_read_b128 v[172:175], v249 offset:40960
	ds_read_b128 v[176:179], v250 offset:40960
	ds_read_b128 v[180:183], v251 offset:40960
	v_mul_f32_e32 v252, v89, v225
	v_fmac_f32_e32 v254, v89, v89
	v_mul_f32_e32 v253, v121, v225
	v_fmac_f32_e32 v255, v121, v121
	s_waitcnt lgkmcnt(7)
	v_fmac_f32_e32 v128, v252, v184
	v_fmac_f32_e32 v144, v253, v184
	v_fmac_f32_e32 v129, v252, v185
	v_fmac_f32_e32 v145, v253, v185
	v_fmac_f32_e32 v130, v252, v186
	v_fmac_f32_e32 v146, v253, v186
	v_fmac_f32_e32 v131, v252, v187
	v_fmac_f32_e32 v147, v253, v187
	s_waitcnt lgkmcnt(6)
	v_fmac_f32_e32 v132, v252, v188
	v_fmac_f32_e32 v148, v253, v188
	v_fmac_f32_e32 v133, v252, v189
	v_fmac_f32_e32 v149, v253, v189
	v_fmac_f32_e32 v134, v252, v190
	v_fmac_f32_e32 v150, v253, v190
	v_fmac_f32_e32 v135, v252, v191
	v_fmac_f32_e32 v151, v253, v191
	s_waitcnt lgkmcnt(5)
	v_fmac_f32_e32 v136, v252, v232
	v_fmac_f32_e32 v152, v253, v232
	v_fmac_f32_e32 v137, v252, v233
	v_fmac_f32_e32 v153, v253, v233
	v_fmac_f32_e32 v138, v252, v234
	v_fmac_f32_e32 v154, v253, v234
	v_fmac_f32_e32 v139, v252, v235
	v_fmac_f32_e32 v155, v253, v235
	s_waitcnt lgkmcnt(4)
	v_fmac_f32_e32 v140, v252, v240
	v_fmac_f32_e32 v156, v253, v240
	v_fmac_f32_e32 v141, v252, v241
	v_fmac_f32_e32 v157, v253, v241
	v_fmac_f32_e32 v142, v252, v242
	v_fmac_f32_e32 v158, v253, v242
	v_fmac_f32_e32 v143, v252, v243
	v_fmac_f32_e32 v159, v253, v243
	ds_read_b128 v[184:187], v248 offset:45056
	ds_read_b128 v[188:191], v249 offset:45056
	ds_read_b128 v[232:235], v250 offset:45056
	ds_read_b128 v[240:243], v251 offset:45056
	v_mul_f32_e32 v252, v90, v226
	v_fmac_f32_e32 v254, v90, v90
	v_mul_f32_e32 v253, v122, v226
	v_fmac_f32_e32 v255, v122, v122
	s_waitcnt lgkmcnt(7)
	v_fmac_f32_e32 v128, v252, v168
	v_fmac_f32_e32 v144, v253, v168
	v_fmac_f32_e32 v129, v252, v169
	v_fmac_f32_e32 v145, v253, v169
	v_fmac_f32_e32 v130, v252, v170
	v_fmac_f32_e32 v146, v253, v170
	v_fmac_f32_e32 v131, v252, v171
	v_fmac_f32_e32 v147, v253, v171
	s_waitcnt lgkmcnt(6)
	v_fmac_f32_e32 v132, v252, v172
	v_fmac_f32_e32 v148, v253, v172
	v_fmac_f32_e32 v133, v252, v173
	v_fmac_f32_e32 v149, v253, v173
	v_fmac_f32_e32 v134, v252, v174
	v_fmac_f32_e32 v150, v253, v174
	v_fmac_f32_e32 v135, v252, v175
	v_fmac_f32_e32 v151, v253, v175
	s_waitcnt lgkmcnt(5)
	v_fmac_f32_e32 v136, v252, v176
	v_fmac_f32_e32 v152, v253, v176
	v_fmac_f32_e32 v137, v252, v177
	v_fmac_f32_e32 v153, v253, v177
	v_fmac_f32_e32 v138, v252, v178
	v_fmac_f32_e32 v154, v253, v178
	v_fmac_f32_e32 v139, v252, v179
	v_fmac_f32_e32 v155, v253, v179
	s_waitcnt lgkmcnt(4)
	v_fmac_f32_e32 v140, v252, v180
	v_fmac_f32_e32 v156, v253, v180
	v_fmac_f32_e32 v141, v252, v181
	v_fmac_f32_e32 v157, v253, v181
	v_fmac_f32_e32 v142, v252, v182
	v_fmac_f32_e32 v158, v253, v182
	v_fmac_f32_e32 v143, v252, v183
	v_fmac_f32_e32 v159, v253, v183
	ds_read_b128 v[168:171], v248 offset:49152
	ds_read_b128 v[172:175], v249 offset:49152
	ds_read_b128 v[176:179], v250 offset:49152
	ds_read_b128 v[180:183], v251 offset:49152
	v_mul_f32_e32 v252, v91, v227
	v_fmac_f32_e32 v254, v91, v91
	v_mul_f32_e32 v253, v123, v227
	v_fmac_f32_e32 v255, v123, v123
	s_waitcnt lgkmcnt(7)
	v_fmac_f32_e32 v128, v252, v184
	v_fmac_f32_e32 v144, v253, v184
	v_fmac_f32_e32 v129, v252, v185
	v_fmac_f32_e32 v145, v253, v185
	v_fmac_f32_e32 v130, v252, v186
	v_fmac_f32_e32 v146, v253, v186
	v_fmac_f32_e32 v131, v252, v187
	v_fmac_f32_e32 v147, v253, v187
	s_waitcnt lgkmcnt(6)
	v_fmac_f32_e32 v132, v252, v188
	v_fmac_f32_e32 v148, v253, v188
	v_fmac_f32_e32 v133, v252, v189
	v_fmac_f32_e32 v149, v253, v189
	v_fmac_f32_e32 v134, v252, v190
	v_fmac_f32_e32 v150, v253, v190
	v_fmac_f32_e32 v135, v252, v191
	v_fmac_f32_e32 v151, v253, v191
	s_waitcnt lgkmcnt(5)
	v_fmac_f32_e32 v136, v252, v232
	v_fmac_f32_e32 v152, v253, v232
	v_fmac_f32_e32 v137, v252, v233
	v_fmac_f32_e32 v153, v253, v233
	v_fmac_f32_e32 v138, v252, v234
	v_fmac_f32_e32 v154, v253, v234
	v_fmac_f32_e32 v139, v252, v235
	v_fmac_f32_e32 v155, v253, v235
	s_waitcnt lgkmcnt(4)
	v_fmac_f32_e32 v140, v252, v240
	v_fmac_f32_e32 v156, v253, v240
	v_fmac_f32_e32 v141, v252, v241
	v_fmac_f32_e32 v157, v253, v241
	v_fmac_f32_e32 v142, v252, v242
	v_fmac_f32_e32 v158, v253, v242
	v_fmac_f32_e32 v143, v252, v243
	v_fmac_f32_e32 v159, v253, v243
	ds_read_b128 v[184:187], v248 offset:53248
	ds_read_b128 v[188:191], v249 offset:53248
	ds_read_b128 v[232:235], v250 offset:53248
	ds_read_b128 v[240:243], v251 offset:53248
	v_mul_f32_e32 v252, v92, v228
	v_fmac_f32_e32 v254, v92, v92
	v_mul_f32_e32 v253, v124, v228
	v_fmac_f32_e32 v255, v124, v124
	s_waitcnt lgkmcnt(7)
	v_fmac_f32_e32 v128, v252, v168
	v_fmac_f32_e32 v144, v253, v168
	v_fmac_f32_e32 v129, v252, v169
	v_fmac_f32_e32 v145, v253, v169
	v_fmac_f32_e32 v130, v252, v170
	v_fmac_f32_e32 v146, v253, v170
	v_fmac_f32_e32 v131, v252, v171
	v_fmac_f32_e32 v147, v253, v171
	s_waitcnt lgkmcnt(6)
	v_fmac_f32_e32 v132, v252, v172
	v_fmac_f32_e32 v148, v253, v172
	v_fmac_f32_e32 v133, v252, v173
	v_fmac_f32_e32 v149, v253, v173
	v_fmac_f32_e32 v134, v252, v174
	v_fmac_f32_e32 v150, v253, v174
	v_fmac_f32_e32 v135, v252, v175
	v_fmac_f32_e32 v151, v253, v175
	s_waitcnt lgkmcnt(5)
	v_fmac_f32_e32 v136, v252, v176
	v_fmac_f32_e32 v152, v253, v176
	v_fmac_f32_e32 v137, v252, v177
	v_fmac_f32_e32 v153, v253, v177
	v_fmac_f32_e32 v138, v252, v178
	v_fmac_f32_e32 v154, v253, v178
	v_fmac_f32_e32 v139, v252, v179
	v_fmac_f32_e32 v155, v253, v179
	s_waitcnt lgkmcnt(4)
	v_fmac_f32_e32 v140, v252, v180
	v_fmac_f32_e32 v156, v253, v180
	v_fmac_f32_e32 v141, v252, v181
	v_fmac_f32_e32 v157, v253, v181
	v_fmac_f32_e32 v142, v252, v182
	v_fmac_f32_e32 v158, v253, v182
	v_fmac_f32_e32 v143, v252, v183
	v_fmac_f32_e32 v159, v253, v183
	ds_read_b128 v[168:171], v248 offset:57344
	ds_read_b128 v[172:175], v249 offset:57344
	ds_read_b128 v[176:179], v250 offset:57344
	ds_read_b128 v[180:183], v251 offset:57344
	v_mul_f32_e32 v252, v93, v229
	v_fmac_f32_e32 v254, v93, v93
	v_mul_f32_e32 v253, v125, v229
	v_fmac_f32_e32 v255, v125, v125
	s_waitcnt lgkmcnt(7)
	v_fmac_f32_e32 v128, v252, v184
	v_fmac_f32_e32 v144, v253, v184
	v_fmac_f32_e32 v129, v252, v185
	v_fmac_f32_e32 v145, v253, v185
	v_fmac_f32_e32 v130, v252, v186
	v_fmac_f32_e32 v146, v253, v186
	v_fmac_f32_e32 v131, v252, v187
	v_fmac_f32_e32 v147, v253, v187
	s_waitcnt lgkmcnt(6)
	v_fmac_f32_e32 v132, v252, v188
	v_fmac_f32_e32 v148, v253, v188
	v_fmac_f32_e32 v133, v252, v189
	v_fmac_f32_e32 v149, v253, v189
	v_fmac_f32_e32 v134, v252, v190
	v_fmac_f32_e32 v150, v253, v190
	v_fmac_f32_e32 v135, v252, v191
	v_fmac_f32_e32 v151, v253, v191
	s_waitcnt lgkmcnt(5)
	v_fmac_f32_e32 v136, v252, v232
	v_fmac_f32_e32 v152, v253, v232
	v_fmac_f32_e32 v137, v252, v233
	v_fmac_f32_e32 v153, v253, v233
	v_fmac_f32_e32 v138, v252, v234
	v_fmac_f32_e32 v154, v253, v234
	v_fmac_f32_e32 v139, v252, v235
	v_fmac_f32_e32 v155, v253, v235
	s_waitcnt lgkmcnt(4)
	v_fmac_f32_e32 v140, v252, v240
	v_fmac_f32_e32 v156, v253, v240
	v_fmac_f32_e32 v141, v252, v241
	v_fmac_f32_e32 v157, v253, v241
	v_fmac_f32_e32 v142, v252, v242
	v_fmac_f32_e32 v158, v253, v242
	v_fmac_f32_e32 v143, v252, v243
	v_fmac_f32_e32 v159, v253, v243
	ds_read_b128 v[184:187], v248 offset:61440
	ds_read_b128 v[188:191], v249 offset:61440
	ds_read_b128 v[232:235], v250 offset:61440
	ds_read_b128 v[240:243], v251 offset:61440
	v_mul_f32_e32 v252, v94, v230
	v_fmac_f32_e32 v254, v94, v94
	v_mul_f32_e32 v253, v126, v230
	v_fmac_f32_e32 v255, v126, v126
	s_waitcnt lgkmcnt(7)
	v_fmac_f32_e32 v128, v252, v168
	v_fmac_f32_e32 v144, v253, v168
	v_fmac_f32_e32 v129, v252, v169
	v_fmac_f32_e32 v145, v253, v169
	v_fmac_f32_e32 v130, v252, v170
	v_fmac_f32_e32 v146, v253, v170
	v_fmac_f32_e32 v131, v252, v171
	v_fmac_f32_e32 v147, v253, v171
	s_waitcnt lgkmcnt(6)
	v_fmac_f32_e32 v132, v252, v172
	v_fmac_f32_e32 v148, v253, v172
	v_fmac_f32_e32 v133, v252, v173
	v_fmac_f32_e32 v149, v253, v173
	v_fmac_f32_e32 v134, v252, v174
	v_fmac_f32_e32 v150, v253, v174
	v_fmac_f32_e32 v135, v252, v175
	v_fmac_f32_e32 v151, v253, v175
	s_waitcnt lgkmcnt(5)
	v_fmac_f32_e32 v136, v252, v176
	v_fmac_f32_e32 v152, v253, v176
	v_fmac_f32_e32 v137, v252, v177
	v_fmac_f32_e32 v153, v253, v177
	v_fmac_f32_e32 v138, v252, v178
	v_fmac_f32_e32 v154, v253, v178
	v_fmac_f32_e32 v139, v252, v179
	v_fmac_f32_e32 v155, v253, v179
	s_waitcnt lgkmcnt(4)
	v_fmac_f32_e32 v140, v252, v180
	v_fmac_f32_e32 v156, v253, v180
	v_fmac_f32_e32 v141, v252, v181
	v_fmac_f32_e32 v157, v253, v181
	v_fmac_f32_e32 v142, v252, v182
	v_fmac_f32_e32 v158, v253, v182
	v_fmac_f32_e32 v143, v252, v183
	v_fmac_f32_e32 v159, v253, v183
	v_mul_f32_e32 v252, v95, v231
	v_fmac_f32_e32 v254, v95, v95
	v_mul_f32_e32 v253, v127, v231
	v_fmac_f32_e32 v255, v127, v127
	s_waitcnt lgkmcnt(3)
	v_fmac_f32_e32 v128, v252, v184
	v_fmac_f32_e32 v144, v253, v184
	v_fmac_f32_e32 v129, v252, v185
	v_fmac_f32_e32 v145, v253, v185
	v_fmac_f32_e32 v130, v252, v186
	v_fmac_f32_e32 v146, v253, v186
	v_fmac_f32_e32 v131, v252, v187
	v_fmac_f32_e32 v147, v253, v187
	s_waitcnt lgkmcnt(2)
	v_fmac_f32_e32 v132, v252, v188
	v_fmac_f32_e32 v148, v253, v188
	v_fmac_f32_e32 v133, v252, v189
	v_fmac_f32_e32 v149, v253, v189
	v_fmac_f32_e32 v134, v252, v190
	v_fmac_f32_e32 v150, v253, v190
	v_fmac_f32_e32 v135, v252, v191
	v_fmac_f32_e32 v151, v253, v191
	s_waitcnt lgkmcnt(1)
	v_fmac_f32_e32 v136, v252, v232
	v_fmac_f32_e32 v152, v253, v232
	v_fmac_f32_e32 v137, v252, v233
	v_fmac_f32_e32 v153, v253, v233
	v_fmac_f32_e32 v138, v252, v234
	v_fmac_f32_e32 v154, v253, v234
	v_fmac_f32_e32 v139, v252, v235
	v_fmac_f32_e32 v155, v253, v235
	s_waitcnt lgkmcnt(0)
	v_fmac_f32_e32 v140, v252, v240
	v_fmac_f32_e32 v156, v253, v240
	v_fmac_f32_e32 v141, v252, v241
	v_fmac_f32_e32 v157, v253, v241
	v_fmac_f32_e32 v142, v252, v242
	v_fmac_f32_e32 v158, v253, v242
	v_fmac_f32_e32 v143, v252, v243
	v_fmac_f32_e32 v159, v253, v243
	v_xor_b32_e32 v162, 32, v197
	v_lshlrev_b32_e32 v162, 2, v162
	ds_bpermute_b32 v160, v162, v254
	ds_bpermute_b32 v161, v162, v255
	s_waitcnt lgkmcnt(0)
	v_add_f32_e32 v254, v254, v160
	v_add_f32_e32 v255, v255, v161
	v_xor_b32_e32 v162, 16, v197
	v_lshlrev_b32_e32 v162, 2, v162
	ds_bpermute_b32 v160, v162, v254
	ds_bpermute_b32 v161, v162, v255
	s_waitcnt lgkmcnt(0)
	v_add_f32_e32 v254, v254, v160
	v_add_f32_e32 v255, v255, v161
	v_xor_b32_e32 v162, 8, v197
	v_lshlrev_b32_e32 v162, 2, v162
	ds_bpermute_b32 v160, v162, v254
	ds_bpermute_b32 v161, v162, v255
	s_waitcnt lgkmcnt(0)
	v_add_f32_e32 v254, v254, v160
	v_add_f32_e32 v255, v255, v161
	v_xor_b32_e32 v162, 4, v197
	v_lshlrev_b32_e32 v162, 2, v162
	ds_bpermute_b32 v160, v162, v254
	ds_bpermute_b32 v161, v162, v255
	s_waitcnt lgkmcnt(0)
	v_add_f32_e32 v254, v254, v160
	v_add_f32_e32 v255, v255, v161
	v_xor_b32_e32 v162, 2, v197
	v_lshlrev_b32_e32 v162, 2, v162
	ds_bpermute_b32 v160, v162, v254
	ds_bpermute_b32 v161, v162, v255
	s_waitcnt lgkmcnt(0)
	v_add_f32_e32 v254, v254, v160
	v_add_f32_e32 v255, v255, v161
	v_xor_b32_e32 v162, 1, v197
	v_lshlrev_b32_e32 v162, 2, v162
	ds_bpermute_b32 v160, v162, v254
	ds_bpermute_b32 v161, v162, v255
	s_waitcnt lgkmcnt(0)
	v_add_f32_e32 v254, v254, v160
	v_add_f32_e32 v255, v255, v161
	v_mov_b32_e32 v160, 0x358637bd
	v_fma_f32 v254, v254, s20, v160
	v_fma_f32 v255, v255, s20, v160
	v_rsq_f32_e32 v254, v254
	v_rsq_f32_e32 v255, v255
	s_nop 0
	s_lshl_b32 s18, s16, 12
	s_add_u32 s22, s6, s18
	s_addc_u32 s23, s7, 0
	v_mul_f32_e32 v163, v64, v254
	v_mul_f32_e32 v165, v65, v254
	v_mul_f32_e32 v167, v66, v254
	v_mul_f32_e32 v199, v67, v254
	v_mul_f32_e32 v163, v163, v200
	v_mul_f32_e32 v165, v165, v201
	v_mul_f32_e32 v167, v167, v202
	v_mul_f32_e32 v199, v199, v203
	v_cvt_pk_bf16_f32 v192, v163, v165
	v_cvt_pk_bf16_f32 v193, v167, v199
	global_store_dwordx2 v164, v[192:193], s[22:23] offset:0
	v_mul_f32_e32 v163, v68, v254
	v_mul_f32_e32 v165, v69, v254
	v_mul_f32_e32 v167, v70, v254
	v_mul_f32_e32 v199, v71, v254
	v_mul_f32_e32 v163, v163, v204
	v_mul_f32_e32 v165, v165, v205
	v_mul_f32_e32 v167, v167, v206
	v_mul_f32_e32 v199, v199, v207
	v_cvt_pk_bf16_f32 v238, v163, v165
	v_cvt_pk_bf16_f32 v239, v167, v199
	global_store_dwordx2 v164, v[238:239], s[22:23] offset:512
	v_mul_f32_e32 v163, v72, v254
	v_mul_f32_e32 v165, v73, v254
	v_mul_f32_e32 v167, v74, v254
	v_mul_f32_e32 v199, v75, v254
	v_mul_f32_e32 v163, v163, v208
	v_mul_f32_e32 v165, v165, v209
	v_mul_f32_e32 v167, v167, v210
	v_mul_f32_e32 v199, v199, v211
	v_cvt_pk_bf16_f32 v192, v163, v165
	v_cvt_pk_bf16_f32 v193, v167, v199
	global_store_dwordx2 v164, v[192:193], s[22:23] offset:1024
	v_mul_f32_e32 v163, v76, v254
	v_mul_f32_e32 v165, v77, v254
	v_mul_f32_e32 v167, v78, v254
	v_mul_f32_e32 v199, v79, v254
	v_mul_f32_e32 v163, v163, v212
	v_mul_f32_e32 v165, v165, v213
	v_mul_f32_e32 v167, v167, v214
	v_mul_f32_e32 v199, v199, v215
	v_cvt_pk_bf16_f32 v238, v163, v165
	v_cvt_pk_bf16_f32 v239, v167, v199
	global_store_dwordx2 v164, v[238:239], s[22:23] offset:1536
	v_mul_f32_e32 v163, v80, v254
	v_mul_f32_e32 v165, v81, v254
	v_mul_f32_e32 v167, v82, v254
	v_mul_f32_e32 v199, v83, v254
	v_mul_f32_e32 v163, v163, v216
	v_mul_f32_e32 v165, v165, v217
	v_mul_f32_e32 v167, v167, v218
	v_mul_f32_e32 v199, v199, v219
	v_cvt_pk_bf16_f32 v192, v163, v165
	v_cvt_pk_bf16_f32 v193, v167, v199
	global_store_dwordx2 v164, v[192:193], s[22:23] offset:2048
	v_mul_f32_e32 v163, v84, v254
	v_mul_f32_e32 v165, v85, v254
	v_mul_f32_e32 v167, v86, v254
	v_mul_f32_e32 v199, v87, v254
	v_mul_f32_e32 v163, v163, v220
	v_mul_f32_e32 v165, v165, v221
	v_mul_f32_e32 v167, v167, v222
	v_mul_f32_e32 v199, v199, v223
	v_cvt_pk_bf16_f32 v238, v163, v165
	v_cvt_pk_bf16_f32 v239, v167, v199
	global_store_dwordx2 v164, v[238:239], s[22:23] offset:2560
	v_mul_f32_e32 v163, v88, v254
	v_mul_f32_e32 v165, v89, v254
	v_mul_f32_e32 v167, v90, v254
	v_mul_f32_e32 v199, v91, v254
	v_mul_f32_e32 v163, v163, v224
	v_mul_f32_e32 v165, v165, v225
	v_mul_f32_e32 v167, v167, v226
	v_mul_f32_e32 v199, v199, v227
	v_cvt_pk_bf16_f32 v192, v163, v165
	v_cvt_pk_bf16_f32 v193, v167, v199
	global_store_dwordx2 v164, v[192:193], s[22:23] offset:3072
	v_mul_f32_e32 v163, v92, v254
	v_mul_f32_e32 v165, v93, v254
	v_mul_f32_e32 v167, v94, v254
	v_mul_f32_e32 v199, v95, v254
	v_mul_f32_e32 v163, v163, v228
	v_mul_f32_e32 v165, v165, v229
	v_mul_f32_e32 v167, v167, v230
	v_mul_f32_e32 v199, v199, v231
	v_cvt_pk_bf16_f32 v238, v163, v165
	v_cvt_pk_bf16_f32 v239, v167, v199
	global_store_dwordx2 v164, v[238:239], s[22:23] offset:3584
	s_add_u32 s22, s22, 0x1000
	s_addc_u32 s23, s23, 0
	v_mul_f32_e32 v163, v96, v255
	v_mul_f32_e32 v165, v97, v255
	v_mul_f32_e32 v167, v98, v255
	v_mul_f32_e32 v199, v99, v255
	v_mul_f32_e32 v163, v163, v200
	v_mul_f32_e32 v165, v165, v201
	v_mul_f32_e32 v167, v167, v202
	v_mul_f32_e32 v199, v199, v203
	v_cvt_pk_bf16_f32 v192, v163, v165
	v_cvt_pk_bf16_f32 v193, v167, v199
	global_store_dwordx2 v164, v[192:193], s[22:23] offset:0
	v_mul_f32_e32 v163, v100, v255
	v_mul_f32_e32 v165, v101, v255
	v_mul_f32_e32 v167, v102, v255
	v_mul_f32_e32 v199, v103, v255
	v_mul_f32_e32 v163, v163, v204
	v_mul_f32_e32 v165, v165, v205
	v_mul_f32_e32 v167, v167, v206
	v_mul_f32_e32 v199, v199, v207
	v_cvt_pk_bf16_f32 v238, v163, v165
	v_cvt_pk_bf16_f32 v239, v167, v199
	global_store_dwordx2 v164, v[238:239], s[22:23] offset:512
	v_mul_f32_e32 v163, v104, v255
	v_mul_f32_e32 v165, v105, v255
	v_mul_f32_e32 v167, v106, v255
	v_mul_f32_e32 v199, v107, v255
	v_mul_f32_e32 v163, v163, v208
	v_mul_f32_e32 v165, v165, v209
	v_mul_f32_e32 v167, v167, v210
	v_mul_f32_e32 v199, v199, v211
	v_cvt_pk_bf16_f32 v192, v163, v165
	v_cvt_pk_bf16_f32 v193, v167, v199
	global_store_dwordx2 v164, v[192:193], s[22:23] offset:1024
	v_mul_f32_e32 v163, v108, v255
	v_mul_f32_e32 v165, v109, v255
	v_mul_f32_e32 v167, v110, v255
	v_mul_f32_e32 v199, v111, v255
	v_mul_f32_e32 v163, v163, v212
	v_mul_f32_e32 v165, v165, v213
	v_mul_f32_e32 v167, v167, v214
	v_mul_f32_e32 v199, v199, v215
	v_cvt_pk_bf16_f32 v238, v163, v165
	v_cvt_pk_bf16_f32 v239, v167, v199
	global_store_dwordx2 v164, v[238:239], s[22:23] offset:1536
	v_mul_f32_e32 v163, v112, v255
	v_mul_f32_e32 v165, v113, v255
	v_mul_f32_e32 v167, v114, v255
	v_mul_f32_e32 v199, v115, v255
	v_mul_f32_e32 v163, v163, v216
	v_mul_f32_e32 v165, v165, v217
	v_mul_f32_e32 v167, v167, v218
	v_mul_f32_e32 v199, v199, v219
	v_cvt_pk_bf16_f32 v192, v163, v165
	v_cvt_pk_bf16_f32 v193, v167, v199
	global_store_dwordx2 v164, v[192:193], s[22:23] offset:2048
	v_mul_f32_e32 v163, v116, v255
	v_mul_f32_e32 v165, v117, v255
	v_mul_f32_e32 v167, v118, v255
	v_mul_f32_e32 v199, v119, v255
	v_mul_f32_e32 v163, v163, v220
	v_mul_f32_e32 v165, v165, v221
	v_mul_f32_e32 v167, v167, v222
	v_mul_f32_e32 v199, v199, v223
	v_cvt_pk_bf16_f32 v238, v163, v165
	v_cvt_pk_bf16_f32 v239, v167, v199
	global_store_dwordx2 v164, v[238:239], s[22:23] offset:2560
	v_mul_f32_e32 v163, v120, v255
	v_mul_f32_e32 v165, v121, v255
	v_mul_f32_e32 v167, v122, v255
	v_mul_f32_e32 v199, v123, v255
	v_mul_f32_e32 v163, v163, v224
	v_mul_f32_e32 v165, v165, v225
	v_mul_f32_e32 v167, v167, v226
	v_mul_f32_e32 v199, v199, v227
	v_cvt_pk_bf16_f32 v192, v163, v165
	v_cvt_pk_bf16_f32 v193, v167, v199
	global_store_dwordx2 v164, v[192:193], s[22:23] offset:3072
	v_mul_f32_e32 v163, v124, v255
	v_mul_f32_e32 v165, v125, v255
	v_mul_f32_e32 v167, v126, v255
	v_mul_f32_e32 v199, v127, v255
	v_mul_f32_e32 v163, v163, v228
	v_mul_f32_e32 v165, v165, v229
	v_mul_f32_e32 v167, v167, v230
	v_mul_f32_e32 v199, v199, v231
	v_cvt_pk_bf16_f32 v238, v163, v165
	v_cvt_pk_bf16_f32 v239, v167, v199
	global_store_dwordx2 v164, v[238:239], s[22:23] offset:3584
	v_xor_b32_e32 v162, 32, v197
	v_lshlrev_b32_e32 v162, 2, v162
	v_cndmask_b32_e64 v163, v144, v128, s[24:25]
	v_cndmask_b32_e64 v128, v128, v144, s[24:25]
	ds_bpermute_b32 v144, v162, v163
	v_cndmask_b32_e64 v165, v145, v129, s[24:25]
	v_cndmask_b32_e64 v129, v129, v145, s[24:25]
	ds_bpermute_b32 v145, v162, v165
	v_cndmask_b32_e64 v167, v146, v130, s[24:25]
	v_cndmask_b32_e64 v130, v130, v146, s[24:25]
	ds_bpermute_b32 v146, v162, v167
	v_cndmask_b32_e64 v199, v147, v131, s[24:25]
	v_cndmask_b32_e64 v131, v131, v147, s[24:25]
	ds_bpermute_b32 v147, v162, v199
	v_cndmask_b32_e64 v163, v148, v132, s[24:25]
	v_cndmask_b32_e64 v132, v132, v148, s[24:25]
	ds_bpermute_b32 v148, v162, v163
	v_cndmask_b32_e64 v165, v149, v133, s[24:25]
	v_cndmask_b32_e64 v133, v133, v149, s[24:25]
	ds_bpermute_b32 v149, v162, v165
	v_cndmask_b32_e64 v167, v150, v134, s[24:25]
	v_cndmask_b32_e64 v134, v134, v150, s[24:25]
	ds_bpermute_b32 v150, v162, v167
	v_cndmask_b32_e64 v199, v151, v135, s[24:25]
	v_cndmask_b32_e64 v135, v135, v151, s[24:25]
	ds_bpermute_b32 v151, v162, v199
	s_waitcnt lgkmcnt(0)
	v_add_f32_e32 v128, v128, v144
	v_add_f32_e32 v129, v129, v145
	v_add_f32_e32 v130, v130, v146
	v_add_f32_e32 v131, v131, v147
	v_add_f32_e32 v132, v132, v148
	v_add_f32_e32 v133, v133, v149
	v_add_f32_e32 v134, v134, v150
	v_add_f32_e32 v135, v135, v151
	v_cndmask_b32_e64 v163, v152, v136, s[24:25]
	v_cndmask_b32_e64 v136, v136, v152, s[24:25]
	ds_bpermute_b32 v152, v162, v163
	v_cndmask_b32_e64 v165, v153, v137, s[24:25]
	v_cndmask_b32_e64 v137, v137, v153, s[24:25]
	ds_bpermute_b32 v153, v162, v165
	v_cndmask_b32_e64 v167, v154, v138, s[24:25]
	v_cndmask_b32_e64 v138, v138, v154, s[24:25]
	ds_bpermute_b32 v154, v162, v167
	v_cndmask_b32_e64 v199, v155, v139, s[24:25]
	v_cndmask_b32_e64 v139, v139, v155, s[24:25]
	ds_bpermute_b32 v155, v162, v199
	v_cndmask_b32_e64 v163, v156, v140, s[24:25]
	v_cndmask_b32_e64 v140, v140, v156, s[24:25]
	ds_bpermute_b32 v156, v162, v163
	v_cndmask_b32_e64 v165, v157, v141, s[24:25]
	v_cndmask_b32_e64 v141, v141, v157, s[24:25]
	ds_bpermute_b32 v157, v162, v165
	v_cndmask_b32_e64 v167, v158, v142, s[24:25]
	v_cndmask_b32_e64 v142, v142, v158, s[24:25]
	ds_bpermute_b32 v158, v162, v167
	v_cndmask_b32_e64 v199, v159, v143, s[24:25]
	v_cndmask_b32_e64 v143, v143, v159, s[24:25]
	ds_bpermute_b32 v159, v162, v199
	s_waitcnt lgkmcnt(0)
	v_add_f32_e32 v136, v136, v152
	v_add_f32_e32 v137, v137, v153
	v_add_f32_e32 v138, v138, v154
	v_add_f32_e32 v139, v139, v155
	v_add_f32_e32 v140, v140, v156
	v_add_f32_e32 v141, v141, v157
	v_add_f32_e32 v142, v142, v158
	v_add_f32_e32 v143, v143, v159
	v_xor_b32_e32 v162, 16, v197
	v_lshlrev_b32_e32 v162, 2, v162
	v_cndmask_b32_e64 v163, v136, v128, s[26:27]
	v_cndmask_b32_e64 v128, v128, v136, s[26:27]
	ds_bpermute_b32 v136, v162, v163
	v_cndmask_b32_e64 v165, v137, v129, s[26:27]
	v_cndmask_b32_e64 v129, v129, v137, s[26:27]
	ds_bpermute_b32 v137, v162, v165
	v_cndmask_b32_e64 v167, v138, v130, s[26:27]
	v_cndmask_b32_e64 v130, v130, v138, s[26:27]
	ds_bpermute_b32 v138, v162, v167
	v_cndmask_b32_e64 v199, v139, v131, s[26:27]
	v_cndmask_b32_e64 v131, v131, v139, s[26:27]
	ds_bpermute_b32 v139, v162, v199
	v_cndmask_b32_e64 v163, v140, v132, s[26:27]
	v_cndmask_b32_e64 v132, v132, v140, s[26:27]
	ds_bpermute_b32 v140, v162, v163
	v_cndmask_b32_e64 v165, v141, v133, s[26:27]
	v_cndmask_b32_e64 v133, v133, v141, s[26:27]
	ds_bpermute_b32 v141, v162, v165
	v_cndmask_b32_e64 v167, v142, v134, s[26:27]
	v_cndmask_b32_e64 v134, v134, v142, s[26:27]
	ds_bpermute_b32 v142, v162, v167
	v_cndmask_b32_e64 v199, v143, v135, s[26:27]
	v_cndmask_b32_e64 v135, v135, v143, s[26:27]
	ds_bpermute_b32 v143, v162, v199
	s_waitcnt lgkmcnt(0)
	v_add_f32_e32 v128, v128, v136
	v_add_f32_e32 v129, v129, v137
	v_add_f32_e32 v130, v130, v138
	v_add_f32_e32 v131, v131, v139
	v_add_f32_e32 v132, v132, v140
	v_add_f32_e32 v133, v133, v141
	v_add_f32_e32 v134, v134, v142
	v_add_f32_e32 v135, v135, v143
	v_xor_b32_e32 v162, 8, v197
	v_lshlrev_b32_e32 v162, 2, v162
	v_cndmask_b32_e64 v163, v132, v128, s[28:29]
	v_cndmask_b32_e64 v128, v128, v132, s[28:29]
	ds_bpermute_b32 v132, v162, v163
	v_cndmask_b32_e64 v165, v133, v129, s[28:29]
	v_cndmask_b32_e64 v129, v129, v133, s[28:29]
	ds_bpermute_b32 v133, v162, v165
	v_cndmask_b32_e64 v167, v134, v130, s[28:29]
	v_cndmask_b32_e64 v130, v130, v134, s[28:29]
	ds_bpermute_b32 v134, v162, v167
	v_cndmask_b32_e64 v199, v135, v131, s[28:29]
	v_cndmask_b32_e64 v131, v131, v135, s[28:29]
	ds_bpermute_b32 v135, v162, v199
	s_waitcnt lgkmcnt(0)
	v_add_f32_e32 v128, v128, v132
	v_add_f32_e32 v129, v129, v133
	v_add_f32_e32 v130, v130, v134
	v_add_f32_e32 v131, v131, v135
	v_xor_b32_e32 v162, 4, v197
	v_lshlrev_b32_e32 v162, 2, v162
	v_cndmask_b32_e64 v163, v130, v128, s[30:31]
	v_cndmask_b32_e64 v128, v128, v130, s[30:31]
	ds_bpermute_b32 v130, v162, v163
	v_cndmask_b32_e64 v165, v131, v129, s[30:31]
	v_cndmask_b32_e64 v129, v129, v131, s[30:31]
	ds_bpermute_b32 v131, v162, v165
	s_waitcnt lgkmcnt(0)
	v_add_f32_e32 v128, v128, v130
	v_add_f32_e32 v129, v129, v131
	v_xor_b32_e32 v162, 2, v197
	v_lshlrev_b32_e32 v162, 2, v162
	v_cndmask_b32_e64 v163, v129, v128, s[34:35]
	v_cndmask_b32_e64 v128, v128, v129, s[34:35]
	ds_bpermute_b32 v129, v162, v163
	s_waitcnt lgkmcnt(0)
	v_add_f32_e32 v128, v128, v129
	v_xor_b32_e32 v162, 1, v197
	v_lshlrev_b32_e32 v162, 2, v162
	ds_bpermute_b32 v160, v162, v128
	s_waitcnt lgkmcnt(0)
	v_add_f32_e32 v128, v128, v160
	v_cndmask_b32_e64 v160, v254, v255, s[24:25]
	v_mul_f32_e32 v128, v128, v160
	v_mul_f32_e32 v163, 0xbfb8aa3b, v128
	v_exp_f32_e32 v163, v163
	v_add_f32_e32 v167, v128, v195
	v_add_f32_e32 v163, 1.0, v163
	v_and_b32_e32 v199, 0x7fffffff, v167
	v_mul_f32_e32 v199, 0xbfb8aa3b, v199
	v_exp_f32_e32 v199, v199
	v_rcp_f32_e32 v163, v163
	v_add_f32_e32 v160, 1.0, v199
	v_log_f32_e32 v160, v160
	v_mul_f32_e32 v161, v199, v199
	v_mul_f32_e32 v160, 0x3f317218, v160
	v_mul_f32_e32 v162, v161, v199
	v_fma_f32 v161, v161, -0.5, v199
	v_mov_b32_e32 v165, 0x3eaaaaab
	v_fmac_f32_e32 v161, v162, v165
	v_cmp_gt_f32_e32 vcc, 0x3c800000, v199
	v_max_f32_e32 v167, 0, v167
	s_nop 0
	v_cndmask_b32_e32 v160, v160, v161, vcc
	v_add_f32_e32 v167, v167, v160
	v_mul_f32_e64 v165, -v237, v167
	v_bfe_u32 v162, v197, 1, 4
	v_cmp_gt_u32_e32 vcc, 8, v162
	v_and_b32_e32 v162, 7, v162
	s_lshr_b32 s18, s16, 11
	s_lshl_b32 s18, s18, 3
	v_add_u32_e32 v162, s18, v162
	v_lshlrev_b32_e32 v162, 13, v162
	s_and_b32 s18, s16, 2047
	v_lshrrev_b32_e32 v161, 5, v197
	v_add_u32_e32 v161, s18, v161
	v_lshl_add_u32 v162, v161, 2, v162
	v_cndmask_b32_e32 v160, v165, v163, vcc
	v_and_b32_e32 v161, 1, v197
	v_cmp_eq_u32_e64 s[22:23], 0, v161
	s_nop 1
	s_and_b64 s[0:1], s[22:23], vcc
	s_andn2_b64 s[2:3], s[22:23], vcc
	s_mov_b64 s[22:23], exec
	s_mov_b64 exec, s[0:1]
	global_store_dword v162, v160, s[12:13]
	s_mov_b64 exec, s[2:3]
	global_store_dword v162, v160, s[14:15]
	s_mov_b64 exec, s[22:23]
	s_add_u32 s16, s16, 2
	s_add_u32 s17, s17, 1
	s_cmp_lt_u32 s17, 2
	s_cbranch_scc1 .Lp0_loop
	v_lshrrev_b32_e32 v136, 4, v198
	v_lshrrev_b32_e32 v145, 3, v198
	v_lshlrev_b32_e32 v144, 3, v198
	v_readlane_b32 s72, v236, 22
	v_readlane_b32 s73, v236, 23
	v_readlane_b32 s74, v236, 24
	v_readlane_b32 s75, v236, 25
	v_readlane_b32 s76, v236, 26
	v_readlane_b32 s77, v236, 27
	v_readlane_b32 s78, v236, 28
	v_readlane_b32 s79, v236, 29
	v_readlane_b32 s80, v236, 30
	v_readlane_b32 s81, v236, 31
	v_readlane_b32 s82, v236, 32
	v_readlane_b32 s83, v236, 33
	v_readlane_b32 s84, v236, 34
	v_readlane_b32 s85, v236, 35
	v_readlane_b32 s86, v236, 36
	v_readlane_b32 s87, v236, 37
	s_nop 3
